# combo3 plus un-aligned epilogues for 8 GEMM copies (leading half no longer waits for trailing half before its epilogue except on the last unit)
# baseline (speedup 1.0000x reference)
; #define PG8_STAGE(bufoff, gbase, voff) do { _Pragma("unroll") for (int _i = 0; _i < 2; ++_i) \
;         __builtin_amdgcn_global_load_lds((const unsigned*)((const char*)(gbase) + (voff)[_i]), (PG8_LAS unsigned*)(lds + (bufoff) + ldsw + _i * 8192), 16, 0, 0); } while (0)
; #define PG8_LDA(dst, b, h) do { _Pragma("unroll") for (int m = 0; m < 4; ++m) _Pragma("unroll") for (int k = 0; k < 2; ++k) dst[m][k] = *(const PG8_LAS bf16x8*)(lds + PG8_SA(b, h) + aoff + m * 2048 + k * 1024); } while (0)
; #define PG8_LDB(dst, b, h) do { _Pragma("unroll") for (int n = 0; n < 2; ++n) _Pragma("unroll") for (int k = 0; k < 2; ++k) dst[n][k] = *(const PG8_LAS bf16x8*)(lds + PG8_SB(b, h) + boff + n * 2048 + k * 1024); } while (0)
; #define PG8_MMA(ai, bj, At, Bt) do { __builtin_amdgcn_s_setprio(1); _Pragma("unroll") for (int m = 0; m < 4; ++m) _Pragma("unroll") for (int n = 0; n < 2; ++n) _Pragma("unroll") for (int k = 0; k < 2; ++k) \
;         acc[ai][bj][m][n] = __builtin_amdgcn_mfma_f32_16x16x32_bf16(Bt[n][k], At[m][k], acc[ai][bj][m][n], 0, 0, 0); __builtin_amdgcn_s_setprio(0); } while (0)
; #define PG8_WAIT_V(n) asm volatile("s_waitcnt vmcnt(" #n ")" ::: "memory")
; #define PG8_WAIT_L(n) asm volatile("s_waitcnt lgkmcnt(" #n ")" ::: "memory")
; #define PG8_BAR __builtin_amdgcn_s_barrier()
; #define PG8_SCHED __builtin_amdgcn_sched_barrier(0)
; template <class Epi, class Sched, bool ALIGN_EPI = false, bool SP2 = false>
; __device__ __forceinline__ void gemm_phase(PG8_LAS unsigned char* lds, const Gemm g, const Sched& S, const Epi& E, const int tid_in) {
;     ...
;             PG8_LDB(B0, 0, 0); PG8_LDB(B1, 0, 1); PG8_SCHED; PG8_LDA(At, 0, 0); PG8_STAGE(PG8_SA(1, 1), a1 + hstepA, voffA);
;             PG8_WAIT_V(8); PG8_WAIT_L(0); PG8_BAR; PG8_MMA(0, 0, At, B0); PG8_MMA(0, 1, At, B1); PG8_BAR; PG8_SCHED;
;             PG8_LDA(At, 0, 1); PG8_STAGE(PG8_SB(0, 0), b2, voffB); PG8_STAGE(PG8_SB(0, 1), b2 + hstepB, voffB); PG8_STAGE(PG8_SA(0, 0), a2, voffA);
;             PG8_WAIT_V(8); PG8_WAIT_L(0); PG8_BAR; PG8_MMA(1, 0, At, B0); PG8_MMA(1, 1, At, B1); PG8_BAR; PG8_SCHED;
;             PG8_LDB(B0, 1, 0); PG8_LDB(B1, 1, 1); PG8_SCHED; PG8_LDA(At, 1, 0); PG8_STAGE(PG8_SA(0, 1), a2 + hstepA, voffA);
;             PG8_WAIT_V(8); PG8_WAIT_L(0); PG8_BAR; PG8_MMA(0, 0, At, B0); PG8_MMA(0, 1, At, B1); PG8_BAR; PG8_SCHED;
.LBB0_289:
	s_add_u32 s12, s46, 0xfff80080
	s_addc_u32 s13, s47, -1
	s_add_i32 s68, 0, 0x10000
	s_cmp_eq_u32 s67, 28
	s_cselect_b32 s51, s41, s13
	s_cselect_b32 s50, s63, s12
	v_add_u32_e32 v138, s68, v141
	s_cselect_b32 s49, s39, s66
	s_cselect_b32 s48, s64, s65
	s_add_i32 s69, 0, 0x14000
	ds_read_b128 v[142:145], v138
	ds_read_b128 v[150:153], v138 offset:1024
	ds_read_b128 v[154:157], v138 offset:2048
	ds_read_b128 v[158:161], v138 offset:3072
	v_add_u32_e32 v138, s69, v141
	ds_read_b128 v[162:165], v138
	ds_read_b128 v[166:169], v138 offset:1024
	ds_read_b128 v[170:173], v138 offset:2048
	ds_read_b128 v[174:177], v138 offset:3072
	v_lshl_add_u64 v[190:191], s[46:47], 0, v[134:135]
	s_add_i32 m0, s54, 0xc000
	ds_read_b128 v[178:181], v149
	ds_read_b128 v[182:185], v149 offset:1024
	ds_read_b128 v[186:189], v149 offset:2048
	ds_read_b128 v[194:197], v149 offset:3072
	ds_read_b128 v[198:201], v149 offset:4096
	ds_read_b128 v[202:205], v149 offset:5120
	ds_read_b128 v[206:209], v149 offset:6144
	ds_read_b128 v[210:213], v149 offset:7168
	global_load_lds_dwordx4 v[190:191], off
	v_lshl_add_u64 v[190:191], s[46:47], 0, v[136:137]
	s_add_i32 m0, s54, 0xe000
	s_nop 0
	global_load_lds_dwordx4 v[190:191], off
	s_waitcnt vmcnt(8)
	s_waitcnt lgkmcnt(0)
	s_barrier
	s_setprio 1
	s_waitcnt lgkmcnt(0)
	v_mfma_f32_16x16x32_bf16 v[124:127], v[142:145], v[178:181], v[124:127]
	v_mfma_f32_16x16x32_bf16 v[120:123], v[154:157], v[178:181], v[120:123]
	v_mfma_f32_16x16x32_bf16 v[108:111], v[142:145], v[186:189], v[108:111]
	v_mfma_f32_16x16x32_bf16 v[104:107], v[154:157], v[186:189], v[104:107]
	v_mfma_f32_16x16x32_bf16 v[92:95], v[142:145], v[198:201], v[92:95]
	v_mfma_f32_16x16x32_bf16 v[88:91], v[154:157], v[198:201], v[88:91]
	v_mfma_f32_16x16x32_bf16 v[76:79], v[142:145], v[206:209], v[76:79]
	v_mfma_f32_16x16x32_bf16 v[72:75], v[154:157], v[206:209], v[72:75]
	v_mfma_f32_16x16x32_bf16 v[124:127], v[150:153], v[182:185], v[124:127]
	v_mfma_f32_16x16x32_bf16 v[120:123], v[158:161], v[182:185], v[120:123]
	v_mfma_f32_16x16x32_bf16 v[108:111], v[150:153], v[194:197], v[108:111]
	v_mfma_f32_16x16x32_bf16 v[104:107], v[158:161], v[194:197], v[104:107]
	v_mfma_f32_16x16x32_bf16 v[92:95], v[150:153], v[202:205], v[92:95]
	v_mfma_f32_16x16x32_bf16 v[88:91], v[158:161], v[202:205], v[88:91]
	v_mfma_f32_16x16x32_bf16 v[76:79], v[150:153], v[210:213], v[76:79]
	v_mfma_f32_16x16x32_bf16 v[72:75], v[158:161], v[210:213], v[72:75]
	v_mfma_f32_16x16x32_bf16 v[116:119], v[162:165], v[178:181], v[116:119]
	v_mfma_f32_16x16x32_bf16 v[112:115], v[170:173], v[178:181], v[112:115]
	v_mfma_f32_16x16x32_bf16 v[100:103], v[162:165], v[186:189], v[100:103]
	v_mfma_f32_16x16x32_bf16 v[96:99], v[170:173], v[186:189], v[96:99]
	v_mfma_f32_16x16x32_bf16 v[84:87], v[162:165], v[198:201], v[84:87]
	v_mfma_f32_16x16x32_bf16 v[80:83], v[170:173], v[198:201], v[80:83]
	v_mfma_f32_16x16x32_bf16 v[68:71], v[162:165], v[206:209], v[68:71]
	v_mfma_f32_16x16x32_bf16 v[64:67], v[170:173], v[206:209], v[64:67]
	v_mfma_f32_16x16x32_bf16 v[116:119], v[166:169], v[182:185], v[116:119]
	v_mfma_f32_16x16x32_bf16 v[112:115], v[174:177], v[182:185], v[112:115]
	v_mfma_f32_16x16x32_bf16 v[100:103], v[166:169], v[194:197], v[100:103]
	v_mfma_f32_16x16x32_bf16 v[96:99], v[174:177], v[194:197], v[96:99]
	v_mfma_f32_16x16x32_bf16 v[84:87], v[166:169], v[202:205], v[84:87]
	v_mfma_f32_16x16x32_bf16 v[80:83], v[174:177], v[202:205], v[80:83]
	v_mfma_f32_16x16x32_bf16 v[68:71], v[166:169], v[210:213], v[68:71]
	v_mfma_f32_16x16x32_bf16 v[64:67], v[174:177], v[210:213], v[64:67]
	s_setprio 0
	s_barrier
	s_add_i32 s12, s68, s53
	v_lshl_add_u64 v[190:191], s[48:49], 0, v[192:193]
	s_mov_b32 m0, s12
	ds_read_b128 v[178:181], v149 offset:16384
	ds_read_b128 v[182:185], v149 offset:17408
	ds_read_b128 v[186:189], v149 offset:18432
	ds_read_b128 v[194:197], v149 offset:19456
	ds_read_b128 v[198:201], v149 offset:20480
	ds_read_b128 v[202:205], v149 offset:21504
	ds_read_b128 v[206:209], v149 offset:22528
	ds_read_b128 v[210:213], v149 offset:23552
	global_load_lds_dwordx4 v[190:191], off
	s_add_i32 m0, s12, 0x2000
	s_add_u32 s12, s48, 0x80000
	v_lshl_add_u64 v[214:215], s[48:49], 0, v[132:133]
	s_addc_u32 s13, s49, 0
	s_add_i32 s68, s69, s53
	global_load_lds_dwordx4 v[214:215], off
	v_lshl_add_u64 v[216:217], s[12:13], 0, v[192:193]
	s_mov_b32 m0, s68
	v_lshl_add_u64 v[218:219], s[50:51], 0, v[130:131]
	global_load_lds_dwordx4 v[216:217], off
	v_lshl_add_u64 v[216:217], s[12:13], 0, v[132:133]
	s_add_i32 m0, s68, 0x2000
	s_nop 0
	global_load_lds_dwordx4 v[216:217], off
	v_lshl_add_u64 v[216:217], s[50:51], 0, v[128:129]
	s_mov_b32 m0, s54
	s_nop 0
	global_load_lds_dwordx4 v[216:217], off
	s_mov_b32 m0, s55
	s_nop 0
	global_load_lds_dwordx4 v[218:219], off
	s_waitcnt vmcnt(8)
	s_waitcnt lgkmcnt(0)
	s_barrier
; #define PG8_STAGE(bufoff, gbase, voff) do { _Pragma("unroll") for (int _i = 0; _i < 2; ++_i) \
;         __builtin_amdgcn_global_load_lds((const unsigned*)((const char*)(gbase) + (voff)[_i]), (PG8_LAS unsigned*)(lds + (bufoff) + ldsw + _i * 8192), 16, 0, 0); } while (0)
; #define PG8_LDA(dst, b, h) do { _Pragma("unroll") for (int m = 0; m < 4; ++m) _Pragma("unroll") for (int k = 0; k < 2; ++k) dst[m][k] = *(const PG8_LAS bf16x8*)(lds + PG8_SA(b, h) + aoff + m * 2048 + k * 1024); } while (0)
; #define PG8_LDB(dst, b, h) do { _Pragma("unroll") for (int n = 0; n < 2; ++n) _Pragma("unroll") for (int k = 0; k < 2; ++k) dst[n][k] = *(const PG8_LAS bf16x8*)(lds + PG8_SB(b, h) + boff + n * 2048 + k * 1024); } while (0)
; #define PG8_MMA(ai, bj, At, Bt) do { __builtin_amdgcn_s_setprio(1); _Pragma("unroll") for (int m = 0; m < 4; ++m) _Pragma("unroll") for (int n = 0; n < 2; ++n) _Pragma("unroll") for (int k = 0; k < 2; ++k) \
;         acc[ai][bj][m][n] = __builtin_amdgcn_mfma_f32_16x16x32_bf16(Bt[n][k], At[m][k], acc[ai][bj][m][n], 0, 0, 0); __builtin_amdgcn_s_setprio(0); } while (0)
; #define PG8_WAIT_V(n) asm volatile("s_waitcnt vmcnt(" #n ")" ::: "memory")
; #define PG8_WAIT_L(n) asm volatile("s_waitcnt lgkmcnt(" #n ")" ::: "memory")
; #define PG8_BAR __builtin_amdgcn_s_barrier()
; #define PG8_SCHED __builtin_amdgcn_sched_barrier(0)
; template <class Epi, class Sched, bool ALIGN_EPI = false, bool SP2 = false>
; __device__ __forceinline__ void gemm_phase(PG8_LAS unsigned char* lds, const Gemm g, const Sched& S, const Epi& E, const int tid_in) {
;     ...
;             PG8_WAIT_V(8); PG8_WAIT_L(0); PG8_BAR; PG8_MMA(1, 0, At, B0); PG8_MMA(1, 1, At, B1); PG8_BAR; PG8_SCHED;
;             PG8_LDB(B0, 1, 0); PG8_LDB(B1, 1, 1); PG8_SCHED; PG8_LDA(At, 1, 0); PG8_STAGE(PG8_SA(0, 1), a2 + hstepA, voffA);
;             PG8_WAIT_V(8); PG8_WAIT_L(0); PG8_BAR; PG8_MMA(0, 0, At, B0); PG8_MMA(0, 1, At, B1); PG8_BAR; PG8_SCHED;
	s_setprio 1
	s_waitcnt lgkmcnt(0)
	v_mfma_f32_16x16x32_bf16 v[60:63], v[142:145], v[178:181], v[60:63]
	v_mfma_f32_16x16x32_bf16 v[56:59], v[154:157], v[178:181], v[56:59]
	v_mfma_f32_16x16x32_bf16 v[48:51], v[142:145], v[186:189], v[48:51]
	v_mfma_f32_16x16x32_bf16 v[40:43], v[154:157], v[186:189], v[40:43]
	v_mfma_f32_16x16x32_bf16 v[32:35], v[142:145], v[198:201], v[32:35]
	v_mfma_f32_16x16x32_bf16 v[24:27], v[154:157], v[198:201], v[24:27]
	v_mfma_f32_16x16x32_bf16 v[16:19], v[142:145], v[206:209], v[16:19]
	v_mfma_f32_16x16x32_bf16 v[8:11], v[154:157], v[206:209], v[8:11]
	v_mfma_f32_16x16x32_bf16 v[60:63], v[150:153], v[182:185], v[60:63]
	v_mfma_f32_16x16x32_bf16 v[56:59], v[158:161], v[182:185], v[56:59]
	v_mfma_f32_16x16x32_bf16 v[48:51], v[150:153], v[194:197], v[48:51]
	v_mfma_f32_16x16x32_bf16 v[40:43], v[158:161], v[194:197], v[40:43]
	v_mfma_f32_16x16x32_bf16 v[32:35], v[150:153], v[202:205], v[32:35]
	v_mfma_f32_16x16x32_bf16 v[24:27], v[158:161], v[202:205], v[24:27]
	v_mfma_f32_16x16x32_bf16 v[16:19], v[150:153], v[210:213], v[16:19]
	v_mfma_f32_16x16x32_bf16 v[8:11], v[158:161], v[210:213], v[8:11]
	v_mfma_f32_16x16x32_bf16 v[52:55], v[162:165], v[178:181], v[52:55]
	v_mfma_f32_16x16x32_bf16 v[44:47], v[170:173], v[178:181], v[44:47]
	v_mfma_f32_16x16x32_bf16 v[36:39], v[162:165], v[186:189], v[36:39]
	v_mfma_f32_16x16x32_bf16 v[28:31], v[170:173], v[186:189], v[28:31]
	v_mfma_f32_16x16x32_bf16 v[20:23], v[162:165], v[198:201], v[20:23]
	v_mfma_f32_16x16x32_bf16 v[12:15], v[170:173], v[198:201], v[12:15]
	v_mfma_f32_16x16x32_bf16 v[4:7], v[162:165], v[206:209], v[4:7]
	v_mfma_f32_16x16x32_bf16 v[0:3], v[170:173], v[206:209], v[0:3]
	v_mfma_f32_16x16x32_bf16 v[52:55], v[166:169], v[182:185], v[52:55]
	v_mfma_f32_16x16x32_bf16 v[44:47], v[174:177], v[182:185], v[44:47]
	v_mfma_f32_16x16x32_bf16 v[36:39], v[166:169], v[194:197], v[36:39]
	v_mfma_f32_16x16x32_bf16 v[28:31], v[174:177], v[194:197], v[28:31]
	v_mfma_f32_16x16x32_bf16 v[20:23], v[166:169], v[202:205], v[20:23]
	v_mfma_f32_16x16x32_bf16 v[12:15], v[174:177], v[202:205], v[12:15]
	v_mfma_f32_16x16x32_bf16 v[4:7], v[166:169], v[210:213], v[4:7]
	v_mfma_f32_16x16x32_bf16 v[0:3], v[174:177], v[210:213], v[0:3]
	s_setprio 0
	s_barrier
	s_add_i32 s68, 0, 0x18000
	v_add_u32_e32 v138, s68, v141
	s_add_i32 s69, 0, 0x1c000
	ds_read_b128 v[142:145], v138
	ds_read_b128 v[150:153], v138 offset:1024
	ds_read_b128 v[154:157], v138 offset:2048
	ds_read_b128 v[158:161], v138 offset:3072
	v_add_u32_e32 v138, s69, v141
	ds_read_b128 v[162:165], v138
	ds_read_b128 v[166:169], v138 offset:1024
	ds_read_b128 v[170:173], v138 offset:2048
	ds_read_b128 v[174:177], v138 offset:3072
	s_add_u32 s12, s50, 0x80000
	s_addc_u32 s13, s51, 0
	s_mov_b32 m0, s56
	v_lshl_add_u64 v[220:221], s[12:13], 0, v[128:129]
	ds_read_b128 v[178:181], v149 offset:32768
	ds_read_b128 v[182:185], v149 offset:33792
	ds_read_b128 v[186:189], v149 offset:34816
	ds_read_b128 v[194:197], v149 offset:35840
	ds_read_b128 v[198:201], v149 offset:36864
	ds_read_b128 v[202:205], v149 offset:37888
	ds_read_b128 v[206:209], v149 offset:38912
	ds_read_b128 v[210:213], v149 offset:39936
	global_load_lds_dwordx4 v[220:221], off
	v_lshl_add_u64 v[220:221], s[12:13], 0, v[130:131]
	s_mov_b32 m0, s57
	s_nop 0
	global_load_lds_dwordx4 v[220:221], off
	s_waitcnt vmcnt(8)
	s_waitcnt lgkmcnt(0)
	s_barrier
	s_setprio 1
	s_waitcnt lgkmcnt(0)
	v_mfma_f32_16x16x32_bf16 v[124:127], v[142:145], v[178:181], v[124:127]
	v_mfma_f32_16x16x32_bf16 v[120:123], v[154:157], v[178:181], v[120:123]
	v_mfma_f32_16x16x32_bf16 v[108:111], v[142:145], v[186:189], v[108:111]
	v_mfma_f32_16x16x32_bf16 v[104:107], v[154:157], v[186:189], v[104:107]
	v_mfma_f32_16x16x32_bf16 v[92:95], v[142:145], v[198:201], v[92:95]
	v_mfma_f32_16x16x32_bf16 v[88:91], v[154:157], v[198:201], v[88:91]
	v_mfma_f32_16x16x32_bf16 v[76:79], v[142:145], v[206:209], v[76:79]
	v_mfma_f32_16x16x32_bf16 v[72:75], v[154:157], v[206:209], v[72:75]
	v_mfma_f32_16x16x32_bf16 v[124:127], v[150:153], v[182:185], v[124:127]
	v_mfma_f32_16x16x32_bf16 v[120:123], v[158:161], v[182:185], v[120:123]
	v_mfma_f32_16x16x32_bf16 v[108:111], v[150:153], v[194:197], v[108:111]
	v_mfma_f32_16x16x32_bf16 v[104:107], v[158:161], v[194:197], v[104:107]
	v_mfma_f32_16x16x32_bf16 v[92:95], v[150:153], v[202:205], v[92:95]
	v_mfma_f32_16x16x32_bf16 v[88:91], v[158:161], v[202:205], v[88:91]
	v_mfma_f32_16x16x32_bf16 v[76:79], v[150:153], v[210:213], v[76:79]
	v_mfma_f32_16x16x32_bf16 v[72:75], v[158:161], v[210:213], v[72:75]
	v_mfma_f32_16x16x32_bf16 v[116:119], v[162:165], v[178:181], v[116:119]
	v_mfma_f32_16x16x32_bf16 v[112:115], v[170:173], v[178:181], v[112:115]
	v_mfma_f32_16x16x32_bf16 v[100:103], v[162:165], v[186:189], v[100:103]
	v_mfma_f32_16x16x32_bf16 v[96:99], v[170:173], v[186:189], v[96:99]
	v_mfma_f32_16x16x32_bf16 v[84:87], v[162:165], v[198:201], v[84:87]
	v_mfma_f32_16x16x32_bf16 v[80:83], v[170:173], v[198:201], v[80:83]
	v_mfma_f32_16x16x32_bf16 v[68:71], v[162:165], v[206:209], v[68:71]
	v_mfma_f32_16x16x32_bf16 v[64:67], v[170:173], v[206:209], v[64:67]
	v_mfma_f32_16x16x32_bf16 v[116:119], v[166:169], v[182:185], v[116:119]
	v_mfma_f32_16x16x32_bf16 v[112:115], v[174:177], v[182:185], v[112:115]
	v_mfma_f32_16x16x32_bf16 v[100:103], v[166:169], v[194:197], v[100:103]
	v_mfma_f32_16x16x32_bf16 v[96:99], v[174:177], v[194:197], v[96:99]
	v_mfma_f32_16x16x32_bf16 v[84:87], v[166:169], v[202:205], v[84:87]
	v_mfma_f32_16x16x32_bf16 v[80:83], v[174:177], v[202:205], v[80:83]
	v_mfma_f32_16x16x32_bf16 v[68:71], v[166:169], v[210:213], v[68:71]
	v_mfma_f32_16x16x32_bf16 v[64:67], v[174:177], v[210:213], v[64:67]
	s_setprio 0
	s_barrier
; #define PG8_STAGE(bufoff, gbase, voff) do { _Pragma("unroll") for (int _i = 0; _i < 2; ++_i) \
;         __builtin_amdgcn_global_load_lds((const unsigned*)((const char*)(gbase) + (voff)[_i]), (PG8_LAS unsigned*)(lds + (bufoff) + ldsw + _i * 8192), 16, 0, 0); } while (0)
; #define PG8_LDA(dst, b, h) do { _Pragma("unroll") for (int m = 0; m < 4; ++m) _Pragma("unroll") for (int k = 0; k < 2; ++k) dst[m][k] = *(const PG8_LAS bf16x8*)(lds + PG8_SA(b, h) + aoff + m * 2048 + k * 1024); } while (0)
; #define PG8_MMA(ai, bj, At, Bt) do { __builtin_amdgcn_s_setprio(1); _Pragma("unroll") for (int m = 0; m < 4; ++m) _Pragma("unroll") for (int n = 0; n < 2; ++n) _Pragma("unroll") for (int k = 0; k < 2; ++k) \
;         acc[ai][bj][m][n] = __builtin_amdgcn_mfma_f32_16x16x32_bf16(Bt[n][k], At[m][k], acc[ai][bj][m][n], 0, 0, 0); __builtin_amdgcn_s_setprio(0); } while (0)
; #define PG8_WAIT_V(n) asm volatile("s_waitcnt vmcnt(" #n ")" ::: "memory")
; #define PG8_WAIT_L(n) asm volatile("s_waitcnt lgkmcnt(" #n ")" ::: "memory")
; #define PG8_BAR __builtin_amdgcn_s_barrier()
; #define PG8_SCHED __builtin_amdgcn_sched_barrier(0)
;     __device__ __forceinline__ void operator()(const f32x4 (&acc)[2][2][4][2], const Unit& u, int wr, int wc, int fr, int fq) const {
;     ...
;         float rsv[2][4];
; #pragma unroll
;         for (int ai = 0; ai < 2; ++ai)
; #pragma unroll
;             for (int m = 0; m < 4; ++m) rsv[ai][m] = rs ? rs[row0 + ai * HALF + m * 16] : 1.f;
; template <class Epi, class Sched, bool ALIGN_EPI = false, bool SP2 = false>
; __device__ __forceinline__ void gemm_phase(PG8_LAS unsigned char* lds, const Gemm g, const Sched& S, const Epi& E, const int tid_in) {
;     ...
;             PG8_LDA(At, 1, 1); PG8_STAGE(PG8_SB(1, 0), b3, voffB); PG8_STAGE(PG8_SB(1, 1), b3 + hstepB, voffB); PG8_STAGE(PG8_SA(1, 0), a3, voffA);
;             PG8_WAIT_V(8); PG8_WAIT_L(0); PG8_BAR; PG8_MMA(1, 0, At, B0); PG8_MMA(1, 1, At, B1); PG8_BAR; PG8_SCHED;
	s_add_i32 s12, s68, s53
	v_lshl_add_u64 v[190:191], v[190:191], 0, s[26:27]
	s_mov_b32 m0, s12
	ds_read_b128 v[178:181], v149 offset:49152
	ds_read_b128 v[182:185], v149 offset:50176
	ds_read_b128 v[186:189], v149 offset:51200
	ds_read_b128 v[194:197], v149 offset:52224
	ds_read_b128 v[198:201], v149 offset:53248
	ds_read_b128 v[202:205], v149 offset:54272
	ds_read_b128 v[206:209], v149 offset:55296
	ds_read_b128 v[210:213], v149 offset:56320
	global_load_lds_dwordx4 v[190:191], off
	s_add_i32 m0, s12, 0x2000
	s_add_u32 s12, s48, 0x80080
	v_lshl_add_u64 v[190:191], v[214:215], 0, s[26:27]
	s_addc_u32 s13, s49, 0
	s_add_i32 s48, s69, s53
	global_load_lds_dwordx4 v[190:191], off
	v_lshl_add_u64 v[190:191], s[12:13], 0, v[192:193]
	s_mov_b32 m0, s48
	s_nop 0
	global_load_lds_dwordx4 v[190:191], off
	v_lshl_add_u64 v[190:191], s[12:13], 0, v[132:133]
	s_add_i32 m0, s48, 0x2000
	s_nop 0
	global_load_lds_dwordx4 v[190:191], off
	v_lshl_add_u64 v[190:191], v[216:217], 0, s[26:27]
	s_mov_b32 m0, s58
	s_nop 0
	global_load_lds_dwordx4 v[190:191], off
	v_lshl_add_u64 v[190:191], v[218:219], 0, s[26:27]
	s_mov_b32 m0, s59
	s_nop 0
	global_load_lds_dwordx4 v[190:191], off
	s_waitcnt vmcnt(8)
	s_waitcnt lgkmcnt(0)
	s_barrier
	s_setprio 1
	s_waitcnt lgkmcnt(0)
	v_mfma_f32_16x16x32_bf16 v[60:63], v[142:145], v[178:181], v[60:63]
	v_mfma_f32_16x16x32_bf16 v[56:59], v[154:157], v[178:181], v[56:59]
	v_mfma_f32_16x16x32_bf16 v[48:51], v[142:145], v[186:189], v[48:51]
	v_mfma_f32_16x16x32_bf16 v[40:43], v[154:157], v[186:189], v[40:43]
	v_mfma_f32_16x16x32_bf16 v[32:35], v[142:145], v[198:201], v[32:35]
	v_mfma_f32_16x16x32_bf16 v[24:27], v[154:157], v[198:201], v[24:27]
	v_mfma_f32_16x16x32_bf16 v[16:19], v[142:145], v[206:209], v[16:19]
	v_mfma_f32_16x16x32_bf16 v[8:11], v[154:157], v[206:209], v[8:11]
	v_mfma_f32_16x16x32_bf16 v[60:63], v[150:153], v[182:185], v[60:63]
	v_mfma_f32_16x16x32_bf16 v[56:59], v[158:161], v[182:185], v[56:59]
	v_mfma_f32_16x16x32_bf16 v[48:51], v[150:153], v[194:197], v[48:51]
	v_mfma_f32_16x16x32_bf16 v[40:43], v[158:161], v[194:197], v[40:43]
	v_mfma_f32_16x16x32_bf16 v[32:35], v[150:153], v[202:205], v[32:35]
	v_mfma_f32_16x16x32_bf16 v[24:27], v[158:161], v[202:205], v[24:27]
	v_mfma_f32_16x16x32_bf16 v[16:19], v[150:153], v[210:213], v[16:19]
	v_mfma_f32_16x16x32_bf16 v[8:11], v[158:161], v[210:213], v[8:11]
	v_mfma_f32_16x16x32_bf16 v[52:55], v[162:165], v[178:181], v[52:55]
	v_mfma_f32_16x16x32_bf16 v[44:47], v[170:173], v[178:181], v[44:47]
	v_mfma_f32_16x16x32_bf16 v[36:39], v[162:165], v[186:189], v[36:39]
	v_mfma_f32_16x16x32_bf16 v[28:31], v[170:173], v[186:189], v[28:31]
	v_mfma_f32_16x16x32_bf16 v[20:23], v[162:165], v[198:201], v[20:23]
	v_mfma_f32_16x16x32_bf16 v[12:15], v[170:173], v[198:201], v[12:15]
	v_mfma_f32_16x16x32_bf16 v[4:7], v[162:165], v[206:209], v[4:7]
	v_mfma_f32_16x16x32_bf16 v[0:3], v[170:173], v[206:209], v[0:3]
	v_mfma_f32_16x16x32_bf16 v[52:55], v[166:169], v[182:185], v[52:55]
	v_mfma_f32_16x16x32_bf16 v[44:47], v[174:177], v[182:185], v[44:47]
	v_mfma_f32_16x16x32_bf16 v[36:39], v[166:169], v[194:197], v[36:39]
	v_mfma_f32_16x16x32_bf16 v[28:31], v[174:177], v[194:197], v[28:31]
	v_mfma_f32_16x16x32_bf16 v[20:23], v[166:169], v[202:205], v[20:23]
	v_mfma_f32_16x16x32_bf16 v[12:15], v[174:177], v[202:205], v[12:15]
	v_mfma_f32_16x16x32_bf16 v[4:7], v[166:169], v[210:213], v[4:7]
	v_mfma_f32_16x16x32_bf16 v[0:3], v[174:177], v[210:213], v[0:3]
	s_setprio 0
	s_barrier
	s_add_i32 s67, s67, 2
	s_add_u32 s46, s46, 0x100
	s_addc_u32 s47, s47, 0
	s_add_u32 s65, s65, 0x100
	s_addc_u32 s66, s66, 0
	s_cmp_gt_u32 s67, 29
	s_cbranch_scc0 .LBB0_289
	s_andn2_b64 vcc, s[36:37], s[34:35]
	s_cbranch_vccz .LBB0_292
	s_barrier
.LBB0_292:
	v_lshl_add_u32 v144, s62, 8, v139
	v_ashrrev_i32_e32 v145, 31, v144
	v_lshl_add_u64 v[142:143], v[144:145], 2, s[30:31]
	global_load_dword v154, v[142:143], off
	global_load_dword v156, v[142:143], off offset:64
	global_load_dword v152, v[142:143], off offset:128
	global_load_dword v150, v[142:143], off offset:192
	global_load_dword v148, v[142:143], off offset:512
	global_load_dword v146, v[142:143], off offset:576
	global_load_dword v140, v[142:143], off offset:640
	global_load_dword v138, v[142:143], off offset:704
	v_lshl_or_b32 v142, s61, 8, v147
	v_ashrrev_i32_e32 v143, 31, v142
	v_lshl_add_u64 v[142:143], v[142:143], 1, s[28:29]
	s_movk_i32 s39, 0xa00
	v_mad_i64_i32 v[158:159], s[12:13], v144, s39, v[142:143]
	v_add_u32_e32 v151, 0x80, v144
	v_add_u32_e32 v145, 0xb0, v144
	s_mov_b64 s[46:47], -1
	s_andn2_b64 vcc, exec, s[34:35]
	s_waitcnt vmcnt(0)
; __device__ __forceinline__ unsigned cvt_pk_bf16(float lo, float hi) { unsigned r; asm volatile("v_cvt_pk_bf16_f32 %0, %1, %2" : "=v"(r) : "v"(lo), "v"(hi)); return r; }
;     __device__ __forceinline__ void operator()(const f32x4 (&acc)[2][2][4][2], const Unit& u, int wr, int wc, int fr, int fq) const {
;     ...
;         for (int ai = 0; ai < 2; ++ai)
; #pragma unroll
;             for (int m = 0; m < 4; ++m) { bf16_t* rowp = base + (size_t)(row0 + ai * HALF + m * 16) * ldc + col0;
;                 const float rsc = rsv[ai][m];
; #pragma unroll
;                 for (int bj = 0; bj < 2; ++bj) { f32x4 v0 = acc[ai][bj][m][0] * rsc, v1 = acc[ai][bj][m][1] * rsc;
;                     if (ACT == 1) {
; #pragma unroll
;                         for (int e = 0; e < 4; ++e) { const float a = fmaxf(v0[e], 0.f), b = fmaxf(v1[e], 0.f); v0[e] = a * a; v1[e] = b * b; } }
;                     u32x4 w; w.x = cvt_pk_bf16(v0[0], v0[1]); w.y = cvt_pk_bf16(v0[2], v0[3]); w.z = cvt_pk_bf16(v1[0], v1[1]); w.w = cvt_pk_bf16(v1[2], v1[3]);
;                     *(u32x4*)(rowp + bj * HALF) = w; } }
	v_pk_mul_f32 v[126:127], v[126:127], v[154:155] op_sel_hi:[1,0]
	v_pk_mul_f32 v[124:125], v[124:125], v[154:155] op_sel_hi:[1,0]
	v_pk_mul_f32 v[160:161], v[122:123], v[154:155] op_sel_hi:[1,0]
	v_pk_mul_f32 v[122:123], v[120:121], v[154:155] op_sel_hi:[1,0]
	v_cvt_pk_bf16_f32 v120, v124, v125
	v_cvt_pk_bf16_f32 v121, v126, v127
	v_pk_mul_f32 v[116:117], v[116:117], v[154:155] op_sel_hi:[1,0]
	v_cvt_pk_bf16_f32 v122, v122, v123
	v_cvt_pk_bf16_f32 v123, v160, v161
	global_store_dwordx4 v[158:159], v[120:123], off
	v_pk_mul_f32 v[118:119], v[118:119], v[154:155] op_sel_hi:[1,0]
	v_pk_mul_f32 v[110:111], v[110:111], v[156:157] op_sel_hi:[1,0]
	v_pk_mul_f32 v[120:121], v[114:115], v[154:155] op_sel_hi:[1,0]
	v_pk_mul_f32 v[114:115], v[112:113], v[154:155] op_sel_hi:[1,0]
	v_cvt_pk_bf16_f32 v112, v116, v117
	v_cvt_pk_bf16_f32 v113, v118, v119
	v_pk_mul_f32 v[108:109], v[108:109], v[156:157] op_sel_hi:[1,0]
	v_cvt_pk_bf16_f32 v114, v114, v115
	v_cvt_pk_bf16_f32 v115, v120, v121
	global_store_dwordx4 v[158:159], v[112:115], off offset:256
	v_pk_mul_f32 v[100:101], v[100:101], v[156:157] op_sel_hi:[1,0]
	v_pk_mul_f32 v[102:103], v[102:103], v[156:157] op_sel_hi:[1,0]
	v_or_b32_e32 v112, 16, v144
	v_mad_i64_i32 v[112:113], s[12:13], v112, s39, v[142:143]
	v_pk_mul_f32 v[114:115], v[106:107], v[156:157] op_sel_hi:[1,0]
	v_pk_mul_f32 v[106:107], v[104:105], v[156:157] op_sel_hi:[1,0]
	v_cvt_pk_bf16_f32 v104, v108, v109
	v_cvt_pk_bf16_f32 v105, v110, v111
	v_pk_mul_f32 v[94:95], v[94:95], v[152:153] op_sel_hi:[1,0]
	v_cvt_pk_bf16_f32 v106, v106, v107
	v_cvt_pk_bf16_f32 v107, v114, v115
	global_store_dwordx4 v[112:113], v[104:107], off
	v_pk_mul_f32 v[92:93], v[92:93], v[152:153] op_sel_hi:[1,0]
	v_pk_mul_f32 v[84:85], v[84:85], v[152:153] op_sel_hi:[1,0]
	v_pk_mul_f32 v[104:105], v[98:99], v[156:157] op_sel_hi:[1,0]
	v_pk_mul_f32 v[98:99], v[96:97], v[156:157] op_sel_hi:[1,0]
	v_cvt_pk_bf16_f32 v96, v100, v101
	v_cvt_pk_bf16_f32 v97, v102, v103
	v_pk_mul_f32 v[86:87], v[86:87], v[152:153] op_sel_hi:[1,0]
	v_cvt_pk_bf16_f32 v98, v98, v99
	v_cvt_pk_bf16_f32 v99, v104, v105
	global_store_dwordx4 v[112:113], v[96:99], off offset:256
	v_pk_mul_f32 v[78:79], v[78:79], v[150:151] op_sel_hi:[1,0]
	v_pk_mul_f32 v[76:77], v[76:77], v[150:151] op_sel_hi:[1,0]
	v_or_b32_e32 v96, 32, v144
	v_mad_i64_i32 v[96:97], s[12:13], v96, s39, v[142:143]
	v_pk_mul_f32 v[98:99], v[90:91], v[152:153] op_sel_hi:[1,0]
	v_pk_mul_f32 v[90:91], v[88:89], v[152:153] op_sel_hi:[1,0]
	v_cvt_pk_bf16_f32 v88, v92, v93
	v_cvt_pk_bf16_f32 v89, v94, v95
	v_pk_mul_f32 v[70:71], v[70:71], v[150:151] op_sel_hi:[1,0]
	v_cvt_pk_bf16_f32 v90, v90, v91
	v_cvt_pk_bf16_f32 v91, v98, v99
	global_store_dwordx4 v[96:97], v[88:91], off
	v_pk_mul_f32 v[68:69], v[68:69], v[150:151] op_sel_hi:[1,0]
	v_pk_mul_f32 v[62:63], v[62:63], v[148:149] op_sel_hi:[1,0]
	v_pk_mul_f32 v[88:89], v[82:83], v[152:153] op_sel_hi:[1,0]
	v_pk_mul_f32 v[82:83], v[80:81], v[152:153] op_sel_hi:[1,0]
	v_cvt_pk_bf16_f32 v80, v84, v85
	v_cvt_pk_bf16_f32 v81, v86, v87
	v_pk_mul_f32 v[60:61], v[60:61], v[148:149] op_sel_hi:[1,0]
	v_cvt_pk_bf16_f32 v82, v82, v83
	v_cvt_pk_bf16_f32 v83, v88, v89
	global_store_dwordx4 v[96:97], v[80:83], off offset:256
	v_pk_mul_f32 v[52:53], v[52:53], v[148:149] op_sel_hi:[1,0]
	v_pk_mul_f32 v[54:55], v[54:55], v[148:149] op_sel_hi:[1,0]
	v_or_b32_e32 v80, 48, v144
	v_mad_i64_i32 v[80:81], s[12:13], v80, s39, v[142:143]
	v_pk_mul_f32 v[82:83], v[74:75], v[150:151] op_sel_hi:[1,0]
	v_pk_mul_f32 v[74:75], v[72:73], v[150:151] op_sel_hi:[1,0]
	v_cvt_pk_bf16_f32 v72, v76, v77
	v_cvt_pk_bf16_f32 v73, v78, v79
	v_pk_mul_f32 v[48:49], v[48:49], v[146:147] op_sel_hi:[1,0]
	v_cvt_pk_bf16_f32 v74, v74, v75
	v_cvt_pk_bf16_f32 v75, v82, v83
	global_store_dwordx4 v[80:81], v[72:75], off
	v_pk_mul_f32 v[36:37], v[36:37], v[146:147] op_sel_hi:[1,0]
; __device__ __forceinline__ unsigned cvt_pk_bf16(float lo, float hi) { unsigned r; asm volatile("v_cvt_pk_bf16_f32 %0, %1, %2" : "=v"(r) : "v"(lo), "v"(hi)); return r; }
; #define PG8_BAR __builtin_amdgcn_s_barrier()
;     __device__ __forceinline__ void operator()(const f32x4 (&acc)[2][2][4][2], const Unit& u, int wr, int wc, int fr, int fq) const {
;     ...
;         for (int ai = 0; ai < 2; ++ai)
; #pragma unroll
;             for (int m = 0; m < 4; ++m) { bf16_t* rowp = base + (size_t)(row0 + ai * HALF + m * 16) * ldc + col0;
;                 const float rsc = rsv[ai][m];
; #pragma unroll
;                 for (int bj = 0; bj < 2; ++bj) { f32x4 v0 = acc[ai][bj][m][0] * rsc, v1 = acc[ai][bj][m][1] * rsc;
;                     if (ACT == 1) {
; #pragma unroll
;                         for (int e = 0; e < 4; ++e) { const float a = fmaxf(v0[e], 0.f), b = fmaxf(v1[e], 0.f); v0[e] = a * a; v1[e] = b * b; } }
;                     u32x4 w; w.x = cvt_pk_bf16(v0[0], v0[1]); w.y = cvt_pk_bf16(v0[2], v0[3]); w.z = cvt_pk_bf16(v1[0], v1[1]); w.w = cvt_pk_bf16(v1[2], v1[3]);
;                     *(u32x4*)(rowp + bj * HALF) = w; } }
; template <class Epi, class Sched, bool ALIGN_EPI = false, bool SP2 = false>
; __device__ __forceinline__ void gemm_phase(PG8_LAS unsigned char* lds, const Gemm g, const Sched& S, const Epi& E, const int tid_in) {
;     ...
;         if (!has_next) break;
; #pragma unroll
;         for (int a = 0; a < 2; ++a)
; #pragma unroll
;             for (int b = 0; b < 2; ++b)
; #pragma unroll
;                 for (int m = 0; m < 4; ++m)
; #pragma unroll
;                     for (int n = 0; n < 2; ++n) acc[a][b][m][n] = (f32x4){0.f, 0.f, 0.f, 0.f};
;         cur = nxt; cA = nA; cB = nB; ++ui;
;         if constexpr (ALIGN_EPI) { if (wr == 1) PG8_BAR; }
	v_pk_mul_f32 v[38:39], v[38:39], v[146:147] op_sel_hi:[1,0]
	v_pk_mul_f32 v[72:73], v[66:67], v[150:151] op_sel_hi:[1,0]
	v_pk_mul_f32 v[66:67], v[64:65], v[150:151] op_sel_hi:[1,0]
	v_cvt_pk_bf16_f32 v64, v68, v69
	v_cvt_pk_bf16_f32 v65, v70, v71
	v_pk_mul_f32 v[32:33], v[32:33], v[140:141] op_sel_hi:[1,0]
	v_cvt_pk_bf16_f32 v66, v66, v67
	v_cvt_pk_bf16_f32 v67, v72, v73
	global_store_dwordx4 v[80:81], v[64:67], off offset:256
	v_pk_mul_f32 v[22:23], v[22:23], v[140:141] op_sel_hi:[1,0]
	v_pk_mul_f32 v[20:21], v[20:21], v[140:141] op_sel_hi:[1,0]
	v_mad_i64_i32 v[64:65], s[12:13], v151, s39, v[142:143]
	v_pk_mul_f32 v[66:67], v[58:59], v[148:149] op_sel_hi:[1,0]
	v_pk_mul_f32 v[58:59], v[56:57], v[148:149] op_sel_hi:[1,0]
	v_cvt_pk_bf16_f32 v56, v60, v61
	v_cvt_pk_bf16_f32 v57, v62, v63
	v_pk_mul_f32 v[16:17], v[16:17], v[138:139] op_sel_hi:[1,0]
	v_cvt_pk_bf16_f32 v58, v58, v59
	v_cvt_pk_bf16_f32 v59, v66, v67
	global_store_dwordx4 v[64:65], v[56:59], off
	v_pk_mul_f32 v[6:7], v[6:7], v[138:139] op_sel_hi:[1,0]
	v_pk_mul_f32 v[4:5], v[4:5], v[138:139] op_sel_hi:[1,0]
	v_pk_mul_f32 v[56:57], v[46:47], v[148:149] op_sel_hi:[1,0]
	v_pk_mul_f32 v[46:47], v[44:45], v[148:149] op_sel_hi:[1,0]
	v_cvt_pk_bf16_f32 v44, v52, v53
	v_cvt_pk_bf16_f32 v45, v54, v55
	s_nop 0
	v_cvt_pk_bf16_f32 v46, v46, v47
	v_cvt_pk_bf16_f32 v47, v56, v57
	global_store_dwordx4 v[64:65], v[44:47], off offset:256
	s_nop 1
	v_add_u32_e32 v44, 0x90, v144
	v_mad_i64_i32 v[44:45], s[12:13], v44, s39, v[142:143]
	v_pk_mul_f32 v[46:47], v[50:51], v[146:147] op_sel_hi:[1,0]
	v_pk_mul_f32 v[50:51], v[42:43], v[146:147] op_sel_hi:[1,0]
	v_pk_mul_f32 v[42:43], v[40:41], v[146:147] op_sel_hi:[1,0]
	v_cvt_pk_bf16_f32 v40, v48, v49
	v_cvt_pk_bf16_f32 v41, v46, v47
	s_nop 0
	v_cvt_pk_bf16_f32 v42, v42, v43
	v_cvt_pk_bf16_f32 v43, v50, v51
	global_store_dwordx4 v[44:45], v[40:43], off
	s_nop 1
	v_pk_mul_f32 v[40:41], v[30:31], v[146:147] op_sel_hi:[1,0]
	v_pk_mul_f32 v[30:31], v[28:29], v[146:147] op_sel_hi:[1,0]
	v_cvt_pk_bf16_f32 v28, v36, v37
	v_cvt_pk_bf16_f32 v29, v38, v39
	s_nop 0
	v_cvt_pk_bf16_f32 v30, v30, v31
	v_cvt_pk_bf16_f32 v31, v40, v41
	global_store_dwordx4 v[44:45], v[28:31], off offset:256
	s_nop 1
	v_add_u32_e32 v28, 0xa0, v144
	v_mad_i64_i32 v[28:29], s[12:13], v28, s39, v[142:143]
	v_pk_mul_f32 v[30:31], v[34:35], v[140:141] op_sel_hi:[1,0]
	v_pk_mul_f32 v[34:35], v[26:27], v[140:141] op_sel_hi:[1,0]
	v_pk_mul_f32 v[26:27], v[24:25], v[140:141] op_sel_hi:[1,0]
	v_cvt_pk_bf16_f32 v24, v32, v33
	v_cvt_pk_bf16_f32 v25, v30, v31
	s_nop 0
	v_cvt_pk_bf16_f32 v26, v26, v27
	v_cvt_pk_bf16_f32 v27, v34, v35
	global_store_dwordx4 v[28:29], v[24:27], off
	s_nop 1
	v_pk_mul_f32 v[24:25], v[14:15], v[140:141] op_sel_hi:[1,0]
	v_pk_mul_f32 v[14:15], v[12:13], v[140:141] op_sel_hi:[1,0]
	v_cvt_pk_bf16_f32 v12, v20, v21
	v_cvt_pk_bf16_f32 v13, v22, v23
	s_nop 0
	v_cvt_pk_bf16_f32 v14, v14, v15
	v_cvt_pk_bf16_f32 v15, v24, v25
	global_store_dwordx4 v[28:29], v[12:15], off offset:256
	s_nop 1
	v_mad_i64_i32 v[12:13], s[12:13], v145, s39, v[142:143]
	v_pk_mul_f32 v[14:15], v[18:19], v[138:139] op_sel_hi:[1,0]
	v_pk_mul_f32 v[18:19], v[10:11], v[138:139] op_sel_hi:[1,0]
	v_pk_mul_f32 v[10:11], v[8:9], v[138:139] op_sel_hi:[1,0]
	v_cvt_pk_bf16_f32 v8, v16, v17
	v_cvt_pk_bf16_f32 v9, v14, v15
	s_nop 0
	v_cvt_pk_bf16_f32 v10, v10, v11
	v_cvt_pk_bf16_f32 v11, v18, v19
	global_store_dwordx4 v[12:13], v[8:11], off
	s_nop 1
	v_pk_mul_f32 v[8:9], v[2:3], v[138:139] op_sel_hi:[1,0]
	v_pk_mul_f32 v[2:3], v[0:1], v[138:139] op_sel_hi:[1,0]
	v_cvt_pk_bf16_f32 v0, v4, v5
	v_cvt_pk_bf16_f32 v1, v6, v7
	s_nop 0
	v_cvt_pk_bf16_f32 v2, v2, v3
	v_cvt_pk_bf16_f32 v3, v8, v9
	global_store_dwordx4 v[12:13], v[0:3], off offset:256
	s_cbranch_vccnz .LBB0_281
	s_andn2_b64 vcc, exec, s[22:23]
	s_cbranch_vccnz .LBB0_280
	s_branch .LBB0_280

; #define PG8_STAGE(bufoff, gbase, voff) do { _Pragma("unroll") for (int _i = 0; _i < 2; ++_i) \
;         __builtin_amdgcn_global_load_lds((const unsigned*)((const char*)(gbase) + (voff)[_i]), (PG8_LAS unsigned*)(lds + (bufoff) + ldsw + _i * 8192), 16, 0, 0); } while (0)
; #define PG8_LDA(dst, b, h) do { _Pragma("unroll") for (int m = 0; m < 4; ++m) _Pragma("unroll") for (int k = 0; k < 2; ++k) dst[m][k] = *(const PG8_LAS bf16x8*)(lds + PG8_SA(b, h) + aoff + m * 2048 + k * 1024); } while (0)
; #define PG8_LDB(dst, b, h) do { _Pragma("unroll") for (int n = 0; n < 2; ++n) _Pragma("unroll") for (int k = 0; k < 2; ++k) dst[n][k] = *(const PG8_LAS bf16x8*)(lds + PG8_SB(b, h) + boff + n * 2048 + k * 1024); } while (0)
; #define PG8_MMA(ai, bj, At, Bt) do { __builtin_amdgcn_s_setprio(1); _Pragma("unroll") for (int m = 0; m < 4; ++m) _Pragma("unroll") for (int n = 0; n < 2; ++n) _Pragma("unroll") for (int k = 0; k < 2; ++k) \
;         acc[ai][bj][m][n] = __builtin_amdgcn_mfma_f32_16x16x32_bf16(Bt[n][k], At[m][k], acc[ai][bj][m][n], 0, 0, 0); __builtin_amdgcn_s_setprio(0); } while (0)
; #define PG8_WAIT_V(n) asm volatile("s_waitcnt vmcnt(" #n ")" ::: "memory")
; #define PG8_WAIT_L(n) asm volatile("s_waitcnt lgkmcnt(" #n ")" ::: "memory")
; #define PG8_BAR __builtin_amdgcn_s_barrier()
; #define PG8_SCHED __builtin_amdgcn_sched_barrier(0)
; template <class Epi, class Sched, bool ALIGN_EPI = false, bool SP2 = false>
; __device__ __forceinline__ void gemm_phase(PG8_LAS unsigned char* lds, const Gemm g, const Sched& S, const Epi& E, const int tid_in) {
;     ...
;             PG8_LDB(B0, 0, 0); PG8_LDB(B1, 0, 1); PG8_SCHED; PG8_LDA(At, 0, 0); PG8_STAGE(PG8_SA(1, 1), a1 + hstepA, voffA);
;             PG8_WAIT_V(8); PG8_WAIT_L(0); PG8_BAR; PG8_MMA(0, 0, At, B0); PG8_MMA(0, 1, At, B1); PG8_BAR; PG8_SCHED;
;             PG8_LDA(At, 0, 1); PG8_STAGE(PG8_SB(0, 0), b2, voffB); PG8_STAGE(PG8_SB(0, 1), b2 + hstepB, voffB); PG8_STAGE(PG8_SA(0, 0), a2, voffA);
;             PG8_WAIT_V(8); PG8_WAIT_L(0); PG8_BAR; PG8_MMA(1, 0, At, B0); PG8_MMA(1, 1, At, B1); PG8_BAR; PG8_SCHED;
.LBB0_427:
	s_add_u32 s12, s52, 0xfffc0080
	s_addc_u32 s13, s53, -1
	s_add_i32 s70, 0, 0x10000
	s_cmp_eq_u32 s69, 4
	s_cselect_b32 s57, s1, s13
	s_cselect_b32 s56, s37, s12
	s_cselect_b32 s55, s45, s68
	s_cselect_b32 s54, s47, s67
	s_add_i32 s71, 0, 0x14000
	v_add_u32_e32 v140, s70, v242
	v_add_u32_e32 v156, s71, v242
	ds_read_b128 v[128:131], v140
	ds_read_b128 v[132:135], v140 offset:1024
	ds_read_b128 v[136:139], v140 offset:2048
	ds_read_b128 v[140:143], v140 offset:3072
	ds_read_b128 v[144:147], v156
	ds_read_b128 v[148:151], v156 offset:1024
	ds_read_b128 v[152:155], v156 offset:2048
	ds_read_b128 v[156:159], v156 offset:3072
	v_lshl_add_u64 v[194:195], s[52:53], 0, v[206:207]
	s_add_i32 m0, s60, 0xc000
	ds_read_b128 v[160:163], v244
	ds_read_b128 v[164:167], v244 offset:1024
	ds_read_b128 v[168:171], v244 offset:2048
	ds_read_b128 v[172:175], v244 offset:3072
	ds_read_b128 v[176:179], v244 offset:4096
	ds_read_b128 v[180:183], v244 offset:5120
	ds_read_b128 v[184:187], v244 offset:6144
	ds_read_b128 v[188:191], v244 offset:7168
	global_load_lds_dwordx4 v[194:195], off
	v_lshl_add_u64 v[194:195], s[52:53], 0, v[208:209]
	s_add_i32 m0, s60, 0xe000
	s_nop 0
	global_load_lds_dwordx4 v[194:195], off
	s_waitcnt vmcnt(8)
	s_waitcnt lgkmcnt(0)
	s_barrier
	s_setprio 1
	s_waitcnt lgkmcnt(0)
	v_mfma_f32_16x16x32_bf16 v[124:127], v[128:131], v[160:163], v[124:127]
	v_mfma_f32_16x16x32_bf16 v[120:123], v[136:139], v[160:163], v[120:123]
	v_mfma_f32_16x16x32_bf16 v[108:111], v[128:131], v[168:171], v[108:111]
	v_mfma_f32_16x16x32_bf16 v[104:107], v[136:139], v[168:171], v[104:107]
	v_mfma_f32_16x16x32_bf16 v[92:95], v[128:131], v[176:179], v[92:95]
	v_mfma_f32_16x16x32_bf16 v[88:91], v[136:139], v[176:179], v[88:91]
	v_mfma_f32_16x16x32_bf16 v[76:79], v[128:131], v[184:187], v[76:79]
	v_mfma_f32_16x16x32_bf16 v[72:75], v[136:139], v[184:187], v[72:75]
	v_mfma_f32_16x16x32_bf16 v[124:127], v[132:135], v[164:167], v[124:127]
	v_mfma_f32_16x16x32_bf16 v[120:123], v[140:143], v[164:167], v[120:123]
	v_mfma_f32_16x16x32_bf16 v[108:111], v[132:135], v[172:175], v[108:111]
	v_mfma_f32_16x16x32_bf16 v[104:107], v[140:143], v[172:175], v[104:107]
	v_mfma_f32_16x16x32_bf16 v[92:95], v[132:135], v[180:183], v[92:95]
	v_mfma_f32_16x16x32_bf16 v[88:91], v[140:143], v[180:183], v[88:91]
	v_mfma_f32_16x16x32_bf16 v[76:79], v[132:135], v[188:191], v[76:79]
	v_mfma_f32_16x16x32_bf16 v[72:75], v[140:143], v[188:191], v[72:75]
	v_mfma_f32_16x16x32_bf16 v[116:119], v[144:147], v[160:163], v[116:119]
	v_mfma_f32_16x16x32_bf16 v[112:115], v[152:155], v[160:163], v[112:115]
	v_mfma_f32_16x16x32_bf16 v[100:103], v[144:147], v[168:171], v[100:103]
	v_mfma_f32_16x16x32_bf16 v[96:99], v[152:155], v[168:171], v[96:99]
	v_mfma_f32_16x16x32_bf16 v[84:87], v[144:147], v[176:179], v[84:87]
	v_mfma_f32_16x16x32_bf16 v[80:83], v[152:155], v[176:179], v[80:83]
	v_mfma_f32_16x16x32_bf16 v[68:71], v[144:147], v[184:187], v[68:71]
	v_mfma_f32_16x16x32_bf16 v[64:67], v[152:155], v[184:187], v[64:67]
	v_mfma_f32_16x16x32_bf16 v[116:119], v[148:151], v[164:167], v[116:119]
	v_mfma_f32_16x16x32_bf16 v[112:115], v[156:159], v[164:167], v[112:115]
	v_mfma_f32_16x16x32_bf16 v[100:103], v[148:151], v[172:175], v[100:103]
	v_mfma_f32_16x16x32_bf16 v[96:99], v[156:159], v[172:175], v[96:99]
	v_mfma_f32_16x16x32_bf16 v[84:87], v[148:151], v[180:183], v[84:87]
	v_mfma_f32_16x16x32_bf16 v[80:83], v[156:159], v[180:183], v[80:83]
	v_mfma_f32_16x16x32_bf16 v[68:71], v[148:151], v[188:191], v[68:71]
	v_mfma_f32_16x16x32_bf16 v[64:67], v[156:159], v[188:191], v[64:67]
	s_setprio 0
	s_barrier
	s_add_i32 s12, s70, s59
	v_lshl_add_u64 v[194:195], s[54:55], 0, v[200:201]
	s_mov_b32 m0, s12
	ds_read_b128 v[160:163], v244 offset:16384
	ds_read_b128 v[164:167], v244 offset:17408
	ds_read_b128 v[168:171], v244 offset:18432
	ds_read_b128 v[172:175], v244 offset:19456
	ds_read_b128 v[176:179], v244 offset:20480
	ds_read_b128 v[180:183], v244 offset:21504
	ds_read_b128 v[184:187], v244 offset:22528
	ds_read_b128 v[188:191], v244 offset:23552
	global_load_lds_dwordx4 v[194:195], off
	s_add_i32 m0, s12, 0x2000
	s_add_u32 s12, s54, 0x20000
	v_lshl_add_u64 v[196:197], s[54:55], 0, v[204:205]
	s_addc_u32 s13, s55, 0
	s_add_i32 s70, s71, s59
	global_load_lds_dwordx4 v[196:197], off
	v_lshl_add_u64 v[210:211], s[12:13], 0, v[200:201]
	s_mov_b32 m0, s70
	v_lshl_add_u64 v[212:213], s[56:57], 0, v[202:203]
	global_load_lds_dwordx4 v[210:211], off
	v_lshl_add_u64 v[210:211], s[12:13], 0, v[204:205]
	s_add_i32 m0, s70, 0x2000
	s_nop 0
	global_load_lds_dwordx4 v[210:211], off
	v_lshl_add_u64 v[210:211], s[56:57], 0, v[198:199]
	s_mov_b32 m0, s60
	s_nop 0
	global_load_lds_dwordx4 v[210:211], off
	s_mov_b32 m0, s61
	s_nop 0
	global_load_lds_dwordx4 v[212:213], off
	s_waitcnt vmcnt(8)
	s_waitcnt lgkmcnt(0)
	s_barrier
; #define PG8_STAGE(bufoff, gbase, voff) do { _Pragma("unroll") for (int _i = 0; _i < 2; ++_i) \
;         __builtin_amdgcn_global_load_lds((const unsigned*)((const char*)(gbase) + (voff)[_i]), (PG8_LAS unsigned*)(lds + (bufoff) + ldsw + _i * 8192), 16, 0, 0); } while (0)
; #define PG8_LDA(dst, b, h) do { _Pragma("unroll") for (int m = 0; m < 4; ++m) _Pragma("unroll") for (int k = 0; k < 2; ++k) dst[m][k] = *(const PG8_LAS bf16x8*)(lds + PG8_SA(b, h) + aoff + m * 2048 + k * 1024); } while (0)
; #define PG8_LDB(dst, b, h) do { _Pragma("unroll") for (int n = 0; n < 2; ++n) _Pragma("unroll") for (int k = 0; k < 2; ++k) dst[n][k] = *(const PG8_LAS bf16x8*)(lds + PG8_SB(b, h) + boff + n * 2048 + k * 1024); } while (0)
; #define PG8_MMA(ai, bj, At, Bt) do { __builtin_amdgcn_s_setprio(1); _Pragma("unroll") for (int m = 0; m < 4; ++m) _Pragma("unroll") for (int n = 0; n < 2; ++n) _Pragma("unroll") for (int k = 0; k < 2; ++k) \
;         acc[ai][bj][m][n] = __builtin_amdgcn_mfma_f32_16x16x32_bf16(Bt[n][k], At[m][k], acc[ai][bj][m][n], 0, 0, 0); __builtin_amdgcn_s_setprio(0); } while (0)
; #define PG8_WAIT_V(n) asm volatile("s_waitcnt vmcnt(" #n ")" ::: "memory")
; #define PG8_WAIT_L(n) asm volatile("s_waitcnt lgkmcnt(" #n ")" ::: "memory")
; #define PG8_BAR __builtin_amdgcn_s_barrier()
; #define PG8_SCHED __builtin_amdgcn_sched_barrier(0)
; template <class Epi, class Sched, bool ALIGN_EPI = false, bool SP2 = false>
; __device__ __forceinline__ void gemm_phase(PG8_LAS unsigned char* lds, const Gemm g, const Sched& S, const Epi& E, const int tid_in) {
;     ...
;             PG8_WAIT_V(8); PG8_WAIT_L(0); PG8_BAR; PG8_MMA(1, 0, At, B0); PG8_MMA(1, 1, At, B1); PG8_BAR; PG8_SCHED;
;             PG8_LDB(B0, 1, 0); PG8_LDB(B1, 1, 1); PG8_SCHED; PG8_LDA(At, 1, 0); PG8_STAGE(PG8_SA(0, 1), a2 + hstepA, voffA);
;             PG8_WAIT_V(8); PG8_WAIT_L(0); PG8_BAR; PG8_MMA(0, 0, At, B0); PG8_MMA(0, 1, At, B1); PG8_BAR; PG8_SCHED;
	s_setprio 1
	s_waitcnt lgkmcnt(0)
	v_mfma_f32_16x16x32_bf16 v[60:63], v[128:131], v[160:163], v[60:63]
	v_mfma_f32_16x16x32_bf16 v[56:59], v[136:139], v[160:163], v[56:59]
	v_mfma_f32_16x16x32_bf16 v[44:47], v[128:131], v[168:171], v[44:47]
	v_mfma_f32_16x16x32_bf16 v[40:43], v[136:139], v[168:171], v[40:43]
	v_mfma_f32_16x16x32_bf16 v[28:31], v[128:131], v[176:179], v[28:31]
	v_mfma_f32_16x16x32_bf16 v[24:27], v[136:139], v[176:179], v[24:27]
	v_mfma_f32_16x16x32_bf16 v[12:15], v[128:131], v[184:187], v[12:15]
	v_mfma_f32_16x16x32_bf16 v[8:11], v[136:139], v[184:187], v[8:11]
	v_mfma_f32_16x16x32_bf16 v[60:63], v[132:135], v[164:167], v[60:63]
	v_mfma_f32_16x16x32_bf16 v[56:59], v[140:143], v[164:167], v[56:59]
	v_mfma_f32_16x16x32_bf16 v[44:47], v[132:135], v[172:175], v[44:47]
	v_mfma_f32_16x16x32_bf16 v[40:43], v[140:143], v[172:175], v[40:43]
	v_mfma_f32_16x16x32_bf16 v[28:31], v[132:135], v[180:183], v[28:31]
	v_mfma_f32_16x16x32_bf16 v[24:27], v[140:143], v[180:183], v[24:27]
	v_mfma_f32_16x16x32_bf16 v[12:15], v[132:135], v[188:191], v[12:15]
	v_mfma_f32_16x16x32_bf16 v[8:11], v[140:143], v[188:191], v[8:11]
	v_mfma_f32_16x16x32_bf16 v[52:55], v[144:147], v[160:163], v[52:55]
	v_mfma_f32_16x16x32_bf16 v[48:51], v[152:155], v[160:163], v[48:51]
	v_mfma_f32_16x16x32_bf16 v[36:39], v[144:147], v[168:171], v[36:39]
	v_mfma_f32_16x16x32_bf16 v[32:35], v[152:155], v[168:171], v[32:35]
	v_mfma_f32_16x16x32_bf16 v[20:23], v[144:147], v[176:179], v[20:23]
	v_mfma_f32_16x16x32_bf16 v[16:19], v[152:155], v[176:179], v[16:19]
	v_mfma_f32_16x16x32_bf16 v[4:7], v[144:147], v[184:187], v[4:7]
	v_mfma_f32_16x16x32_bf16 v[0:3], v[152:155], v[184:187], v[0:3]
	v_mfma_f32_16x16x32_bf16 v[52:55], v[148:151], v[164:167], v[52:55]
	v_mfma_f32_16x16x32_bf16 v[48:51], v[156:159], v[164:167], v[48:51]
	v_mfma_f32_16x16x32_bf16 v[36:39], v[148:151], v[172:175], v[36:39]
	v_mfma_f32_16x16x32_bf16 v[32:35], v[156:159], v[172:175], v[32:35]
	v_mfma_f32_16x16x32_bf16 v[20:23], v[148:151], v[180:183], v[20:23]
	v_mfma_f32_16x16x32_bf16 v[16:19], v[156:159], v[180:183], v[16:19]
	v_mfma_f32_16x16x32_bf16 v[4:7], v[148:151], v[188:191], v[4:7]
	v_mfma_f32_16x16x32_bf16 v[0:3], v[156:159], v[188:191], v[0:3]
	s_setprio 0
	s_barrier
	s_add_i32 s70, 0, 0x18000
	s_add_i32 s71, 0, 0x1c000
	v_add_u32_e32 v140, s70, v242
	v_add_u32_e32 v156, s71, v242
	ds_read_b128 v[128:131], v140
	ds_read_b128 v[132:135], v140 offset:1024
	ds_read_b128 v[136:139], v140 offset:2048
	ds_read_b128 v[140:143], v140 offset:3072
	ds_read_b128 v[144:147], v156
	ds_read_b128 v[148:151], v156 offset:1024
	ds_read_b128 v[152:155], v156 offset:2048
	ds_read_b128 v[156:159], v156 offset:3072
	s_add_u32 s12, s56, 0x40000
	s_addc_u32 s13, s57, 0
	s_mov_b32 m0, s62
	v_lshl_add_u64 v[214:215], s[12:13], 0, v[198:199]
	ds_read_b128 v[160:163], v244 offset:32768
	ds_read_b128 v[164:167], v244 offset:33792
	ds_read_b128 v[168:171], v244 offset:34816
	ds_read_b128 v[172:175], v244 offset:35840
	ds_read_b128 v[176:179], v244 offset:36864
	ds_read_b128 v[180:183], v244 offset:37888
	ds_read_b128 v[184:187], v244 offset:38912
	ds_read_b128 v[188:191], v244 offset:39936
	global_load_lds_dwordx4 v[214:215], off
	v_lshl_add_u64 v[214:215], s[12:13], 0, v[202:203]
	s_mov_b32 m0, s63
	s_nop 0
	global_load_lds_dwordx4 v[214:215], off
	s_waitcnt vmcnt(8)
	s_waitcnt lgkmcnt(0)
	s_barrier
	s_setprio 1
	s_waitcnt lgkmcnt(0)
	v_mfma_f32_16x16x32_bf16 v[124:127], v[128:131], v[160:163], v[124:127]
	v_mfma_f32_16x16x32_bf16 v[120:123], v[136:139], v[160:163], v[120:123]
	v_mfma_f32_16x16x32_bf16 v[108:111], v[128:131], v[168:171], v[108:111]
	v_mfma_f32_16x16x32_bf16 v[104:107], v[136:139], v[168:171], v[104:107]
	v_mfma_f32_16x16x32_bf16 v[92:95], v[128:131], v[176:179], v[92:95]
	v_mfma_f32_16x16x32_bf16 v[88:91], v[136:139], v[176:179], v[88:91]
	v_mfma_f32_16x16x32_bf16 v[76:79], v[128:131], v[184:187], v[76:79]
	v_mfma_f32_16x16x32_bf16 v[72:75], v[136:139], v[184:187], v[72:75]
	v_mfma_f32_16x16x32_bf16 v[124:127], v[132:135], v[164:167], v[124:127]
	v_mfma_f32_16x16x32_bf16 v[120:123], v[140:143], v[164:167], v[120:123]
	v_mfma_f32_16x16x32_bf16 v[108:111], v[132:135], v[172:175], v[108:111]
	v_mfma_f32_16x16x32_bf16 v[104:107], v[140:143], v[172:175], v[104:107]
	v_mfma_f32_16x16x32_bf16 v[92:95], v[132:135], v[180:183], v[92:95]
	v_mfma_f32_16x16x32_bf16 v[88:91], v[140:143], v[180:183], v[88:91]
	v_mfma_f32_16x16x32_bf16 v[76:79], v[132:135], v[188:191], v[76:79]
	v_mfma_f32_16x16x32_bf16 v[72:75], v[140:143], v[188:191], v[72:75]
	v_mfma_f32_16x16x32_bf16 v[116:119], v[144:147], v[160:163], v[116:119]
	v_mfma_f32_16x16x32_bf16 v[112:115], v[152:155], v[160:163], v[112:115]
	v_mfma_f32_16x16x32_bf16 v[100:103], v[144:147], v[168:171], v[100:103]
	v_mfma_f32_16x16x32_bf16 v[96:99], v[152:155], v[168:171], v[96:99]
	v_mfma_f32_16x16x32_bf16 v[84:87], v[144:147], v[176:179], v[84:87]
	v_mfma_f32_16x16x32_bf16 v[80:83], v[152:155], v[176:179], v[80:83]
	v_mfma_f32_16x16x32_bf16 v[68:71], v[144:147], v[184:187], v[68:71]
	v_mfma_f32_16x16x32_bf16 v[64:67], v[152:155], v[184:187], v[64:67]
	v_mfma_f32_16x16x32_bf16 v[116:119], v[148:151], v[164:167], v[116:119]
	v_mfma_f32_16x16x32_bf16 v[112:115], v[156:159], v[164:167], v[112:115]
	v_mfma_f32_16x16x32_bf16 v[100:103], v[148:151], v[172:175], v[100:103]
	v_mfma_f32_16x16x32_bf16 v[96:99], v[156:159], v[172:175], v[96:99]
	v_mfma_f32_16x16x32_bf16 v[84:87], v[148:151], v[180:183], v[84:87]
	v_mfma_f32_16x16x32_bf16 v[80:83], v[156:159], v[180:183], v[80:83]
	v_mfma_f32_16x16x32_bf16 v[68:71], v[148:151], v[188:191], v[68:71]
	v_mfma_f32_16x16x32_bf16 v[64:67], v[156:159], v[188:191], v[64:67]
	s_setprio 0
	s_barrier
; #define PG8_STAGE(bufoff, gbase, voff) do { _Pragma("unroll") for (int _i = 0; _i < 2; ++_i) \
;         __builtin_amdgcn_global_load_lds((const unsigned*)((const char*)(gbase) + (voff)[_i]), (PG8_LAS unsigned*)(lds + (bufoff) + ldsw + _i * 8192), 16, 0, 0); } while (0)
; #define PG8_LDA(dst, b, h) do { _Pragma("unroll") for (int m = 0; m < 4; ++m) _Pragma("unroll") for (int k = 0; k < 2; ++k) dst[m][k] = *(const PG8_LAS bf16x8*)(lds + PG8_SA(b, h) + aoff + m * 2048 + k * 1024); } while (0)
; #define PG8_MMA(ai, bj, At, Bt) do { __builtin_amdgcn_s_setprio(1); _Pragma("unroll") for (int m = 0; m < 4; ++m) _Pragma("unroll") for (int n = 0; n < 2; ++n) _Pragma("unroll") for (int k = 0; k < 2; ++k) \
;         acc[ai][bj][m][n] = __builtin_amdgcn_mfma_f32_16x16x32_bf16(Bt[n][k], At[m][k], acc[ai][bj][m][n], 0, 0, 0); __builtin_amdgcn_s_setprio(0); } while (0)
; #define PG8_WAIT_V(n) asm volatile("s_waitcnt vmcnt(" #n ")" ::: "memory")
; #define PG8_WAIT_L(n) asm volatile("s_waitcnt lgkmcnt(" #n ")" ::: "memory")
; #define PG8_BAR __builtin_amdgcn_s_barrier()
; #define PG8_SCHED __builtin_amdgcn_sched_barrier(0)
; template <class Epi, class Sched, bool ALIGN_EPI = false, bool SP2 = false>
; __device__ __forceinline__ void gemm_phase(PG8_LAS unsigned char* lds, const Gemm g, const Sched& S, const Epi& E, const int tid_in) {
;     ...
;             PG8_LDA(At, 1, 1); PG8_STAGE(PG8_SB(1, 0), b3, voffB); PG8_STAGE(PG8_SB(1, 1), b3 + hstepB, voffB); PG8_STAGE(PG8_SA(1, 0), a3, voffA);
;             PG8_WAIT_V(8); PG8_WAIT_L(0); PG8_BAR; PG8_MMA(1, 0, At, B0); PG8_MMA(1, 1, At, B1); PG8_BAR; PG8_SCHED;
;     ...
;         if constexpr (ALIGN_EPI) { if (wr == 0) PG8_BAR; }
	s_add_i32 s12, s70, s59
	v_lshl_add_u64 v[194:195], v[194:195], 0, s[26:27]
	s_mov_b32 m0, s12
	ds_read_b128 v[160:163], v244 offset:49152
	ds_read_b128 v[164:167], v244 offset:50176
	ds_read_b128 v[168:171], v244 offset:51200
	ds_read_b128 v[172:175], v244 offset:52224
	ds_read_b128 v[176:179], v244 offset:53248
	ds_read_b128 v[180:183], v244 offset:54272
	ds_read_b128 v[184:187], v244 offset:55296
	ds_read_b128 v[188:191], v244 offset:56320
	global_load_lds_dwordx4 v[194:195], off
	s_add_i32 m0, s12, 0x2000
	s_add_u32 s12, s54, 0x20080
	v_lshl_add_u64 v[194:195], v[196:197], 0, s[26:27]
	s_addc_u32 s13, s55, 0
	s_add_i32 s54, s71, s59
	global_load_lds_dwordx4 v[194:195], off
	v_lshl_add_u64 v[194:195], s[12:13], 0, v[200:201]
	s_mov_b32 m0, s54
	s_nop 0
	global_load_lds_dwordx4 v[194:195], off
	v_lshl_add_u64 v[194:195], s[12:13], 0, v[204:205]
	s_add_i32 m0, s54, 0x2000
	s_nop 0
	global_load_lds_dwordx4 v[194:195], off
	v_lshl_add_u64 v[194:195], v[210:211], 0, s[26:27]
	s_mov_b32 m0, s64
	s_nop 0
	global_load_lds_dwordx4 v[194:195], off
	v_lshl_add_u64 v[194:195], v[212:213], 0, s[26:27]
	s_mov_b32 m0, s65
	s_nop 0
	global_load_lds_dwordx4 v[194:195], off
	s_waitcnt vmcnt(8)
	s_waitcnt lgkmcnt(0)
	s_barrier
	s_setprio 1
	s_waitcnt lgkmcnt(0)
	v_mfma_f32_16x16x32_bf16 v[60:63], v[128:131], v[160:163], v[60:63]
	v_mfma_f32_16x16x32_bf16 v[56:59], v[136:139], v[160:163], v[56:59]
	v_mfma_f32_16x16x32_bf16 v[44:47], v[128:131], v[168:171], v[44:47]
	v_mfma_f32_16x16x32_bf16 v[40:43], v[136:139], v[168:171], v[40:43]
	v_mfma_f32_16x16x32_bf16 v[28:31], v[128:131], v[176:179], v[28:31]
	v_mfma_f32_16x16x32_bf16 v[24:27], v[136:139], v[176:179], v[24:27]
	v_mfma_f32_16x16x32_bf16 v[12:15], v[128:131], v[184:187], v[12:15]
	v_mfma_f32_16x16x32_bf16 v[8:11], v[136:139], v[184:187], v[8:11]
	v_mfma_f32_16x16x32_bf16 v[60:63], v[132:135], v[164:167], v[60:63]
	v_mfma_f32_16x16x32_bf16 v[56:59], v[140:143], v[164:167], v[56:59]
	v_mfma_f32_16x16x32_bf16 v[44:47], v[132:135], v[172:175], v[44:47]
	v_mfma_f32_16x16x32_bf16 v[40:43], v[140:143], v[172:175], v[40:43]
	v_mfma_f32_16x16x32_bf16 v[28:31], v[132:135], v[180:183], v[28:31]
	v_mfma_f32_16x16x32_bf16 v[24:27], v[140:143], v[180:183], v[24:27]
	v_mfma_f32_16x16x32_bf16 v[12:15], v[132:135], v[188:191], v[12:15]
	v_mfma_f32_16x16x32_bf16 v[8:11], v[140:143], v[188:191], v[8:11]
	v_mfma_f32_16x16x32_bf16 v[52:55], v[144:147], v[160:163], v[52:55]
	v_mfma_f32_16x16x32_bf16 v[48:51], v[152:155], v[160:163], v[48:51]
	v_mfma_f32_16x16x32_bf16 v[36:39], v[144:147], v[168:171], v[36:39]
	v_mfma_f32_16x16x32_bf16 v[32:35], v[152:155], v[168:171], v[32:35]
	v_mfma_f32_16x16x32_bf16 v[20:23], v[144:147], v[176:179], v[20:23]
	v_mfma_f32_16x16x32_bf16 v[16:19], v[152:155], v[176:179], v[16:19]
	v_mfma_f32_16x16x32_bf16 v[4:7], v[144:147], v[184:187], v[4:7]
	v_mfma_f32_16x16x32_bf16 v[0:3], v[152:155], v[184:187], v[0:3]
	v_mfma_f32_16x16x32_bf16 v[52:55], v[148:151], v[164:167], v[52:55]
	v_mfma_f32_16x16x32_bf16 v[48:51], v[156:159], v[164:167], v[48:51]
	v_mfma_f32_16x16x32_bf16 v[36:39], v[148:151], v[172:175], v[36:39]
	v_mfma_f32_16x16x32_bf16 v[32:35], v[156:159], v[172:175], v[32:35]
	v_mfma_f32_16x16x32_bf16 v[20:23], v[148:151], v[180:183], v[20:23]
	v_mfma_f32_16x16x32_bf16 v[16:19], v[156:159], v[180:183], v[16:19]
	v_mfma_f32_16x16x32_bf16 v[4:7], v[148:151], v[188:191], v[4:7]
	v_mfma_f32_16x16x32_bf16 v[0:3], v[156:159], v[188:191], v[0:3]
	s_setprio 0
	s_barrier
	s_add_i32 s69, s69, 2
	s_add_u32 s52, s52, 0x100
	s_addc_u32 s53, s53, 0
	s_add_u32 s67, s67, 0x100
	s_addc_u32 s68, s68, 0
	s_cmp_gt_u32 s69, 5
	s_cbranch_scc0 .LBB0_427
	s_andn2_b64 vcc, s[42:43], s[34:35]
	s_cbranch_vccz .LBB0_430
	s_barrier

; __device__ __forceinline__ unsigned cvt_pk_bf16(float lo, float hi) { unsigned r; asm volatile("v_cvt_pk_bf16_f32 %0, %1, %2" : "=v"(r) : "v"(lo), "v"(hi)); return r; }
; #define PG8_BAR __builtin_amdgcn_s_barrier()
;     __device__ __forceinline__ void operator()(const f32x4 (&acc)[2][2][4][2], const Unit& u, int wr, int wc, int fr, int fq) const {
;     ...
;                     u32x4 w; w.x = cvt_pk_bf16(v0[0], v0[1]); w.y = cvt_pk_bf16(v0[2], v0[3]); w.z = cvt_pk_bf16(v1[0], v1[1]); w.w = cvt_pk_bf16(v1[2], v1[3]);
;                     *(u32x4*)(Q + (size_t)row * 3072 + col) = w; } } }
; template <class Epi, class Sched, bool ALIGN_EPI = false, bool SP2 = false>
; __device__ __forceinline__ void gemm_phase(PG8_LAS unsigned char* lds, const Gemm g, const Sched& S, const Epi& E, const int tid_in) {
;     ...
;         if (!has_next) break;
; #pragma unroll
;         for (int a = 0; a < 2; ++a)
; #pragma unroll
;             for (int b = 0; b < 2; ++b)
; #pragma unroll
;                 for (int m = 0; m < 4; ++m)
; #pragma unroll
;                     for (int n = 0; n < 2; ++n) acc[a][b][m][n] = (f32x4){0.f, 0.f, 0.f, 0.f};
;         cur = nxt; cA = nA; cB = nB; ++ui;
;         if constexpr (ALIGN_EPI) { if (wr == 1) PG8_BAR; }
.LBB0_526:
	s_or_b64 exec, exec, s[0:1]
	s_andn2_b64 vcc, exec, s[34:35]
	s_mov_b64 s[0:1], -1
	v_cvt_pk_bf16_f32 v4, v4, v5
	v_cvt_pk_bf16_f32 v5, v6, v7
	v_cvt_pk_bf16_f32 v6, v0, v1
	v_cvt_pk_bf16_f32 v7, v2, v3
	global_store_dwordx4 v[8:9], v[4:7], off offset:256
	s_cbranch_vccnz .LBB0_423
	s_andn2_b64 vcc, exec, s[22:23]
	s_cbranch_vccnz .LBB0_422
	s_branch .LBB0_422

; #define PG8_STAGE(bufoff, gbase, voff) do { _Pragma("unroll") for (int _i = 0; _i < 2; ++_i) \
;         __builtin_amdgcn_global_load_lds((const unsigned*)((const char*)(gbase) + (voff)[_i]), (PG8_LAS unsigned*)(lds + (bufoff) + ldsw + _i * 8192), 16, 0, 0); } while (0)
; #define PG8_LDA(dst, b, h) do { _Pragma("unroll") for (int m = 0; m < 4; ++m) _Pragma("unroll") for (int k = 0; k < 2; ++k) dst[m][k] = *(const PG8_LAS bf16x8*)(lds + PG8_SA(b, h) + aoff + m * 2048 + k * 1024); } while (0)
; #define PG8_LDB(dst, b, h) do { _Pragma("unroll") for (int n = 0; n < 2; ++n) _Pragma("unroll") for (int k = 0; k < 2; ++k) dst[n][k] = *(const PG8_LAS bf16x8*)(lds + PG8_SB(b, h) + boff + n * 2048 + k * 1024); } while (0)
; #define PG8_MMA(ai, bj, At, Bt) do { __builtin_amdgcn_s_setprio(1); _Pragma("unroll") for (int m = 0; m < 4; ++m) _Pragma("unroll") for (int n = 0; n < 2; ++n) _Pragma("unroll") for (int k = 0; k < 2; ++k) \
;         acc[ai][bj][m][n] = __builtin_amdgcn_mfma_f32_16x16x32_bf16(Bt[n][k], At[m][k], acc[ai][bj][m][n], 0, 0, 0); __builtin_amdgcn_s_setprio(0); } while (0)
; #define PG8_WAIT_V(n) asm volatile("s_waitcnt vmcnt(" #n ")" ::: "memory")
; #define PG8_WAIT_L(n) asm volatile("s_waitcnt lgkmcnt(" #n ")" ::: "memory")
; #define PG8_BAR __builtin_amdgcn_s_barrier()
; template <class Epi, class Sched, bool ALIGN_EPI = false, bool SP2 = false>
; __device__ __forceinline__ void gemm_phase(PG8_LAS unsigned char* lds, const Gemm g, const Sched& S, const Epi& E, const int tid_in) {
;     ...
;         for (int t = 0; t < nt; t += 2) {
;             const bool last = (t == nt - 2);
;             const char* a1 = cA + (size_t)(t + 1) * kstep;
;             const char* a2 = last ? nA : cA + (size_t)(t + 2) * kstep; const char* b2 = last ? nB : cB + (size_t)(t + 2) * kstep;
;             const char* a3 = a2 + kstep; const char* b3 = b2 + kstep;
;             if (last && has_next) S.a_ready(nxt);
;             if constexpr (SP2) {
;             PG8_LDB(B0, 0, 0); PG8_LDB(B1, 0, 1); PG8_SCHED; PG8_LDA(At, 0, 0); PG8_STAGE(PG8_SA(1, 1), a1 + hstepA, voffA);
;             PG8_WAIT_V(8); PG8_WAIT_L(0); PG8_BAR; PG8_MMA(0, 0, At, B0); PG8_MMA(0, 1, At, B1); PG8_BAR; PG8_SCHED;
;             PG8_LDA(At, 0, 1); PG8_STAGE(PG8_SB(0, 0), b2, voffB); PG8_STAGE(PG8_SB(0, 1), b2 + hstepB, voffB); PG8_STAGE(PG8_SA(0, 0), a2, voffA);
.LBB0_539:
	s_add_u32 s12, s42, 0xfffc0080
	s_addc_u32 s13, s43, -1
	s_add_i32 s68, 0, 0x10000
	s_cmp_eq_u32 s67, 4
	s_cselect_b32 s47, s37, s13
	s_cselect_b32 s46, s63, s12
	v_add_u32_e32 v130, s68, v133
	s_cselect_b32 s45, s31, s66
	s_cselect_b32 s44, s64, s65
	s_add_i32 s69, 0, 0x14000
	ds_read_b128 v[136:139], v130
	ds_read_b128 v[140:143], v130 offset:1024
	ds_read_b128 v[144:147], v130 offset:2048
	ds_read_b128 v[148:151], v130 offset:3072
	v_add_u32_e32 v130, s69, v133
	ds_read_b128 v[152:155], v130
	ds_read_b128 v[156:159], v130 offset:1024
	ds_read_b128 v[160:163], v130 offset:2048
	ds_read_b128 v[164:167], v130 offset:3072
	v_lshl_add_u64 v[130:131], s[42:43], 0, v[192:193]
	s_add_i32 m0, s52, 0xc000
	ds_read_b128 v[168:171], v135
	ds_read_b128 v[172:175], v135 offset:1024
	ds_read_b128 v[176:179], v135 offset:2048
	ds_read_b128 v[180:183], v135 offset:3072
	ds_read_b128 v[184:187], v135 offset:4096
	ds_read_b128 v[188:191], v135 offset:5120
	ds_read_b128 v[194:197], v135 offset:6144
	ds_read_b128 v[206:209], v135 offset:7168
	global_load_lds_dwordx4 v[130:131], off
	v_lshl_add_u64 v[130:131], s[42:43], 0, v[128:129]
	s_add_i32 m0, s52, 0xe000
	s_nop 0
	global_load_lds_dwordx4 v[130:131], off
	s_waitcnt vmcnt(8)
	s_waitcnt lgkmcnt(0)
	s_barrier
	s_setprio 1
	s_waitcnt lgkmcnt(0)
	v_mfma_f32_16x16x32_bf16 v[124:127], v[136:139], v[168:171], v[124:127]
	v_mfma_f32_16x16x32_bf16 v[120:123], v[144:147], v[168:171], v[120:123]
	v_mfma_f32_16x16x32_bf16 v[116:119], v[136:139], v[176:179], v[116:119]
	v_mfma_f32_16x16x32_bf16 v[108:111], v[144:147], v[176:179], v[108:111]
	v_mfma_f32_16x16x32_bf16 v[100:103], v[136:139], v[184:187], v[100:103]
	v_mfma_f32_16x16x32_bf16 v[92:95], v[144:147], v[184:187], v[92:95]
	v_mfma_f32_16x16x32_bf16 v[84:87], v[136:139], v[194:197], v[84:87]
	v_mfma_f32_16x16x32_bf16 v[76:79], v[144:147], v[194:197], v[76:79]
	v_mfma_f32_16x16x32_bf16 v[124:127], v[140:143], v[172:175], v[124:127]
	v_mfma_f32_16x16x32_bf16 v[120:123], v[148:151], v[172:175], v[120:123]
	v_mfma_f32_16x16x32_bf16 v[116:119], v[140:143], v[180:183], v[116:119]
	v_mfma_f32_16x16x32_bf16 v[108:111], v[148:151], v[180:183], v[108:111]
	v_mfma_f32_16x16x32_bf16 v[100:103], v[140:143], v[188:191], v[100:103]
	v_mfma_f32_16x16x32_bf16 v[92:95], v[148:151], v[188:191], v[92:95]
	v_mfma_f32_16x16x32_bf16 v[84:87], v[140:143], v[206:209], v[84:87]
	v_mfma_f32_16x16x32_bf16 v[76:79], v[148:151], v[206:209], v[76:79]
	v_mfma_f32_16x16x32_bf16 v[112:115], v[152:155], v[168:171], v[112:115]
	v_mfma_f32_16x16x32_bf16 v[104:107], v[160:163], v[168:171], v[104:107]
	v_mfma_f32_16x16x32_bf16 v[96:99], v[152:155], v[176:179], v[96:99]
	v_mfma_f32_16x16x32_bf16 v[88:91], v[160:163], v[176:179], v[88:91]
	v_mfma_f32_16x16x32_bf16 v[80:83], v[152:155], v[184:187], v[80:83]
	v_mfma_f32_16x16x32_bf16 v[72:75], v[160:163], v[184:187], v[72:75]
	v_mfma_f32_16x16x32_bf16 v[68:71], v[152:155], v[194:197], v[68:71]
	v_mfma_f32_16x16x32_bf16 v[64:67], v[160:163], v[194:197], v[64:67]
	v_mfma_f32_16x16x32_bf16 v[112:115], v[156:159], v[172:175], v[112:115]
	v_mfma_f32_16x16x32_bf16 v[104:107], v[164:167], v[172:175], v[104:107]
	v_mfma_f32_16x16x32_bf16 v[96:99], v[156:159], v[180:183], v[96:99]
	v_mfma_f32_16x16x32_bf16 v[88:91], v[164:167], v[180:183], v[88:91]
	v_mfma_f32_16x16x32_bf16 v[80:83], v[156:159], v[188:191], v[80:83]
	v_mfma_f32_16x16x32_bf16 v[72:75], v[164:167], v[188:191], v[72:75]
	v_mfma_f32_16x16x32_bf16 v[68:71], v[156:159], v[206:209], v[68:71]
	v_mfma_f32_16x16x32_bf16 v[64:67], v[164:167], v[206:209], v[64:67]
	s_setprio 0
	s_barrier
	s_add_i32 s12, s68, s51
	v_lshl_add_u64 v[130:131], s[44:45], 0, v[200:201]
	s_mov_b32 m0, s12
	ds_read_b128 v[168:171], v135 offset:16384
	ds_read_b128 v[172:175], v135 offset:17408
	ds_read_b128 v[176:179], v135 offset:18432
	ds_read_b128 v[180:183], v135 offset:19456
	ds_read_b128 v[184:187], v135 offset:20480
	ds_read_b128 v[188:191], v135 offset:21504
	ds_read_b128 v[194:197], v135 offset:22528
	ds_read_b128 v[206:209], v135 offset:23552
	global_load_lds_dwordx4 v[130:131], off
	s_add_i32 m0, s12, 0x2000
	s_add_u32 s12, s44, 0x20000
	v_lshl_add_u64 v[210:211], s[44:45], 0, v[204:205]
	s_addc_u32 s13, s45, 0
	s_add_i32 s68, s69, s51
	global_load_lds_dwordx4 v[210:211], off
	v_lshl_add_u64 v[212:213], s[12:13], 0, v[200:201]
	s_mov_b32 m0, s68
	v_lshl_add_u64 v[214:215], s[46:47], 0, v[202:203]
	global_load_lds_dwordx4 v[212:213], off
	v_lshl_add_u64 v[212:213], s[12:13], 0, v[204:205]
	s_add_i32 m0, s68, 0x2000
	s_nop 0
	global_load_lds_dwordx4 v[212:213], off
	v_lshl_add_u64 v[212:213], s[46:47], 0, v[198:199]
	s_mov_b32 m0, s52
	s_nop 0
	global_load_lds_dwordx4 v[212:213], off
	s_mov_b32 m0, s53
	s_nop 0
	global_load_lds_dwordx4 v[214:215], off
	s_waitcnt vmcnt(8)
	s_waitcnt lgkmcnt(0)
	s_barrier
; #define PG8_STAGE(bufoff, gbase, voff) do { _Pragma("unroll") for (int _i = 0; _i < 2; ++_i) \
;         __builtin_amdgcn_global_load_lds((const unsigned*)((const char*)(gbase) + (voff)[_i]), (PG8_LAS unsigned*)(lds + (bufoff) + ldsw + _i * 8192), 16, 0, 0); } while (0)
; #define PG8_LDA(dst, b, h) do { _Pragma("unroll") for (int m = 0; m < 4; ++m) _Pragma("unroll") for (int k = 0; k < 2; ++k) dst[m][k] = *(const PG8_LAS bf16x8*)(lds + PG8_SA(b, h) + aoff + m * 2048 + k * 1024); } while (0)
; #define PG8_LDB(dst, b, h) do { _Pragma("unroll") for (int n = 0; n < 2; ++n) _Pragma("unroll") for (int k = 0; k < 2; ++k) dst[n][k] = *(const PG8_LAS bf16x8*)(lds + PG8_SB(b, h) + boff + n * 2048 + k * 1024); } while (0)
; #define PG8_MMA(ai, bj, At, Bt) do { __builtin_amdgcn_s_setprio(1); _Pragma("unroll") for (int m = 0; m < 4; ++m) _Pragma("unroll") for (int n = 0; n < 2; ++n) _Pragma("unroll") for (int k = 0; k < 2; ++k) \
;         acc[ai][bj][m][n] = __builtin_amdgcn_mfma_f32_16x16x32_bf16(Bt[n][k], At[m][k], acc[ai][bj][m][n], 0, 0, 0); __builtin_amdgcn_s_setprio(0); } while (0)
; #define PG8_WAIT_V(n) asm volatile("s_waitcnt vmcnt(" #n ")" ::: "memory")
; #define PG8_WAIT_L(n) asm volatile("s_waitcnt lgkmcnt(" #n ")" ::: "memory")
; #define PG8_BAR __builtin_amdgcn_s_barrier()
; #define PG8_SCHED __builtin_amdgcn_sched_barrier(0)
; template <class Epi, class Sched, bool ALIGN_EPI = false, bool SP2 = false>
; __device__ __forceinline__ void gemm_phase(PG8_LAS unsigned char* lds, const Gemm g, const Sched& S, const Epi& E, const int tid_in) {
;     ...
;             PG8_WAIT_V(8); PG8_WAIT_L(0); PG8_BAR; PG8_MMA(1, 0, At, B0); PG8_MMA(1, 1, At, B1); PG8_BAR; PG8_SCHED;
;             PG8_LDB(B0, 1, 0); PG8_LDB(B1, 1, 1); PG8_SCHED; PG8_LDA(At, 1, 0); PG8_STAGE(PG8_SA(0, 1), a2 + hstepA, voffA);
;             PG8_WAIT_V(8); PG8_WAIT_L(0); PG8_BAR; PG8_MMA(0, 0, At, B0); PG8_MMA(0, 1, At, B1); PG8_BAR; PG8_SCHED;
	s_setprio 1
	s_waitcnt lgkmcnt(0)
	v_mfma_f32_16x16x32_bf16 v[60:63], v[136:139], v[168:171], v[60:63]
	v_mfma_f32_16x16x32_bf16 v[56:59], v[144:147], v[168:171], v[56:59]
	v_mfma_f32_16x16x32_bf16 v[52:55], v[136:139], v[176:179], v[52:55]
	v_mfma_f32_16x16x32_bf16 v[44:47], v[144:147], v[176:179], v[44:47]
	v_mfma_f32_16x16x32_bf16 v[36:39], v[136:139], v[184:187], v[36:39]
	v_mfma_f32_16x16x32_bf16 v[28:31], v[144:147], v[184:187], v[28:31]
	v_mfma_f32_16x16x32_bf16 v[20:23], v[136:139], v[194:197], v[20:23]
	v_mfma_f32_16x16x32_bf16 v[12:15], v[144:147], v[194:197], v[12:15]
	v_mfma_f32_16x16x32_bf16 v[60:63], v[140:143], v[172:175], v[60:63]
	v_mfma_f32_16x16x32_bf16 v[56:59], v[148:151], v[172:175], v[56:59]
	v_mfma_f32_16x16x32_bf16 v[52:55], v[140:143], v[180:183], v[52:55]
	v_mfma_f32_16x16x32_bf16 v[44:47], v[148:151], v[180:183], v[44:47]
	v_mfma_f32_16x16x32_bf16 v[36:39], v[140:143], v[188:191], v[36:39]
	v_mfma_f32_16x16x32_bf16 v[28:31], v[148:151], v[188:191], v[28:31]
	v_mfma_f32_16x16x32_bf16 v[20:23], v[140:143], v[206:209], v[20:23]
	v_mfma_f32_16x16x32_bf16 v[12:15], v[148:151], v[206:209], v[12:15]
	v_mfma_f32_16x16x32_bf16 v[48:51], v[152:155], v[168:171], v[48:51]
	v_mfma_f32_16x16x32_bf16 v[40:43], v[160:163], v[168:171], v[40:43]
	v_mfma_f32_16x16x32_bf16 v[32:35], v[152:155], v[176:179], v[32:35]
	v_mfma_f32_16x16x32_bf16 v[24:27], v[160:163], v[176:179], v[24:27]
	v_mfma_f32_16x16x32_bf16 v[16:19], v[152:155], v[184:187], v[16:19]
	v_mfma_f32_16x16x32_bf16 v[8:11], v[160:163], v[184:187], v[8:11]
	v_mfma_f32_16x16x32_bf16 v[4:7], v[152:155], v[194:197], v[4:7]
	v_mfma_f32_16x16x32_bf16 v[0:3], v[160:163], v[194:197], v[0:3]
	v_mfma_f32_16x16x32_bf16 v[48:51], v[156:159], v[172:175], v[48:51]
	v_mfma_f32_16x16x32_bf16 v[40:43], v[164:167], v[172:175], v[40:43]
	v_mfma_f32_16x16x32_bf16 v[32:35], v[156:159], v[180:183], v[32:35]
	v_mfma_f32_16x16x32_bf16 v[24:27], v[164:167], v[180:183], v[24:27]
	v_mfma_f32_16x16x32_bf16 v[16:19], v[156:159], v[188:191], v[16:19]
	v_mfma_f32_16x16x32_bf16 v[8:11], v[164:167], v[188:191], v[8:11]
	v_mfma_f32_16x16x32_bf16 v[4:7], v[156:159], v[206:209], v[4:7]
	v_mfma_f32_16x16x32_bf16 v[0:3], v[164:167], v[206:209], v[0:3]
	s_setprio 0
	s_barrier
	s_add_i32 s68, 0, 0x18000
	s_add_i32 s69, 0, 0x1c000
	v_add_u32_e32 v148, s68, v133
	v_add_u32_e32 v164, s69, v133
	ds_read_b128 v[136:139], v148
	ds_read_b128 v[140:143], v148 offset:1024
	ds_read_b128 v[144:147], v148 offset:2048
	ds_read_b128 v[148:151], v148 offset:3072
	ds_read_b128 v[152:155], v164
	ds_read_b128 v[156:159], v164 offset:1024
	ds_read_b128 v[160:163], v164 offset:2048
	ds_read_b128 v[164:167], v164 offset:3072
	s_add_u32 s12, s46, 0x40000
	s_addc_u32 s13, s47, 0
	s_mov_b32 m0, s54
	v_lshl_add_u64 v[216:217], s[12:13], 0, v[198:199]
	ds_read_b128 v[168:171], v135 offset:32768
	ds_read_b128 v[172:175], v135 offset:33792
	ds_read_b128 v[176:179], v135 offset:34816
	ds_read_b128 v[180:183], v135 offset:35840
	ds_read_b128 v[184:187], v135 offset:36864
	ds_read_b128 v[188:191], v135 offset:37888
	ds_read_b128 v[194:197], v135 offset:38912
	ds_read_b128 v[206:209], v135 offset:39936
	global_load_lds_dwordx4 v[216:217], off
	v_lshl_add_u64 v[216:217], s[12:13], 0, v[202:203]
	s_mov_b32 m0, s55
	s_nop 0
	global_load_lds_dwordx4 v[216:217], off
	s_waitcnt vmcnt(8)
	s_waitcnt lgkmcnt(0)
	s_barrier
	s_setprio 1
	s_waitcnt lgkmcnt(0)
	v_mfma_f32_16x16x32_bf16 v[124:127], v[136:139], v[168:171], v[124:127]
	v_mfma_f32_16x16x32_bf16 v[120:123], v[144:147], v[168:171], v[120:123]
	v_mfma_f32_16x16x32_bf16 v[116:119], v[136:139], v[176:179], v[116:119]
	v_mfma_f32_16x16x32_bf16 v[108:111], v[144:147], v[176:179], v[108:111]
	v_mfma_f32_16x16x32_bf16 v[100:103], v[136:139], v[184:187], v[100:103]
	v_mfma_f32_16x16x32_bf16 v[92:95], v[144:147], v[184:187], v[92:95]
	v_mfma_f32_16x16x32_bf16 v[84:87], v[136:139], v[194:197], v[84:87]
	v_mfma_f32_16x16x32_bf16 v[76:79], v[144:147], v[194:197], v[76:79]
	v_mfma_f32_16x16x32_bf16 v[124:127], v[140:143], v[172:175], v[124:127]
	v_mfma_f32_16x16x32_bf16 v[120:123], v[148:151], v[172:175], v[120:123]
	v_mfma_f32_16x16x32_bf16 v[116:119], v[140:143], v[180:183], v[116:119]
	v_mfma_f32_16x16x32_bf16 v[108:111], v[148:151], v[180:183], v[108:111]
	v_mfma_f32_16x16x32_bf16 v[100:103], v[140:143], v[188:191], v[100:103]
	v_mfma_f32_16x16x32_bf16 v[92:95], v[148:151], v[188:191], v[92:95]
	v_mfma_f32_16x16x32_bf16 v[84:87], v[140:143], v[206:209], v[84:87]
	v_mfma_f32_16x16x32_bf16 v[76:79], v[148:151], v[206:209], v[76:79]
	v_mfma_f32_16x16x32_bf16 v[112:115], v[152:155], v[168:171], v[112:115]
	v_mfma_f32_16x16x32_bf16 v[104:107], v[160:163], v[168:171], v[104:107]
	v_mfma_f32_16x16x32_bf16 v[96:99], v[152:155], v[176:179], v[96:99]
	v_mfma_f32_16x16x32_bf16 v[88:91], v[160:163], v[176:179], v[88:91]
	v_mfma_f32_16x16x32_bf16 v[80:83], v[152:155], v[184:187], v[80:83]
	v_mfma_f32_16x16x32_bf16 v[72:75], v[160:163], v[184:187], v[72:75]
	v_mfma_f32_16x16x32_bf16 v[68:71], v[152:155], v[194:197], v[68:71]
	v_mfma_f32_16x16x32_bf16 v[64:67], v[160:163], v[194:197], v[64:67]
	v_mfma_f32_16x16x32_bf16 v[112:115], v[156:159], v[172:175], v[112:115]
	v_mfma_f32_16x16x32_bf16 v[104:107], v[164:167], v[172:175], v[104:107]
	v_mfma_f32_16x16x32_bf16 v[96:99], v[156:159], v[180:183], v[96:99]
	v_mfma_f32_16x16x32_bf16 v[88:91], v[164:167], v[180:183], v[88:91]
	v_mfma_f32_16x16x32_bf16 v[80:83], v[156:159], v[188:191], v[80:83]
	v_mfma_f32_16x16x32_bf16 v[72:75], v[164:167], v[188:191], v[72:75]
	v_mfma_f32_16x16x32_bf16 v[68:71], v[156:159], v[206:209], v[68:71]
	v_mfma_f32_16x16x32_bf16 v[64:67], v[164:167], v[206:209], v[64:67]
	s_setprio 0
	s_barrier
; #define PG8_STAGE(bufoff, gbase, voff) do { _Pragma("unroll") for (int _i = 0; _i < 2; ++_i) \
;         __builtin_amdgcn_global_load_lds((const unsigned*)((const char*)(gbase) + (voff)[_i]), (PG8_LAS unsigned*)(lds + (bufoff) + ldsw + _i * 8192), 16, 0, 0); } while (0)
; #define PG8_LDA(dst, b, h) do { _Pragma("unroll") for (int m = 0; m < 4; ++m) _Pragma("unroll") for (int k = 0; k < 2; ++k) dst[m][k] = *(const PG8_LAS bf16x8*)(lds + PG8_SA(b, h) + aoff + m * 2048 + k * 1024); } while (0)
; #define PG8_BAR __builtin_amdgcn_s_barrier()
; template <class Epi, class Sched, bool ALIGN_EPI = false, bool SP2 = false>
; __device__ __forceinline__ void gemm_phase(PG8_LAS unsigned char* lds, const Gemm g, const Sched& S, const Epi& E, const int tid_in) {
;     ...
;             PG8_LDA(At, 1, 1); PG8_STAGE(PG8_SB(1, 0), b3, voffB); PG8_STAGE(PG8_SB(1, 1), b3 + hstepB, voffB); PG8_STAGE(PG8_SA(1, 0), a3, voffA);
;             PG8_WAIT_V(8); PG8_WAIT_L(0); PG8_BAR; PG8_MMA(1, 0, At, B0); PG8_MMA(1, 1, At, B1); PG8_BAR; PG8_SCHED;
;             } else {
;             PG8_LDB(B0, 0, 0); PG8_SCHED; PG8_LDA(At, 0, 0); PG8_STAGE(PG8_SA(1, 1), a1 + hstepA, voffA);
;             PG8_WAIT_L(8); PG8_BAR; PG8_WAIT_L(0); PG8_MMA(0, 0, At, B0); PG8_BAR; PG8_SCHED;
;             PG8_LDB(B1, 0, 1); PG8_STAGE(PG8_SB(0, 0), b2, voffB);
;             PG8_BAR; PG8_WAIT_L(0); PG8_MMA(0, 1, At, B1); PG8_BAR;
;             PG8_LDA(At, 0, 1); PG8_STAGE(PG8_SA(0, 0), a2, voffA);
;             PG8_BAR; PG8_WAIT_L(0); PG8_MMA(1, 0, At, B0); PG8_BAR; PG8_SCHED;
;             PG8_STAGE(PG8_SB(0, 1), b2 + hstepB, voffB);
;             PG8_WAIT_V(6); PG8_BAR; PG8_MMA(1, 1, At, B1); PG8_BAR;
;             PG8_LDB(B0, 1, 0); PG8_SCHED; PG8_LDA(At, 1, 0); PG8_STAGE(PG8_SA(0, 1), a2 + hstepA, voffA);
;             PG8_WAIT_L(8); PG8_BAR; PG8_WAIT_L(0); PG8_MMA(0, 0, At, B0); PG8_BAR; PG8_SCHED;
;             PG8_LDB(B1, 1, 1); PG8_STAGE(PG8_SB(1, 0), b3, voffB);
;             PG8_BAR; PG8_WAIT_L(0); PG8_MMA(0, 1, At, B1); PG8_BAR;
;             PG8_LDA(At, 1, 1); PG8_STAGE(PG8_SA(1, 0), a3, voffA);
;             PG8_BAR; PG8_WAIT_L(0); PG8_MMA(1, 0, At, B0); PG8_BAR; PG8_SCHED;
;             PG8_STAGE(PG8_SB(1, 1), b3 + hstepB, voffB);
;             PG8_WAIT_V(6); PG8_BAR; PG8_MMA(1, 1, At, B1); PG8_BAR;
;             }
;         }
;         if constexpr (ALIGN_EPI) { if (wr == 0) PG8_BAR; }
	s_add_i32 s12, s68, s51
	v_lshl_add_u64 v[130:131], v[130:131], 0, s[26:27]
	s_mov_b32 m0, s12
	ds_read_b128 v[168:171], v135 offset:49152
	ds_read_b128 v[172:175], v135 offset:50176
	ds_read_b128 v[176:179], v135 offset:51200
	ds_read_b128 v[180:183], v135 offset:52224
	ds_read_b128 v[184:187], v135 offset:53248
	ds_read_b128 v[188:191], v135 offset:54272
	ds_read_b128 v[194:197], v135 offset:55296
	ds_read_b128 v[206:209], v135 offset:56320
	global_load_lds_dwordx4 v[130:131], off
	s_add_i32 m0, s12, 0x2000
	s_add_u32 s12, s44, 0x20080
	v_lshl_add_u64 v[130:131], v[210:211], 0, s[26:27]
	s_addc_u32 s13, s45, 0
	s_add_i32 s44, s69, s51
	global_load_lds_dwordx4 v[130:131], off
	v_lshl_add_u64 v[130:131], s[12:13], 0, v[200:201]
	s_mov_b32 m0, s44
	s_nop 0
	global_load_lds_dwordx4 v[130:131], off
	v_lshl_add_u64 v[130:131], s[12:13], 0, v[204:205]
	s_add_i32 m0, s44, 0x2000
	s_nop 0
	global_load_lds_dwordx4 v[130:131], off
	v_lshl_add_u64 v[130:131], v[212:213], 0, s[26:27]
	s_mov_b32 m0, s58
	s_nop 0
	global_load_lds_dwordx4 v[130:131], off
	v_lshl_add_u64 v[130:131], v[214:215], 0, s[26:27]
	s_mov_b32 m0, s59
	s_nop 0
	global_load_lds_dwordx4 v[130:131], off
	s_waitcnt vmcnt(8)
	s_waitcnt lgkmcnt(0)
	s_barrier
	s_setprio 1
	s_waitcnt lgkmcnt(0)
	v_mfma_f32_16x16x32_bf16 v[60:63], v[136:139], v[168:171], v[60:63]
	v_mfma_f32_16x16x32_bf16 v[56:59], v[144:147], v[168:171], v[56:59]
	v_mfma_f32_16x16x32_bf16 v[52:55], v[136:139], v[176:179], v[52:55]
	v_mfma_f32_16x16x32_bf16 v[44:47], v[144:147], v[176:179], v[44:47]
	v_mfma_f32_16x16x32_bf16 v[36:39], v[136:139], v[184:187], v[36:39]
	v_mfma_f32_16x16x32_bf16 v[28:31], v[144:147], v[184:187], v[28:31]
	v_mfma_f32_16x16x32_bf16 v[20:23], v[136:139], v[194:197], v[20:23]
	v_mfma_f32_16x16x32_bf16 v[12:15], v[144:147], v[194:197], v[12:15]
	v_mfma_f32_16x16x32_bf16 v[60:63], v[140:143], v[172:175], v[60:63]
	v_mfma_f32_16x16x32_bf16 v[56:59], v[148:151], v[172:175], v[56:59]
	v_mfma_f32_16x16x32_bf16 v[52:55], v[140:143], v[180:183], v[52:55]
	v_mfma_f32_16x16x32_bf16 v[44:47], v[148:151], v[180:183], v[44:47]
	v_mfma_f32_16x16x32_bf16 v[36:39], v[140:143], v[188:191], v[36:39]
	v_mfma_f32_16x16x32_bf16 v[28:31], v[148:151], v[188:191], v[28:31]
	v_mfma_f32_16x16x32_bf16 v[20:23], v[140:143], v[206:209], v[20:23]
	v_mfma_f32_16x16x32_bf16 v[12:15], v[148:151], v[206:209], v[12:15]
	v_mfma_f32_16x16x32_bf16 v[48:51], v[152:155], v[168:171], v[48:51]
	v_mfma_f32_16x16x32_bf16 v[40:43], v[160:163], v[168:171], v[40:43]
	v_mfma_f32_16x16x32_bf16 v[32:35], v[152:155], v[176:179], v[32:35]
	v_mfma_f32_16x16x32_bf16 v[24:27], v[160:163], v[176:179], v[24:27]
	v_mfma_f32_16x16x32_bf16 v[16:19], v[152:155], v[184:187], v[16:19]
	v_mfma_f32_16x16x32_bf16 v[8:11], v[160:163], v[184:187], v[8:11]
	v_mfma_f32_16x16x32_bf16 v[4:7], v[152:155], v[194:197], v[4:7]
	v_mfma_f32_16x16x32_bf16 v[0:3], v[160:163], v[194:197], v[0:3]
	v_mfma_f32_16x16x32_bf16 v[48:51], v[156:159], v[172:175], v[48:51]
	v_mfma_f32_16x16x32_bf16 v[40:43], v[164:167], v[172:175], v[40:43]
	v_mfma_f32_16x16x32_bf16 v[32:35], v[156:159], v[180:183], v[32:35]
	v_mfma_f32_16x16x32_bf16 v[24:27], v[164:167], v[180:183], v[24:27]
	v_mfma_f32_16x16x32_bf16 v[16:19], v[156:159], v[188:191], v[16:19]
	v_mfma_f32_16x16x32_bf16 v[8:11], v[164:167], v[188:191], v[8:11]
	v_mfma_f32_16x16x32_bf16 v[4:7], v[156:159], v[206:209], v[4:7]
	v_mfma_f32_16x16x32_bf16 v[0:3], v[164:167], v[206:209], v[0:3]
	s_setprio 0
	s_barrier
	s_add_i32 s67, s67, 2
	s_add_u32 s42, s42, 0x100
	s_addc_u32 s43, s43, 0
	s_add_u32 s65, s65, 0x100
	s_addc_u32 s66, s66, 0
	s_cmp_gt_u32 s67, 5
	s_cbranch_scc0 .LBB0_539
	s_andn2_b64 vcc, s[22:23], s[34:35]
	s_cbranch_vccz .LBB0_542
	s_barrier
; __device__ __forceinline__ unsigned cvt_pk_bf16(float lo, float hi) { unsigned r; asm volatile("v_cvt_pk_bf16_f32 %0, %1, %2" : "=v"(r) : "v"(lo), "v"(hi)); return r; }
; #define PG8_BAR __builtin_amdgcn_s_barrier()
;     __device__ __forceinline__ void operator()(const f32x4 (&acc)[2][2][4][2], const Unit& u, int wr, int wc, int fr, int fq) const {
;         const int row0 = u.pm * BM + wr * 64 + fr; int colt = u.pn * BM; bf16_t* base = O;
;         if (split_cols && colt >= split_cols) { base = O2; colt -= split_cols; }
;         const int col0 = colt + wc * 32 + 8 * fq;
;         float rsv[2][4];
; #pragma unroll
;         for (int ai = 0; ai < 2; ++ai)
; #pragma unroll
;             for (int m = 0; m < 4; ++m) rsv[ai][m] = rs ? rs[row0 + ai * HALF + m * 16] : 1.f;
; #pragma unroll
;         for (int ai = 0; ai < 2; ++ai)
; #pragma unroll
;             for (int m = 0; m < 4; ++m) { bf16_t* rowp = base + (size_t)(row0 + ai * HALF + m * 16) * ldc + col0;
;                 const float rsc = rsv[ai][m];
; #pragma unroll
;                 for (int bj = 0; bj < 2; ++bj) { f32x4 v0 = acc[ai][bj][m][0] * rsc, v1 = acc[ai][bj][m][1] * rsc;
;                     if (ACT == 1) {
; #pragma unroll
;                         for (int e = 0; e < 4; ++e) { const float a = fmaxf(v0[e], 0.f), b = fmaxf(v1[e], 0.f); v0[e] = a * a; v1[e] = b * b; } }
;                     u32x4 w; w.x = cvt_pk_bf16(v0[0], v0[1]); w.y = cvt_pk_bf16(v0[2], v0[3]); w.z = cvt_pk_bf16(v1[0], v1[1]); w.w = cvt_pk_bf16(v1[2], v1[3]);
;                     *(u32x4*)(rowp + bj * HALF) = w; } }
; template <class Epi, class Sched, bool ALIGN_EPI = false, bool SP2 = false>
; __device__ __forceinline__ void gemm_phase(PG8_LAS unsigned char* lds, const Gemm g, const Sched& S, const Epi& E, const int tid_in) {
;     ...
;         if (!has_next) break;
; #pragma unroll
;         for (int a = 0; a < 2; ++a)
; #pragma unroll
;             for (int b = 0; b < 2; ++b)
; #pragma unroll
;                 for (int m = 0; m < 4; ++m)
; #pragma unroll
;                     for (int n = 0; n < 2; ++n) acc[a][b][m][n] = (f32x4){0.f, 0.f, 0.f, 0.f};
;         cur = nxt; cA = nA; cB = nB; ++ui;
;         if constexpr (ALIGN_EPI) { if (wr == 1) PG8_BAR; }
.LBB0_542:
	s_cmp_lt_i32 s61, 8
	s_cselect_b32 s12, s57, s11
	v_mov_b32_e32 v131, s12
	s_cselect_b32 s12, 0, 0xfffff800
	v_lshl_or_b32 v137, s61, 8, v134
	v_lshl_add_u32 v136, s62, 8, v132
	s_cselect_b32 s13, s56, s10
	v_add_u32_e32 v138, s12, v137
	v_mov_b32_e32 v130, s13
	v_ashrrev_i32_e32 v139, 31, v138
	v_ashrrev_i32_e32 v137, 31, v136
	v_lshl_add_u64 v[138:139], v[138:139], 1, v[130:131]
	v_lshlrev_b64 v[130:131], 12, v[136:137]
	v_lshl_add_u64 v[130:131], v[138:139], 0, v[130:131]
	v_cvt_pk_bf16_f32 v124, v124, v125
	v_cvt_pk_bf16_f32 v125, v126, v127
	v_cvt_pk_bf16_f32 v126, v120, v121
	v_cvt_pk_bf16_f32 v127, v122, v123
	global_store_dwordx4 v[130:131], v[124:127], off
	v_cvt_pk_bf16_f32 v112, v112, v113
	v_cvt_pk_bf16_f32 v113, v114, v115
	v_cvt_pk_bf16_f32 v114, v104, v105
	v_or_b32_e32 v104, 16, v136
	v_ashrrev_i32_e32 v105, 31, v104
	v_lshlrev_b64 v[104:105], 12, v[104:105]
	v_cvt_pk_bf16_f32 v115, v106, v107
	global_store_dwordx4 v[130:131], v[112:115], off offset:256
	s_mov_b32 s12, 0x80000
	s_nop 0
	v_lshl_add_u64 v[112:113], v[138:139], 0, v[104:105]
	v_cvt_pk_bf16_f32 v104, v116, v117
	v_cvt_pk_bf16_f32 v105, v118, v119
	v_cvt_pk_bf16_f32 v106, v108, v109
	v_cvt_pk_bf16_f32 v107, v110, v111
	global_store_dwordx4 v[112:113], v[104:107], off
	v_cvt_pk_bf16_f32 v96, v96, v97
	v_cvt_pk_bf16_f32 v97, v98, v99
	v_cvt_pk_bf16_f32 v98, v88, v89
	v_or_b32_e32 v88, 32, v136
	v_ashrrev_i32_e32 v89, 31, v88
	v_lshlrev_b64 v[88:89], 12, v[88:89]
	v_cvt_pk_bf16_f32 v99, v90, v91
	global_store_dwordx4 v[112:113], v[96:99], off offset:256
	s_nop 1
	v_lshl_add_u64 v[96:97], v[138:139], 0, v[88:89]
	v_cvt_pk_bf16_f32 v88, v100, v101
	v_cvt_pk_bf16_f32 v89, v102, v103
	v_cvt_pk_bf16_f32 v90, v92, v93
	v_cvt_pk_bf16_f32 v91, v94, v95
	global_store_dwordx4 v[96:97], v[88:91], off
	v_cvt_pk_bf16_f32 v80, v80, v81
	v_cvt_pk_bf16_f32 v81, v82, v83
	v_cvt_pk_bf16_f32 v82, v72, v73
	v_or_b32_e32 v72, 48, v136
	v_ashrrev_i32_e32 v73, 31, v72
	v_lshlrev_b64 v[72:73], 12, v[72:73]
	v_cvt_pk_bf16_f32 v83, v74, v75
	global_store_dwordx4 v[96:97], v[80:83], off offset:256
	s_nop 1
	v_lshl_add_u64 v[80:81], v[138:139], 0, v[72:73]
	v_cvt_pk_bf16_f32 v72, v84, v85
	v_cvt_pk_bf16_f32 v73, v86, v87
	v_cvt_pk_bf16_f32 v74, v76, v77
	v_cvt_pk_bf16_f32 v75, v78, v79
	global_store_dwordx4 v[80:81], v[72:75], off
	v_cvt_pk_bf16_f32 v68, v68, v69
	v_cvt_pk_bf16_f32 v69, v70, v71
	v_cvt_pk_bf16_f32 v70, v64, v65
	v_cvt_pk_bf16_f32 v71, v66, v67
	global_store_dwordx4 v[80:81], v[68:71], off offset:256
	v_cvt_pk_bf16_f32 v60, v60, v61
	v_cvt_pk_bf16_f32 v61, v62, v63
	v_cvt_pk_bf16_f32 v62, v56, v57
	v_add_co_u32_e32 v56, vcc, s12, v130
	v_lshl_add_u64 v[64:65], v[130:131], 0, s[24:25]
	s_nop 0
	v_addc_co_u32_e32 v57, vcc, 0, v131, vcc
	v_cvt_pk_bf16_f32 v63, v58, v59
	global_store_dwordx4 v[56:57], v[60:63], off
	v_cvt_pk_bf16_f32 v48, v48, v49
	v_cvt_pk_bf16_f32 v49, v50, v51
	s_mov_b64 s[12:13], 0x90000
	v_cvt_pk_bf16_f32 v50, v40, v41
	v_cvt_pk_bf16_f32 v51, v42, v43
	global_store_dwordx4 v[64:65], v[48:51], off offset:256
	v_cvt_pk_bf16_f32 v40, v52, v53
	v_cvt_pk_bf16_f32 v41, v54, v55
	v_cvt_pk_bf16_f32 v42, v44, v45
	v_cvt_pk_bf16_f32 v43, v46, v47
	s_nop 1
	v_lshl_add_u64 v[48:49], v[130:131], 0, s[12:13]
	s_mov_b32 s12, 0x90000
	v_add_co_u32_e32 v44, vcc, s12, v130
	s_mov_b64 s[12:13], 0xa0000
	s_nop 0
	v_addc_co_u32_e32 v45, vcc, 0, v131, vcc
	global_store_dwordx4 v[44:45], v[40:43], off
	v_cvt_pk_bf16_f32 v32, v32, v33
	v_cvt_pk_bf16_f32 v33, v34, v35
	v_cvt_pk_bf16_f32 v34, v24, v25
	v_cvt_pk_bf16_f32 v35, v26, v27
	global_store_dwordx4 v[48:49], v[32:35], off offset:256
	v_cvt_pk_bf16_f32 v24, v36, v37
	v_cvt_pk_bf16_f32 v25, v38, v39
	v_cvt_pk_bf16_f32 v26, v28, v29
	v_cvt_pk_bf16_f32 v27, v30, v31
	s_nop 1
	v_lshl_add_u64 v[32:33], v[130:131], 0, s[12:13]
	s_mov_b32 s12, 0xa0000
	v_add_co_u32_e32 v28, vcc, s12, v130
	s_mov_b64 s[12:13], 0xb0000
	s_nop 0
	v_addc_co_u32_e32 v29, vcc, 0, v131, vcc
	global_store_dwordx4 v[28:29], v[24:27], off
	v_cvt_pk_bf16_f32 v16, v16, v17
	v_cvt_pk_bf16_f32 v17, v18, v19
	v_cvt_pk_bf16_f32 v18, v8, v9
	v_cvt_pk_bf16_f32 v19, v10, v11
	global_store_dwordx4 v[32:33], v[16:19], off offset:256
	v_cvt_pk_bf16_f32 v8, v20, v21
	v_cvt_pk_bf16_f32 v9, v22, v23
	v_cvt_pk_bf16_f32 v10, v12, v13
	v_cvt_pk_bf16_f32 v11, v14, v15
	s_nop 1
	v_lshl_add_u64 v[16:17], v[130:131], 0, s[12:13]
	s_mov_b32 s12, 0xb0000
	v_add_co_u32_e32 v12, vcc, s12, v130
	s_nop 1
	v_addc_co_u32_e32 v13, vcc, 0, v131, vcc
	s_andn2_b64 vcc, exec, s[34:35]
	s_mov_b64 s[34:35], -1
	global_store_dwordx4 v[12:13], v[8:11], off
	v_cvt_pk_bf16_f32 v4, v4, v5
	v_cvt_pk_bf16_f32 v5, v6, v7
	v_cvt_pk_bf16_f32 v6, v0, v1
	v_cvt_pk_bf16_f32 v7, v2, v3
	global_store_dwordx4 v[16:17], v[4:7], off offset:256
	s_cbranch_vccnz .LBB0_535
	s_andn2_b64 vcc, exec, s[0:1]
	s_cbranch_vccnz .LBB0_534
	s_branch .LBB0_534

; #define PG8_STAGE(bufoff, gbase, voff) do { _Pragma("unroll") for (int _i = 0; _i < 2; ++_i) \
;         __builtin_amdgcn_global_load_lds((const unsigned*)((const char*)(gbase) + (voff)[_i]), (PG8_LAS unsigned*)(lds + (bufoff) + ldsw + _i * 8192), 16, 0, 0); } while (0)
; #define PG8_LDA(dst, b, h) do { _Pragma("unroll") for (int m = 0; m < 4; ++m) _Pragma("unroll") for (int k = 0; k < 2; ++k) dst[m][k] = *(const PG8_LAS bf16x8*)(lds + PG8_SA(b, h) + aoff + m * 2048 + k * 1024); } while (0)
; #define PG8_LDB(dst, b, h) do { _Pragma("unroll") for (int n = 0; n < 2; ++n) _Pragma("unroll") for (int k = 0; k < 2; ++k) dst[n][k] = *(const PG8_LAS bf16x8*)(lds + PG8_SB(b, h) + boff + n * 2048 + k * 1024); } while (0)
; #define PG8_MMA(ai, bj, At, Bt) do { __builtin_amdgcn_s_setprio(1); _Pragma("unroll") for (int m = 0; m < 4; ++m) _Pragma("unroll") for (int n = 0; n < 2; ++n) _Pragma("unroll") for (int k = 0; k < 2; ++k) \
;         acc[ai][bj][m][n] = __builtin_amdgcn_mfma_f32_16x16x32_bf16(Bt[n][k], At[m][k], acc[ai][bj][m][n], 0, 0, 0); __builtin_amdgcn_s_setprio(0); } while (0)
; #define PG8_WAIT_V(n) asm volatile("s_waitcnt vmcnt(" #n ")" ::: "memory")
; #define PG8_WAIT_L(n) asm volatile("s_waitcnt lgkmcnt(" #n ")" ::: "memory")
; #define PG8_BAR __builtin_amdgcn_s_barrier()
; template <class Epi, class Sched, bool ALIGN_EPI = false, bool SP2 = false>
; __device__ __forceinline__ void gemm_phase(PG8_LAS unsigned char* lds, const Gemm g, const Sched& S, const Epi& E, const int tid_in) {
;     ...
;         for (int t = 0; t < nt; t += 2) {
;             const bool last = (t == nt - 2);
;             const char* a1 = cA + (size_t)(t + 1) * kstep;
;             const char* a2 = last ? nA : cA + (size_t)(t + 2) * kstep; const char* b2 = last ? nB : cB + (size_t)(t + 2) * kstep;
;             const char* a3 = a2 + kstep; const char* b3 = b2 + kstep;
;             if (last && has_next) S.a_ready(nxt);
;             if constexpr (SP2) {
;             PG8_LDB(B0, 0, 0); PG8_LDB(B1, 0, 1); PG8_SCHED; PG8_LDA(At, 0, 0); PG8_STAGE(PG8_SA(1, 1), a1 + hstepA, voffA);
;             PG8_WAIT_V(8); PG8_WAIT_L(0); PG8_BAR; PG8_MMA(0, 0, At, B0); PG8_MMA(0, 1, At, B1); PG8_BAR; PG8_SCHED;
;             PG8_LDA(At, 0, 1); PG8_STAGE(PG8_SB(0, 0), b2, voffB); PG8_STAGE(PG8_SB(0, 1), b2 + hstepB, voffB); PG8_STAGE(PG8_SA(0, 0), a2, voffA);
.LBB0_737:
	s_add_u32 s12, s44, 0xfff80080
	s_addc_u32 s13, s45, -1
	s_add_i32 s66, 0, 0x10000
	s_cmp_eq_u32 s65, 28
	s_cselect_b32 s49, s39, s13
	s_cselect_b32 s48, s61, s12
	s_cselect_b32 s47, s37, s64
	s_cselect_b32 s46, s62, s63
	s_add_i32 s67, 0, 0x14000
	v_add_u32_e32 v140, s66, v225
	v_add_u32_e32 v156, s67, v225
	ds_read_b128 v[128:131], v140
	ds_read_b128 v[132:135], v140 offset:1024
	ds_read_b128 v[136:139], v140 offset:2048
	ds_read_b128 v[140:143], v140 offset:3072
	ds_read_b128 v[144:147], v156
	ds_read_b128 v[148:151], v156 offset:1024
	ds_read_b128 v[152:155], v156 offset:2048
	ds_read_b128 v[156:159], v156 offset:3072
	v_lshl_add_u64 v[194:195], s[44:45], 0, v[204:205]
	s_add_i32 m0, s52, 0xc000
	ds_read_b128 v[160:163], v227
	ds_read_b128 v[164:167], v227 offset:1024
	ds_read_b128 v[168:171], v227 offset:2048
	ds_read_b128 v[172:175], v227 offset:3072
	ds_read_b128 v[176:179], v227 offset:4096
	ds_read_b128 v[180:183], v227 offset:5120
	ds_read_b128 v[184:187], v227 offset:6144
	ds_read_b128 v[188:191], v227 offset:7168
	global_load_lds_dwordx4 v[194:195], off
	v_lshl_add_u64 v[194:195], s[44:45], 0, v[206:207]
	s_add_i32 m0, s52, 0xe000
	s_nop 0
	global_load_lds_dwordx4 v[194:195], off
	s_waitcnt vmcnt(8)
	s_waitcnt lgkmcnt(0)
	s_barrier
	s_setprio 1
	s_waitcnt lgkmcnt(0)
	v_mfma_f32_16x16x32_bf16 v[124:127], v[128:131], v[160:163], v[124:127]
	v_mfma_f32_16x16x32_bf16 v[120:123], v[136:139], v[160:163], v[120:123]
	v_mfma_f32_16x16x32_bf16 v[108:111], v[128:131], v[168:171], v[108:111]
	v_mfma_f32_16x16x32_bf16 v[104:107], v[136:139], v[168:171], v[104:107]
	v_mfma_f32_16x16x32_bf16 v[96:99], v[128:131], v[176:179], v[96:99]
	v_mfma_f32_16x16x32_bf16 v[88:91], v[136:139], v[176:179], v[88:91]
	v_mfma_f32_16x16x32_bf16 v[80:83], v[128:131], v[184:187], v[80:83]
	v_mfma_f32_16x16x32_bf16 v[72:75], v[136:139], v[184:187], v[72:75]
	v_mfma_f32_16x16x32_bf16 v[124:127], v[132:135], v[164:167], v[124:127]
	v_mfma_f32_16x16x32_bf16 v[120:123], v[140:143], v[164:167], v[120:123]
	v_mfma_f32_16x16x32_bf16 v[108:111], v[132:135], v[172:175], v[108:111]
	v_mfma_f32_16x16x32_bf16 v[104:107], v[140:143], v[172:175], v[104:107]
	v_mfma_f32_16x16x32_bf16 v[96:99], v[132:135], v[180:183], v[96:99]
	v_mfma_f32_16x16x32_bf16 v[88:91], v[140:143], v[180:183], v[88:91]
	v_mfma_f32_16x16x32_bf16 v[80:83], v[132:135], v[188:191], v[80:83]
	v_mfma_f32_16x16x32_bf16 v[72:75], v[140:143], v[188:191], v[72:75]
	v_mfma_f32_16x16x32_bf16 v[116:119], v[144:147], v[160:163], v[116:119]
	v_mfma_f32_16x16x32_bf16 v[112:115], v[152:155], v[160:163], v[112:115]
	v_mfma_f32_16x16x32_bf16 v[100:103], v[144:147], v[168:171], v[100:103]
	v_mfma_f32_16x16x32_bf16 v[92:95], v[152:155], v[168:171], v[92:95]
	v_mfma_f32_16x16x32_bf16 v[84:87], v[144:147], v[176:179], v[84:87]
	v_mfma_f32_16x16x32_bf16 v[76:79], v[152:155], v[176:179], v[76:79]
	v_mfma_f32_16x16x32_bf16 v[68:71], v[144:147], v[184:187], v[68:71]
	v_mfma_f32_16x16x32_bf16 v[64:67], v[152:155], v[184:187], v[64:67]
	v_mfma_f32_16x16x32_bf16 v[116:119], v[148:151], v[164:167], v[116:119]
	v_mfma_f32_16x16x32_bf16 v[112:115], v[156:159], v[164:167], v[112:115]
	v_mfma_f32_16x16x32_bf16 v[100:103], v[148:151], v[172:175], v[100:103]
	v_mfma_f32_16x16x32_bf16 v[92:95], v[156:159], v[172:175], v[92:95]
	v_mfma_f32_16x16x32_bf16 v[84:87], v[148:151], v[180:183], v[84:87]
	v_mfma_f32_16x16x32_bf16 v[76:79], v[156:159], v[180:183], v[76:79]
	v_mfma_f32_16x16x32_bf16 v[68:71], v[148:151], v[188:191], v[68:71]
	v_mfma_f32_16x16x32_bf16 v[64:67], v[156:159], v[188:191], v[64:67]
	s_setprio 0
	s_barrier
	s_add_i32 s12, s66, s51
	v_lshl_add_u64 v[194:195], s[46:47], 0, v[192:193]
	s_mov_b32 m0, s12
	ds_read_b128 v[160:163], v227 offset:16384
	ds_read_b128 v[164:167], v227 offset:17408
	ds_read_b128 v[168:171], v227 offset:18432
	ds_read_b128 v[172:175], v227 offset:19456
	ds_read_b128 v[176:179], v227 offset:20480
	ds_read_b128 v[180:183], v227 offset:21504
	ds_read_b128 v[184:187], v227 offset:22528
	ds_read_b128 v[188:191], v227 offset:23552
	global_load_lds_dwordx4 v[194:195], off
	s_add_i32 m0, s12, 0x2000
	s_add_u32 s12, s46, 0x80000
	v_lshl_add_u64 v[196:197], s[46:47], 0, v[202:203]
	s_addc_u32 s13, s47, 0
	s_add_i32 s66, s67, s51
	global_load_lds_dwordx4 v[196:197], off
	v_lshl_add_u64 v[208:209], s[12:13], 0, v[192:193]
	s_mov_b32 m0, s66
	v_lshl_add_u64 v[210:211], s[48:49], 0, v[200:201]
	global_load_lds_dwordx4 v[208:209], off
	v_lshl_add_u64 v[208:209], s[12:13], 0, v[202:203]
	s_add_i32 m0, s66, 0x2000
	s_nop 0
	global_load_lds_dwordx4 v[208:209], off
	v_lshl_add_u64 v[208:209], s[48:49], 0, v[198:199]
	s_mov_b32 m0, s52
	s_nop 0
	global_load_lds_dwordx4 v[208:209], off
	s_mov_b32 m0, s53
	s_nop 0
	global_load_lds_dwordx4 v[210:211], off
	s_waitcnt vmcnt(8)
	s_waitcnt lgkmcnt(0)
	s_barrier
; #define PG8_STAGE(bufoff, gbase, voff) do { _Pragma("unroll") for (int _i = 0; _i < 2; ++_i) \
;         __builtin_amdgcn_global_load_lds((const unsigned*)((const char*)(gbase) + (voff)[_i]), (PG8_LAS unsigned*)(lds + (bufoff) + ldsw + _i * 8192), 16, 0, 0); } while (0)
; #define PG8_LDA(dst, b, h) do { _Pragma("unroll") for (int m = 0; m < 4; ++m) _Pragma("unroll") for (int k = 0; k < 2; ++k) dst[m][k] = *(const PG8_LAS bf16x8*)(lds + PG8_SA(b, h) + aoff + m * 2048 + k * 1024); } while (0)
; #define PG8_LDB(dst, b, h) do { _Pragma("unroll") for (int n = 0; n < 2; ++n) _Pragma("unroll") for (int k = 0; k < 2; ++k) dst[n][k] = *(const PG8_LAS bf16x8*)(lds + PG8_SB(b, h) + boff + n * 2048 + k * 1024); } while (0)
; #define PG8_MMA(ai, bj, At, Bt) do { __builtin_amdgcn_s_setprio(1); _Pragma("unroll") for (int m = 0; m < 4; ++m) _Pragma("unroll") for (int n = 0; n < 2; ++n) _Pragma("unroll") for (int k = 0; k < 2; ++k) \
;         acc[ai][bj][m][n] = __builtin_amdgcn_mfma_f32_16x16x32_bf16(Bt[n][k], At[m][k], acc[ai][bj][m][n], 0, 0, 0); __builtin_amdgcn_s_setprio(0); } while (0)
; #define PG8_WAIT_V(n) asm volatile("s_waitcnt vmcnt(" #n ")" ::: "memory")
; #define PG8_WAIT_L(n) asm volatile("s_waitcnt lgkmcnt(" #n ")" ::: "memory")
; #define PG8_BAR __builtin_amdgcn_s_barrier()
; #define PG8_SCHED __builtin_amdgcn_sched_barrier(0)
; template <class Epi, class Sched, bool ALIGN_EPI = false, bool SP2 = false>
; __device__ __forceinline__ void gemm_phase(PG8_LAS unsigned char* lds, const Gemm g, const Sched& S, const Epi& E, const int tid_in) {
;     ...
;             PG8_WAIT_V(8); PG8_WAIT_L(0); PG8_BAR; PG8_MMA(1, 0, At, B0); PG8_MMA(1, 1, At, B1); PG8_BAR; PG8_SCHED;
;             PG8_LDB(B0, 1, 0); PG8_LDB(B1, 1, 1); PG8_SCHED; PG8_LDA(At, 1, 0); PG8_STAGE(PG8_SA(0, 1), a2 + hstepA, voffA);
;             PG8_WAIT_V(8); PG8_WAIT_L(0); PG8_BAR; PG8_MMA(0, 0, At, B0); PG8_MMA(0, 1, At, B1); PG8_BAR; PG8_SCHED;
	s_setprio 1
	s_waitcnt lgkmcnt(0)
	v_mfma_f32_16x16x32_bf16 v[60:63], v[128:131], v[160:163], v[60:63]
	v_mfma_f32_16x16x32_bf16 v[56:59], v[136:139], v[160:163], v[56:59]
	v_mfma_f32_16x16x32_bf16 v[48:51], v[128:131], v[168:171], v[48:51]
	v_mfma_f32_16x16x32_bf16 v[40:43], v[136:139], v[168:171], v[40:43]
	v_mfma_f32_16x16x32_bf16 v[32:35], v[128:131], v[176:179], v[32:35]
	v_mfma_f32_16x16x32_bf16 v[24:27], v[136:139], v[176:179], v[24:27]
	v_mfma_f32_16x16x32_bf16 v[16:19], v[128:131], v[184:187], v[16:19]
	v_mfma_f32_16x16x32_bf16 v[8:11], v[136:139], v[184:187], v[8:11]
	v_mfma_f32_16x16x32_bf16 v[60:63], v[132:135], v[164:167], v[60:63]
	v_mfma_f32_16x16x32_bf16 v[56:59], v[140:143], v[164:167], v[56:59]
	v_mfma_f32_16x16x32_bf16 v[48:51], v[132:135], v[172:175], v[48:51]
	v_mfma_f32_16x16x32_bf16 v[40:43], v[140:143], v[172:175], v[40:43]
	v_mfma_f32_16x16x32_bf16 v[32:35], v[132:135], v[180:183], v[32:35]
	v_mfma_f32_16x16x32_bf16 v[24:27], v[140:143], v[180:183], v[24:27]
	v_mfma_f32_16x16x32_bf16 v[16:19], v[132:135], v[188:191], v[16:19]
	v_mfma_f32_16x16x32_bf16 v[8:11], v[140:143], v[188:191], v[8:11]
	v_mfma_f32_16x16x32_bf16 v[52:55], v[144:147], v[160:163], v[52:55]
	v_mfma_f32_16x16x32_bf16 v[44:47], v[152:155], v[160:163], v[44:47]
	v_mfma_f32_16x16x32_bf16 v[36:39], v[144:147], v[168:171], v[36:39]
	v_mfma_f32_16x16x32_bf16 v[28:31], v[152:155], v[168:171], v[28:31]
	v_mfma_f32_16x16x32_bf16 v[20:23], v[144:147], v[176:179], v[20:23]
	v_mfma_f32_16x16x32_bf16 v[12:15], v[152:155], v[176:179], v[12:15]
	v_mfma_f32_16x16x32_bf16 v[4:7], v[144:147], v[184:187], v[4:7]
	v_mfma_f32_16x16x32_bf16 v[0:3], v[152:155], v[184:187], v[0:3]
	v_mfma_f32_16x16x32_bf16 v[52:55], v[148:151], v[164:167], v[52:55]
	v_mfma_f32_16x16x32_bf16 v[44:47], v[156:159], v[164:167], v[44:47]
	v_mfma_f32_16x16x32_bf16 v[36:39], v[148:151], v[172:175], v[36:39]
	v_mfma_f32_16x16x32_bf16 v[28:31], v[156:159], v[172:175], v[28:31]
	v_mfma_f32_16x16x32_bf16 v[20:23], v[148:151], v[180:183], v[20:23]
	v_mfma_f32_16x16x32_bf16 v[12:15], v[156:159], v[180:183], v[12:15]
	v_mfma_f32_16x16x32_bf16 v[4:7], v[148:151], v[188:191], v[4:7]
	v_mfma_f32_16x16x32_bf16 v[0:3], v[156:159], v[188:191], v[0:3]
	s_setprio 0
	s_barrier
	s_add_i32 s66, 0, 0x18000
	s_add_i32 s67, 0, 0x1c000
	v_add_u32_e32 v140, s66, v225
	v_add_u32_e32 v156, s67, v225
	ds_read_b128 v[128:131], v140
	ds_read_b128 v[132:135], v140 offset:1024
	ds_read_b128 v[136:139], v140 offset:2048
	ds_read_b128 v[140:143], v140 offset:3072
	ds_read_b128 v[144:147], v156
	ds_read_b128 v[148:151], v156 offset:1024
	ds_read_b128 v[152:155], v156 offset:2048
	ds_read_b128 v[156:159], v156 offset:3072
	s_add_u32 s12, s48, 0x80000
	s_addc_u32 s13, s49, 0
	s_mov_b32 m0, s54
	v_lshl_add_u64 v[212:213], s[12:13], 0, v[198:199]
	ds_read_b128 v[160:163], v227 offset:32768
	ds_read_b128 v[164:167], v227 offset:33792
	ds_read_b128 v[168:171], v227 offset:34816
	ds_read_b128 v[172:175], v227 offset:35840
	ds_read_b128 v[176:179], v227 offset:36864
	ds_read_b128 v[180:183], v227 offset:37888
	ds_read_b128 v[184:187], v227 offset:38912
	ds_read_b128 v[188:191], v227 offset:39936
	global_load_lds_dwordx4 v[212:213], off
	v_lshl_add_u64 v[212:213], s[12:13], 0, v[200:201]
	s_mov_b32 m0, s55
	s_nop 0
	global_load_lds_dwordx4 v[212:213], off
	s_waitcnt vmcnt(8)
	s_waitcnt lgkmcnt(0)
	s_barrier
	s_setprio 1
	s_waitcnt lgkmcnt(0)
	v_mfma_f32_16x16x32_bf16 v[124:127], v[128:131], v[160:163], v[124:127]
	v_mfma_f32_16x16x32_bf16 v[120:123], v[136:139], v[160:163], v[120:123]
	v_mfma_f32_16x16x32_bf16 v[108:111], v[128:131], v[168:171], v[108:111]
	v_mfma_f32_16x16x32_bf16 v[104:107], v[136:139], v[168:171], v[104:107]
	v_mfma_f32_16x16x32_bf16 v[96:99], v[128:131], v[176:179], v[96:99]
	v_mfma_f32_16x16x32_bf16 v[88:91], v[136:139], v[176:179], v[88:91]
	v_mfma_f32_16x16x32_bf16 v[80:83], v[128:131], v[184:187], v[80:83]
	v_mfma_f32_16x16x32_bf16 v[72:75], v[136:139], v[184:187], v[72:75]
	v_mfma_f32_16x16x32_bf16 v[124:127], v[132:135], v[164:167], v[124:127]
	v_mfma_f32_16x16x32_bf16 v[120:123], v[140:143], v[164:167], v[120:123]
	v_mfma_f32_16x16x32_bf16 v[108:111], v[132:135], v[172:175], v[108:111]
	v_mfma_f32_16x16x32_bf16 v[104:107], v[140:143], v[172:175], v[104:107]
	v_mfma_f32_16x16x32_bf16 v[96:99], v[132:135], v[180:183], v[96:99]
	v_mfma_f32_16x16x32_bf16 v[88:91], v[140:143], v[180:183], v[88:91]
	v_mfma_f32_16x16x32_bf16 v[80:83], v[132:135], v[188:191], v[80:83]
	v_mfma_f32_16x16x32_bf16 v[72:75], v[140:143], v[188:191], v[72:75]
	v_mfma_f32_16x16x32_bf16 v[116:119], v[144:147], v[160:163], v[116:119]
	v_mfma_f32_16x16x32_bf16 v[112:115], v[152:155], v[160:163], v[112:115]
	v_mfma_f32_16x16x32_bf16 v[100:103], v[144:147], v[168:171], v[100:103]
	v_mfma_f32_16x16x32_bf16 v[92:95], v[152:155], v[168:171], v[92:95]
	v_mfma_f32_16x16x32_bf16 v[84:87], v[144:147], v[176:179], v[84:87]
	v_mfma_f32_16x16x32_bf16 v[76:79], v[152:155], v[176:179], v[76:79]
	v_mfma_f32_16x16x32_bf16 v[68:71], v[144:147], v[184:187], v[68:71]
	v_mfma_f32_16x16x32_bf16 v[64:67], v[152:155], v[184:187], v[64:67]
	v_mfma_f32_16x16x32_bf16 v[116:119], v[148:151], v[164:167], v[116:119]
	v_mfma_f32_16x16x32_bf16 v[112:115], v[156:159], v[164:167], v[112:115]
	v_mfma_f32_16x16x32_bf16 v[100:103], v[148:151], v[172:175], v[100:103]
	v_mfma_f32_16x16x32_bf16 v[92:95], v[156:159], v[172:175], v[92:95]
	v_mfma_f32_16x16x32_bf16 v[84:87], v[148:151], v[180:183], v[84:87]
	v_mfma_f32_16x16x32_bf16 v[76:79], v[156:159], v[180:183], v[76:79]
	v_mfma_f32_16x16x32_bf16 v[68:71], v[148:151], v[188:191], v[68:71]
	v_mfma_f32_16x16x32_bf16 v[64:67], v[156:159], v[188:191], v[64:67]
	s_setprio 0
	s_barrier
; #define PG8_WAIT_V(n) asm volatile("s_waitcnt vmcnt(" #n ")" ::: "memory")
;     __device__ __forceinline__ void operator()(const f32x4 (&acc)[2][2][4][2], const Unit& u, int wr, int wc, int fr, int fq) const {
;         const int row0 = u.pm * BM + wr * 64 + fr; const int col0 = u.pn * BM + wc * 32 + 8 * fq;
;         u32x4 ov[2][4][2];
; #pragma unroll
;         for (int ai = 0; ai < 2; ++ai)
; #pragma unroll
;             for (int m = 0; m < 4; ++m) { const bf16_t* rowp = H + (size_t)(row0 + ai * HALF + m * 16) * ldc + col0;
; #pragma unroll
; template <class Epi, class Sched, bool ALIGN_EPI = false, bool SP2 = false>
; __device__ __forceinline__ void gemm_phase(PG8_LAS unsigned char* lds, const Gemm g, const Sched& S, const Epi& E, const int tid_in) {
;     ...
;             PG8_LDA(At, 1, 1); PG8_STAGE(PG8_SB(1, 0), b3, voffB); PG8_STAGE(PG8_SB(1, 1), b3 + hstepB, voffB); PG8_STAGE(PG8_SA(1, 0), a3, voffA);
;             PG8_WAIT_V(8); PG8_WAIT_L(0); PG8_BAR; PG8_MMA(1, 0, At, B0); PG8_MMA(1, 1, At, B1); PG8_BAR; PG8_SCHED;
;             } else {
;             PG8_LDB(B0, 0, 0); PG8_SCHED; PG8_LDA(At, 0, 0); PG8_STAGE(PG8_SA(1, 1), a1 + hstepA, voffA);
;             PG8_WAIT_L(8); PG8_BAR; PG8_WAIT_L(0); PG8_MMA(0, 0, At, B0); PG8_BAR; PG8_SCHED;
;             PG8_LDB(B1, 0, 1); PG8_STAGE(PG8_SB(0, 0), b2, voffB);
;             PG8_BAR; PG8_WAIT_L(0); PG8_MMA(0, 1, At, B1); PG8_BAR;
;             PG8_LDA(At, 0, 1); PG8_STAGE(PG8_SA(0, 0), a2, voffA);
;             PG8_BAR; PG8_WAIT_L(0); PG8_MMA(1, 0, At, B0); PG8_BAR; PG8_SCHED;
;             PG8_STAGE(PG8_SB(0, 1), b2 + hstepB, voffB);
;             PG8_WAIT_V(6); PG8_BAR; PG8_MMA(1, 1, At, B1); PG8_BAR;
;             PG8_LDB(B0, 1, 0); PG8_SCHED; PG8_LDA(At, 1, 0); PG8_STAGE(PG8_SA(0, 1), a2 + hstepA, voffA);
;             PG8_WAIT_L(8); PG8_BAR; PG8_WAIT_L(0); PG8_MMA(0, 0, At, B0); PG8_BAR; PG8_SCHED;
;             PG8_LDB(B1, 1, 1); PG8_STAGE(PG8_SB(1, 0), b3, voffB);
;             PG8_BAR; PG8_WAIT_L(0); PG8_MMA(0, 1, At, B1); PG8_BAR;
;             PG8_LDA(At, 1, 1); PG8_STAGE(PG8_SA(1, 0), a3, voffA);
;             PG8_BAR; PG8_WAIT_L(0); PG8_MMA(1, 0, At, B0); PG8_BAR; PG8_SCHED;
;             PG8_STAGE(PG8_SB(1, 1), b3 + hstepB, voffB);
;             PG8_WAIT_V(6); PG8_BAR; PG8_MMA(1, 1, At, B1); PG8_BAR;
;             }
;         }
;         if constexpr (ALIGN_EPI) { if (wr == 0) PG8_BAR; }
	s_add_i32 s12, s66, s51
	v_lshl_add_u64 v[194:195], v[194:195], 0, s[26:27]
	s_mov_b32 m0, s12
	ds_read_b128 v[160:163], v227 offset:49152
	ds_read_b128 v[164:167], v227 offset:50176
	ds_read_b128 v[168:171], v227 offset:51200
	ds_read_b128 v[172:175], v227 offset:52224
	ds_read_b128 v[176:179], v227 offset:53248
	ds_read_b128 v[180:183], v227 offset:54272
	ds_read_b128 v[184:187], v227 offset:55296
	ds_read_b128 v[188:191], v227 offset:56320
	global_load_lds_dwordx4 v[194:195], off
	s_add_i32 m0, s12, 0x2000
	s_add_u32 s12, s46, 0x80080
	v_lshl_add_u64 v[194:195], v[196:197], 0, s[26:27]
	s_addc_u32 s13, s47, 0
	s_add_i32 s46, s67, s51
	global_load_lds_dwordx4 v[194:195], off
	v_lshl_add_u64 v[194:195], s[12:13], 0, v[192:193]
	s_mov_b32 m0, s46
	s_nop 0
	global_load_lds_dwordx4 v[194:195], off
	v_lshl_add_u64 v[194:195], s[12:13], 0, v[202:203]
	s_add_i32 m0, s46, 0x2000
	s_nop 0
	global_load_lds_dwordx4 v[194:195], off
	v_lshl_add_u64 v[194:195], v[208:209], 0, s[26:27]
	s_mov_b32 m0, s56
	s_nop 0
	global_load_lds_dwordx4 v[194:195], off
	v_lshl_add_u64 v[194:195], v[210:211], 0, s[26:27]
	s_mov_b32 m0, s57
	s_nop 0
	global_load_lds_dwordx4 v[194:195], off
	s_waitcnt vmcnt(8)
	s_waitcnt lgkmcnt(0)
	s_barrier
	s_setprio 1
	s_waitcnt lgkmcnt(0)
	v_mfma_f32_16x16x32_bf16 v[60:63], v[128:131], v[160:163], v[60:63]
	v_mfma_f32_16x16x32_bf16 v[56:59], v[136:139], v[160:163], v[56:59]
	v_mfma_f32_16x16x32_bf16 v[48:51], v[128:131], v[168:171], v[48:51]
	v_mfma_f32_16x16x32_bf16 v[40:43], v[136:139], v[168:171], v[40:43]
	v_mfma_f32_16x16x32_bf16 v[32:35], v[128:131], v[176:179], v[32:35]
	v_mfma_f32_16x16x32_bf16 v[24:27], v[136:139], v[176:179], v[24:27]
	v_mfma_f32_16x16x32_bf16 v[16:19], v[128:131], v[184:187], v[16:19]
	v_mfma_f32_16x16x32_bf16 v[8:11], v[136:139], v[184:187], v[8:11]
	v_mfma_f32_16x16x32_bf16 v[60:63], v[132:135], v[164:167], v[60:63]
	v_mfma_f32_16x16x32_bf16 v[56:59], v[140:143], v[164:167], v[56:59]
	v_mfma_f32_16x16x32_bf16 v[48:51], v[132:135], v[172:175], v[48:51]
	v_mfma_f32_16x16x32_bf16 v[40:43], v[140:143], v[172:175], v[40:43]
	v_mfma_f32_16x16x32_bf16 v[32:35], v[132:135], v[180:183], v[32:35]
	v_mfma_f32_16x16x32_bf16 v[24:27], v[140:143], v[180:183], v[24:27]
	v_mfma_f32_16x16x32_bf16 v[16:19], v[132:135], v[188:191], v[16:19]
	v_mfma_f32_16x16x32_bf16 v[8:11], v[140:143], v[188:191], v[8:11]
	v_mfma_f32_16x16x32_bf16 v[52:55], v[144:147], v[160:163], v[52:55]
	v_mfma_f32_16x16x32_bf16 v[44:47], v[152:155], v[160:163], v[44:47]
	v_mfma_f32_16x16x32_bf16 v[36:39], v[144:147], v[168:171], v[36:39]
	v_mfma_f32_16x16x32_bf16 v[28:31], v[152:155], v[168:171], v[28:31]
	v_mfma_f32_16x16x32_bf16 v[20:23], v[144:147], v[176:179], v[20:23]
	v_mfma_f32_16x16x32_bf16 v[12:15], v[152:155], v[176:179], v[12:15]
	v_mfma_f32_16x16x32_bf16 v[4:7], v[144:147], v[184:187], v[4:7]
	v_mfma_f32_16x16x32_bf16 v[0:3], v[152:155], v[184:187], v[0:3]
	v_mfma_f32_16x16x32_bf16 v[52:55], v[148:151], v[164:167], v[52:55]
	v_mfma_f32_16x16x32_bf16 v[44:47], v[156:159], v[164:167], v[44:47]
	v_mfma_f32_16x16x32_bf16 v[36:39], v[148:151], v[172:175], v[36:39]
	v_mfma_f32_16x16x32_bf16 v[28:31], v[156:159], v[172:175], v[28:31]
	v_mfma_f32_16x16x32_bf16 v[20:23], v[148:151], v[180:183], v[20:23]
	v_mfma_f32_16x16x32_bf16 v[12:15], v[156:159], v[180:183], v[12:15]
	v_mfma_f32_16x16x32_bf16 v[4:7], v[148:151], v[188:191], v[4:7]
	v_mfma_f32_16x16x32_bf16 v[0:3], v[156:159], v[188:191], v[0:3]
	s_setprio 0
	s_barrier
	s_add_i32 s65, s65, 2
	s_add_u32 s44, s44, 0x100
	s_addc_u32 s45, s45, 0
	s_add_u32 s63, s63, 0x100
	s_addc_u32 s64, s64, 0
	s_cmp_gt_u32 s65, 29
	s_cbranch_scc0 .LBB0_737
	s_andn2_b64 vcc, s[30:31], s[34:35]
	s_cbranch_vccz .LBB0_740
	s_barrier
.LBB0_740:
	v_lshl_or_b32 v128, s59, 8, v226
	v_lshl_add_u32 v130, s60, 8, v224
	v_ashrrev_i32_e32 v129, 31, v128
	v_lshlrev_b64 v[208:209], 1, v[128:129]
	v_ashrrev_i32_e32 v131, 31, v130
	v_lshl_add_u64 v[136:137], s[28:29], 0, v[208:209]
	v_lshlrev_b64 v[138:139], 12, v[130:131]
	v_lshl_add_u64 v[128:129], v[136:137], 0, v[138:139]
	global_load_dwordx4 v[172:175], v[128:129], off
	global_load_dwordx4 v[164:167], v[128:129], off offset:256
	v_or_b32_e32 v128, 16, v130
	v_ashrrev_i32_e32 v129, 31, v128
	v_lshlrev_b64 v[128:129], 12, v[128:129]
	v_lshl_add_u64 v[140:141], v[136:137], 0, v[128:129]
	global_load_dwordx4 v[132:135], v[140:141], off
	global_load_dwordx4 v[148:151], v[140:141], off offset:256
	v_or_b32_e32 v142, 32, v130
	v_or_b32_e32 v130, 48, v130
	s_mov_b64 s[12:13], 0x90000
	v_ashrrev_i32_e32 v143, 31, v142
	v_ashrrev_i32_e32 v131, 31, v130
	v_lshl_add_u64 v[214:215], v[138:139], 0, s[12:13]
	s_mov_b64 s[12:13], 0xa0000
	v_lshlrev_b64 v[220:221], 12, v[142:143]
	v_lshlrev_b64 v[218:219], 12, v[130:131]
	v_lshl_add_u64 v[216:217], v[138:139], 0, s[24:25]
	v_lshl_add_u64 v[212:213], v[138:139], 0, s[12:13]
	s_mov_b64 s[12:13], 0xb0000
	v_lshl_add_u64 v[210:211], v[138:139], 0, s[12:13]
	v_lshl_add_u64 v[130:131], s[28:29], 0, v[138:139]
	v_lshl_add_u64 v[138:139], v[136:137], 0, v[220:221]
	v_lshl_add_u64 v[142:143], v[136:137], 0, v[218:219]
	v_lshl_add_u64 v[144:145], v[136:137], 0, v[216:217]
	v_lshl_add_u64 v[146:147], v[136:137], 0, v[214:215]
	v_lshl_add_u64 v[194:195], v[136:137], 0, v[212:213]
	v_lshl_add_u64 v[196:197], v[136:137], 0, v[210:211]
	v_lshl_add_u64 v[222:223], v[130:131], 0, v[208:209]
	v_lshl_add_u64 v[228:229], s[28:29], 0, v[128:129]
	global_load_dwordx4 v[188:191], v[138:139], off
	global_load_dwordx4 v[184:187], v[138:139], off offset:256
	global_load_dwordx4 v[180:183], v[142:143], off
	global_load_dwordx4 v[176:179], v[142:143], off offset:256
	global_load_dwordx4 v[168:171], v[144:145], off
	global_load_dwordx4 v[160:163], v[144:145], off offset:256
	global_load_dwordx4 v[156:159], v[146:147], off
	global_load_dwordx4 v[152:155], v[146:147], off offset:256
	s_nop 0
	global_load_dwordx4 v[144:147], v[194:195], off
	global_load_dwordx4 v[140:143], v[194:195], off offset:256
	global_load_dwordx4 v[136:139], v[196:197], off
	global_load_dwordx4 v[128:131], v[196:197], off offset:256
	v_lshl_add_u64 v[194:195], v[228:229], 0, v[208:209]
	s_andn2_b64 vcc, exec, s[34:35]
	s_mov_b64 s[34:35], -1
	s_waitcnt vmcnt(0)
; __device__ __forceinline__ unsigned cvt_pk_bf16(float lo, float hi) { unsigned r; asm volatile("v_cvt_pk_bf16_f32 %0, %1, %2" : "=v"(r) : "v"(lo), "v"(hi)); return r; }
; __device__ __forceinline__ float bf_lo(unsigned w) { return __uint_as_float(w << 16); }
; __device__ __forceinline__ float bf_hi(unsigned w) { return __uint_as_float(w & 0xffff0000u); }
;     __device__ __forceinline__ void operator()(const f32x4 (&acc)[2][2][4][2], const Unit& u, int wr, int wc, int fr, int fq) const {
;     ...
; #pragma unroll
;         for (int ai = 0; ai < 2; ++ai)
; #pragma unroll
;             for (int m = 0; m < 4; ++m) { bf16_t* rowp = H + (size_t)(row0 + ai * HALF + m * 16) * ldc + col0;
;                 float sq = 0.f;
; #pragma unroll
;                 for (int bj = 0; bj < 2; ++bj) { const f32x4 v0 = acc[ai][bj][m][0], v1 = acc[ai][bj][m][1];
;                     const u32x4 o = ov[ai][m][bj]; u32x4 w;
;                     w.x = cvt_pk_bf16(bf_lo(o.x) + v0[0], bf_hi(o.x) + v0[1]); w.y = cvt_pk_bf16(bf_lo(o.y) + v0[2], bf_hi(o.y) + v0[3]);
;                     w.z = cvt_pk_bf16(bf_lo(o.z) + v1[0], bf_hi(o.z) + v1[1]); w.w = cvt_pk_bf16(bf_lo(o.w) + v1[2], bf_hi(o.w) + v1[3]);
;                     if (part) {
; #pragma unroll
;                         for (int e = 0; e < 4; ++e) { const float x = bf_lo(w[e]), y = bf_hi(w[e]); sq += x * x + y * y; } }
;                     if (!dry) *(u32x4*)(rowp + bj * HALF) = w; }
	v_lshlrev_b32_e32 v196, 16, v172
	v_and_b32_e32 v172, 0xffff0000, v172
	v_lshlrev_b32_e32 v230, 16, v164
	v_and_b32_e32 v164, 0xffff0000, v164
	v_lshlrev_b32_e32 v232, 16, v166
	v_lshlrev_b32_e32 v197, 16, v173
	v_and_b32_e32 v173, 0xffff0000, v173
	v_lshlrev_b32_e32 v228, 16, v174
	v_and_b32_e32 v174, 0xffff0000, v174
	v_lshlrev_b32_e32 v229, 16, v175
	v_and_b32_e32 v175, 0xffff0000, v175
	v_lshlrev_b32_e32 v231, 16, v165
	v_and_b32_e32 v165, 0xffff0000, v165
	v_and_b32_e32 v166, 0xffff0000, v166
	v_lshlrev_b32_e32 v233, 16, v167
	v_and_b32_e32 v167, 0xffff0000, v167
	v_add_f32_e32 v124, v124, v196
	v_add_f32_e32 v125, v125, v172
	v_add_f32_e32 v117, v117, v164
	v_add_f32_e32 v164, v112, v232
	v_cvt_pk_bf16_f32 v112, v124, v125
	v_add_f32_e32 v126, v126, v197
	v_add_f32_e32 v127, v127, v173
	v_add_f32_e32 v120, v120, v228
	v_add_f32_e32 v121, v121, v174
	v_add_f32_e32 v122, v122, v229
	v_add_f32_e32 v123, v123, v175
	v_add_f32_e32 v116, v116, v230
	v_add_f32_e32 v119, v119, v165
	v_add_f32_e32 v165, v113, v166
	v_add_f32_e32 v166, v114, v233
	v_add_f32_e32 v167, v115, v167
	v_cvt_pk_bf16_f32 v113, v126, v127
	v_cvt_pk_bf16_f32 v114, v120, v121
	v_cvt_pk_bf16_f32 v115, v122, v123
	global_store_dwordx4 v[222:223], v[112:115], off
	v_add_f32_e32 v118, v118, v231
	s_nop 0
	v_cvt_pk_bf16_f32 v112, v116, v117
	v_cvt_pk_bf16_f32 v113, v118, v119
	v_cvt_pk_bf16_f32 v114, v164, v165
	v_cvt_pk_bf16_f32 v115, v166, v167
	global_store_dwordx4 v[222:223], v[112:115], off offset:256
	s_nop 1
	v_lshlrev_b32_e32 v112, 16, v132
	v_add_f32_e32 v108, v108, v112
	v_and_b32_e32 v112, 0xffff0000, v132
	v_add_f32_e32 v109, v109, v112
	v_cvt_pk_bf16_f32 v108, v108, v109
	v_lshlrev_b32_e32 v109, 16, v133
	v_add_f32_e32 v109, v110, v109
	v_and_b32_e32 v110, 0xffff0000, v133
	v_add_f32_e32 v110, v111, v110
	v_cvt_pk_bf16_f32 v109, v109, v110
	v_lshlrev_b32_e32 v110, 16, v134
	v_add_f32_e32 v104, v104, v110
	v_and_b32_e32 v110, 0xffff0000, v134
	v_add_f32_e32 v105, v105, v110
	v_cvt_pk_bf16_f32 v110, v104, v105
	v_lshlrev_b32_e32 v104, 16, v135
	v_add_f32_e32 v104, v106, v104
	v_and_b32_e32 v105, 0xffff0000, v135
	v_add_f32_e32 v105, v107, v105
	v_cvt_pk_bf16_f32 v111, v104, v105
	v_lshlrev_b32_e32 v104, 16, v148
	v_add_f32_e32 v100, v100, v104
	v_and_b32_e32 v104, 0xffff0000, v148
	v_add_f32_e32 v101, v101, v104
	global_store_dwordx4 v[194:195], v[108:111], off
	v_cvt_pk_bf16_f32 v100, v100, v101
	v_lshlrev_b32_e32 v101, 16, v149
	v_add_f32_e32 v101, v102, v101
	v_and_b32_e32 v102, 0xffff0000, v149
	v_add_f32_e32 v102, v103, v102
	v_cvt_pk_bf16_f32 v101, v101, v102
	v_lshlrev_b32_e32 v102, 16, v150
	v_add_f32_e32 v92, v92, v102
	v_and_b32_e32 v102, 0xffff0000, v150
	v_add_f32_e32 v93, v93, v102
	v_cvt_pk_bf16_f32 v102, v92, v93
	v_lshlrev_b32_e32 v92, 16, v151
	v_and_b32_e32 v93, 0xffff0000, v151
	v_add_f32_e32 v92, v94, v92
	v_add_f32_e32 v93, v95, v93
	v_cvt_pk_bf16_f32 v103, v92, v93
	v_lshl_add_u64 v[92:93], s[28:29], 0, v[220:221]
	global_store_dwordx4 v[194:195], v[100:103], off offset:256
	v_and_b32_e32 v94, 0xffff0000, v189
	v_add_f32_e32 v94, v99, v94
	v_lshl_add_u64 v[100:101], v[92:93], 0, v[208:209]
	v_lshlrev_b32_e32 v92, 16, v188
	v_and_b32_e32 v93, 0xffff0000, v188
	v_add_f32_e32 v92, v96, v92
	v_add_f32_e32 v93, v97, v93
	v_cvt_pk_bf16_f32 v92, v92, v93
	v_lshlrev_b32_e32 v93, 16, v189
	v_add_f32_e32 v93, v98, v93
	v_cvt_pk_bf16_f32 v93, v93, v94
	v_lshlrev_b32_e32 v94, 16, v190
	v_add_f32_e32 v88, v88, v94
	v_and_b32_e32 v94, 0xffff0000, v190
	v_add_f32_e32 v89, v89, v94
	v_cvt_pk_bf16_f32 v94, v88, v89
	v_lshlrev_b32_e32 v88, 16, v191
	v_add_f32_e32 v88, v90, v88
	v_and_b32_e32 v89, 0xffff0000, v191
	v_add_f32_e32 v89, v91, v89
	v_cvt_pk_bf16_f32 v95, v88, v89
	v_lshlrev_b32_e32 v88, 16, v184
	v_add_f32_e32 v84, v84, v88
	v_and_b32_e32 v88, 0xffff0000, v184
	v_add_f32_e32 v85, v85, v88
	global_store_dwordx4 v[100:101], v[92:95], off
	v_cvt_pk_bf16_f32 v84, v84, v85
	v_lshlrev_b32_e32 v85, 16, v185
	v_add_f32_e32 v85, v86, v85
	v_and_b32_e32 v86, 0xffff0000, v185
	v_add_f32_e32 v86, v87, v86
	v_cvt_pk_bf16_f32 v85, v85, v86
	v_lshlrev_b32_e32 v86, 16, v186
	v_add_f32_e32 v76, v76, v86
	v_and_b32_e32 v86, 0xffff0000, v186
	v_add_f32_e32 v77, v77, v86
	v_cvt_pk_bf16_f32 v86, v76, v77
	v_lshlrev_b32_e32 v76, 16, v187
	v_and_b32_e32 v77, 0xffff0000, v187
	v_add_f32_e32 v76, v78, v76
	v_add_f32_e32 v77, v79, v77
	v_cvt_pk_bf16_f32 v87, v76, v77
	v_lshl_add_u64 v[76:77], s[28:29], 0, v[218:219]
	global_store_dwordx4 v[100:101], v[84:87], off offset:256
	v_and_b32_e32 v78, 0xffff0000, v181
	v_add_f32_e32 v78, v83, v78
	v_lshl_add_u64 v[84:85], v[76:77], 0, v[208:209]
	v_lshlrev_b32_e32 v76, 16, v180
	v_and_b32_e32 v77, 0xffff0000, v180
	v_add_f32_e32 v76, v80, v76
	v_add_f32_e32 v77, v81, v77
	v_cvt_pk_bf16_f32 v76, v76, v77
	v_lshlrev_b32_e32 v77, 16, v181
	v_add_f32_e32 v77, v82, v77
	v_cvt_pk_bf16_f32 v77, v77, v78
	v_lshlrev_b32_e32 v78, 16, v182
	v_add_f32_e32 v72, v72, v78
	v_and_b32_e32 v78, 0xffff0000, v182
	v_add_f32_e32 v73, v73, v78
	v_cvt_pk_bf16_f32 v78, v72, v73
	v_lshlrev_b32_e32 v72, 16, v183
	v_add_f32_e32 v72, v74, v72
	v_and_b32_e32 v73, 0xffff0000, v183
	v_add_f32_e32 v73, v75, v73
	v_cvt_pk_bf16_f32 v79, v72, v73
	v_lshlrev_b32_e32 v72, 16, v176
	v_add_f32_e32 v68, v68, v72
	v_and_b32_e32 v72, 0xffff0000, v176
	v_add_f32_e32 v69, v69, v72
	global_store_dwordx4 v[84:85], v[76:79], off
	v_cvt_pk_bf16_f32 v68, v68, v69
	v_lshlrev_b32_e32 v69, 16, v177
	v_add_f32_e32 v69, v70, v69
	v_and_b32_e32 v70, 0xffff0000, v177
	v_add_f32_e32 v70, v71, v70
	v_cvt_pk_bf16_f32 v69, v69, v70
	v_lshlrev_b32_e32 v70, 16, v178
	v_add_f32_e32 v64, v64, v70
; __device__ __forceinline__ unsigned cvt_pk_bf16(float lo, float hi) { unsigned r; asm volatile("v_cvt_pk_bf16_f32 %0, %1, %2" : "=v"(r) : "v"(lo), "v"(hi)); return r; }
; __device__ __forceinline__ float bf_lo(unsigned w) { return __uint_as_float(w << 16); }
; __device__ __forceinline__ float bf_hi(unsigned w) { return __uint_as_float(w & 0xffff0000u); }
; #define PG8_BAR __builtin_amdgcn_s_barrier()
;     __device__ __forceinline__ void operator()(const f32x4 (&acc)[2][2][4][2], const Unit& u, int wr, int wc, int fr, int fq) const {
;     ...
; #pragma unroll
;         for (int ai = 0; ai < 2; ++ai)
; #pragma unroll
;             for (int m = 0; m < 4; ++m) { bf16_t* rowp = H + (size_t)(row0 + ai * HALF + m * 16) * ldc + col0;
;                 float sq = 0.f;
; #pragma unroll
;                 for (int bj = 0; bj < 2; ++bj) { const f32x4 v0 = acc[ai][bj][m][0], v1 = acc[ai][bj][m][1];
;                     const u32x4 o = ov[ai][m][bj]; u32x4 w;
;                     w.x = cvt_pk_bf16(bf_lo(o.x) + v0[0], bf_hi(o.x) + v0[1]); w.y = cvt_pk_bf16(bf_lo(o.y) + v0[2], bf_hi(o.y) + v0[3]);
;                     w.z = cvt_pk_bf16(bf_lo(o.z) + v1[0], bf_hi(o.z) + v1[1]); w.w = cvt_pk_bf16(bf_lo(o.w) + v1[2], bf_hi(o.w) + v1[3]);
;                     if (part) {
; #pragma unroll
;                         for (int e = 0; e < 4; ++e) { const float x = bf_lo(w[e]), y = bf_hi(w[e]); sq += x * x + y * y; } }
;                     if (!dry) *(u32x4*)(rowp + bj * HALF) = w; }
; template <class Epi, class Sched, bool ALIGN_EPI = false, bool SP2 = false>
; __device__ __forceinline__ void gemm_phase(PG8_LAS unsigned char* lds, const Gemm g, const Sched& S, const Epi& E, const int tid_in) {
;     ...
;         if (!has_next) break;
; #pragma unroll
;         for (int a = 0; a < 2; ++a)
; #pragma unroll
;             for (int b = 0; b < 2; ++b)
; #pragma unroll
;                 for (int m = 0; m < 4; ++m)
; #pragma unroll
;                     for (int n = 0; n < 2; ++n) acc[a][b][m][n] = (f32x4){0.f, 0.f, 0.f, 0.f};
;         cur = nxt; cA = nA; cB = nB; ++ui;
;         if constexpr (ALIGN_EPI) { if (wr == 1) PG8_BAR; }
	v_and_b32_e32 v70, 0xffff0000, v178
	v_add_f32_e32 v65, v65, v70
	v_cvt_pk_bf16_f32 v70, v64, v65
	v_lshlrev_b32_e32 v64, 16, v179
	v_add_f32_e32 v64, v66, v64
	v_lshlrev_b32_e32 v66, 16, v168
	v_add_f32_e32 v60, v60, v66
	v_and_b32_e32 v66, 0xffff0000, v168
	v_and_b32_e32 v65, 0xffff0000, v179
	v_add_f32_e32 v61, v61, v66
	v_add_f32_e32 v65, v67, v65
	v_cvt_pk_bf16_f32 v71, v64, v65
	global_store_dwordx4 v[84:85], v[68:71], off offset:256
	v_cvt_pk_bf16_f32 v60, v60, v61
	v_lshlrev_b32_e32 v61, 16, v169
	v_add_f32_e32 v61, v62, v61
	v_and_b32_e32 v62, 0xffff0000, v169
	v_add_f32_e32 v62, v63, v62
	v_cvt_pk_bf16_f32 v61, v61, v62
	v_lshlrev_b32_e32 v62, 16, v170
	v_add_f32_e32 v56, v56, v62
	v_and_b32_e32 v62, 0xffff0000, v170
	v_add_f32_e32 v57, v57, v62
	v_cvt_pk_bf16_f32 v62, v56, v57
	v_lshlrev_b32_e32 v56, 16, v171
	v_add_f32_e32 v56, v58, v56
	v_and_b32_e32 v57, 0xffff0000, v171
	v_add_f32_e32 v57, v59, v57
	v_cvt_pk_bf16_f32 v63, v56, v57
	v_lshlrev_b32_e32 v56, 16, v160
	v_lshl_add_u64 v[64:65], s[28:29], 0, v[216:217]
	v_add_f32_e32 v52, v52, v56
	v_and_b32_e32 v56, 0xffff0000, v160
	v_lshl_add_u64 v[64:65], v[64:65], 0, v[208:209]
	v_add_f32_e32 v53, v53, v56
	global_store_dwordx4 v[64:65], v[60:63], off
	v_cvt_pk_bf16_f32 v52, v52, v53
	v_lshlrev_b32_e32 v53, 16, v161
	v_add_f32_e32 v53, v54, v53
	v_and_b32_e32 v54, 0xffff0000, v161
	v_add_f32_e32 v54, v55, v54
	v_cvt_pk_bf16_f32 v53, v53, v54
	v_lshlrev_b32_e32 v54, 16, v162
	v_add_f32_e32 v44, v44, v54
	v_and_b32_e32 v54, 0xffff0000, v162
	v_add_f32_e32 v45, v45, v54
	v_cvt_pk_bf16_f32 v54, v44, v45
	v_lshlrev_b32_e32 v44, 16, v163
	v_and_b32_e32 v45, 0xffff0000, v163
	v_add_f32_e32 v44, v46, v44
	v_add_f32_e32 v45, v47, v45
	v_cvt_pk_bf16_f32 v55, v44, v45
	v_lshl_add_u64 v[44:45], s[28:29], 0, v[214:215]
	global_store_dwordx4 v[64:65], v[52:55], off offset:256
	v_and_b32_e32 v46, 0xffff0000, v157
	v_add_f32_e32 v46, v51, v46
	v_lshl_add_u64 v[52:53], v[44:45], 0, v[208:209]
	v_lshlrev_b32_e32 v44, 16, v156
	v_and_b32_e32 v45, 0xffff0000, v156
	v_add_f32_e32 v44, v48, v44
	v_add_f32_e32 v45, v49, v45
	v_cvt_pk_bf16_f32 v44, v44, v45
	v_lshlrev_b32_e32 v45, 16, v157
	v_add_f32_e32 v45, v50, v45
	v_cvt_pk_bf16_f32 v45, v45, v46
	v_lshlrev_b32_e32 v46, 16, v158
	v_add_f32_e32 v40, v40, v46
	v_and_b32_e32 v46, 0xffff0000, v158
	v_add_f32_e32 v41, v41, v46
	v_cvt_pk_bf16_f32 v46, v40, v41
	v_lshlrev_b32_e32 v40, 16, v159
	v_add_f32_e32 v40, v42, v40
	v_and_b32_e32 v41, 0xffff0000, v159
	v_add_f32_e32 v41, v43, v41
	v_cvt_pk_bf16_f32 v47, v40, v41
	v_lshlrev_b32_e32 v40, 16, v152
	v_add_f32_e32 v36, v36, v40
	v_and_b32_e32 v40, 0xffff0000, v152
	v_add_f32_e32 v37, v37, v40
	global_store_dwordx4 v[52:53], v[44:47], off
	v_cvt_pk_bf16_f32 v36, v36, v37
	v_lshlrev_b32_e32 v37, 16, v153
	v_add_f32_e32 v37, v38, v37
	v_and_b32_e32 v38, 0xffff0000, v153
	v_add_f32_e32 v38, v39, v38
	v_cvt_pk_bf16_f32 v37, v37, v38
	v_lshlrev_b32_e32 v38, 16, v154
	v_add_f32_e32 v28, v28, v38
	v_and_b32_e32 v38, 0xffff0000, v154
	v_add_f32_e32 v29, v29, v38
	v_cvt_pk_bf16_f32 v38, v28, v29
	v_lshlrev_b32_e32 v28, 16, v155
	v_and_b32_e32 v29, 0xffff0000, v155
	v_add_f32_e32 v28, v30, v28
	v_add_f32_e32 v29, v31, v29
	v_cvt_pk_bf16_f32 v39, v28, v29
	v_lshl_add_u64 v[28:29], s[28:29], 0, v[212:213]
	global_store_dwordx4 v[52:53], v[36:39], off offset:256
	v_and_b32_e32 v30, 0xffff0000, v145
	v_add_f32_e32 v30, v35, v30
	v_lshl_add_u64 v[36:37], v[28:29], 0, v[208:209]
	v_lshlrev_b32_e32 v28, 16, v144
	v_and_b32_e32 v29, 0xffff0000, v144
	v_add_f32_e32 v28, v32, v28
	v_add_f32_e32 v29, v33, v29
	v_cvt_pk_bf16_f32 v28, v28, v29
	v_lshlrev_b32_e32 v29, 16, v145
	v_add_f32_e32 v29, v34, v29
	v_cvt_pk_bf16_f32 v29, v29, v30
	v_lshlrev_b32_e32 v30, 16, v146
	v_add_f32_e32 v24, v24, v30
	v_and_b32_e32 v30, 0xffff0000, v146
	v_add_f32_e32 v25, v25, v30
	v_cvt_pk_bf16_f32 v30, v24, v25
	v_lshlrev_b32_e32 v24, 16, v147
	v_add_f32_e32 v24, v26, v24
	v_and_b32_e32 v25, 0xffff0000, v147
	v_add_f32_e32 v25, v27, v25
	v_cvt_pk_bf16_f32 v31, v24, v25
	v_lshlrev_b32_e32 v24, 16, v140
	v_add_f32_e32 v20, v20, v24
	v_and_b32_e32 v24, 0xffff0000, v140
	v_add_f32_e32 v21, v21, v24
	global_store_dwordx4 v[36:37], v[28:31], off
	v_cvt_pk_bf16_f32 v20, v20, v21
	v_lshlrev_b32_e32 v21, 16, v141
	v_add_f32_e32 v21, v22, v21
	v_and_b32_e32 v22, 0xffff0000, v141
	v_add_f32_e32 v22, v23, v22
	v_cvt_pk_bf16_f32 v21, v21, v22
	v_lshlrev_b32_e32 v22, 16, v142
	v_add_f32_e32 v12, v12, v22
	v_and_b32_e32 v22, 0xffff0000, v142
	v_add_f32_e32 v13, v13, v22
	v_cvt_pk_bf16_f32 v22, v12, v13
	v_lshlrev_b32_e32 v12, 16, v143
	v_and_b32_e32 v13, 0xffff0000, v143
	v_add_f32_e32 v12, v14, v12
	v_add_f32_e32 v13, v15, v13
	v_cvt_pk_bf16_f32 v23, v12, v13
	v_lshl_add_u64 v[12:13], s[28:29], 0, v[210:211]
	global_store_dwordx4 v[36:37], v[20:23], off offset:256
	v_and_b32_e32 v14, 0xffff0000, v137
	v_add_f32_e32 v14, v19, v14
	v_lshl_add_u64 v[20:21], v[12:13], 0, v[208:209]
	v_lshlrev_b32_e32 v12, 16, v136
	v_and_b32_e32 v13, 0xffff0000, v136
	v_add_f32_e32 v12, v16, v12
	v_add_f32_e32 v13, v17, v13
	v_cvt_pk_bf16_f32 v12, v12, v13
	v_lshlrev_b32_e32 v13, 16, v137
	v_add_f32_e32 v13, v18, v13
	v_cvt_pk_bf16_f32 v13, v13, v14
	v_lshlrev_b32_e32 v14, 16, v138
	v_add_f32_e32 v8, v8, v14
	v_and_b32_e32 v14, 0xffff0000, v138
	v_add_f32_e32 v9, v9, v14
	v_cvt_pk_bf16_f32 v14, v8, v9
	v_lshlrev_b32_e32 v8, 16, v139
	v_add_f32_e32 v8, v10, v8
	v_and_b32_e32 v9, 0xffff0000, v139
	v_add_f32_e32 v9, v11, v9
	v_cvt_pk_bf16_f32 v15, v8, v9
	v_lshlrev_b32_e32 v8, 16, v128
	v_add_f32_e32 v4, v4, v8
	v_and_b32_e32 v8, 0xffff0000, v128
	v_add_f32_e32 v5, v5, v8
	global_store_dwordx4 v[20:21], v[12:15], off
	v_cvt_pk_bf16_f32 v4, v4, v5
	v_lshlrev_b32_e32 v5, 16, v129
	v_add_f32_e32 v5, v6, v5
	v_and_b32_e32 v6, 0xffff0000, v129
	v_add_f32_e32 v6, v7, v6
	v_cvt_pk_bf16_f32 v5, v5, v6
	v_lshlrev_b32_e32 v6, 16, v130
	v_add_f32_e32 v0, v0, v6
	v_and_b32_e32 v6, 0xffff0000, v130
	v_add_f32_e32 v1, v1, v6
	v_cvt_pk_bf16_f32 v6, v0, v1
	v_lshlrev_b32_e32 v0, 16, v131
	v_and_b32_e32 v1, 0xffff0000, v131
	v_add_f32_e32 v0, v2, v0
	v_add_f32_e32 v1, v3, v1
	v_cvt_pk_bf16_f32 v7, v0, v1
	global_store_dwordx4 v[20:21], v[4:7], off offset:256
	s_cbranch_vccnz .LBB0_733
	s_andn2_b64 vcc, exec, s[22:23]
	s_cbranch_vccnz .LBB0_732
	s_branch .LBB0_732

; #define PG8_STAGE(bufoff, gbase, voff) do { _Pragma("unroll") for (int _i = 0; _i < 2; ++_i) \
;         __builtin_amdgcn_global_load_lds((const unsigned*)((const char*)(gbase) + (voff)[_i]), (PG8_LAS unsigned*)(lds + (bufoff) + ldsw + _i * 8192), 16, 0, 0); } while (0)
; #define PG8_LDA(dst, b, h) do { _Pragma("unroll") for (int m = 0; m < 4; ++m) _Pragma("unroll") for (int k = 0; k < 2; ++k) dst[m][k] = *(const PG8_LAS bf16x8*)(lds + PG8_SA(b, h) + aoff + m * 2048 + k * 1024); } while (0)
; #define PG8_LDB(dst, b, h) do { _Pragma("unroll") for (int n = 0; n < 2; ++n) _Pragma("unroll") for (int k = 0; k < 2; ++k) dst[n][k] = *(const PG8_LAS bf16x8*)(lds + PG8_SB(b, h) + boff + n * 2048 + k * 1024); } while (0)
; #define PG8_MMA(ai, bj, At, Bt) do { __builtin_amdgcn_s_setprio(1); _Pragma("unroll") for (int m = 0; m < 4; ++m) _Pragma("unroll") for (int n = 0; n < 2; ++n) _Pragma("unroll") for (int k = 0; k < 2; ++k) \
;         acc[ai][bj][m][n] = __builtin_amdgcn_mfma_f32_16x16x32_bf16(Bt[n][k], At[m][k], acc[ai][bj][m][n], 0, 0, 0); __builtin_amdgcn_s_setprio(0); } while (0)
; #define PG8_WAIT_V(n) asm volatile("s_waitcnt vmcnt(" #n ")" ::: "memory")
; #define PG8_WAIT_L(n) asm volatile("s_waitcnt lgkmcnt(" #n ")" ::: "memory")
; #define PG8_BAR __builtin_amdgcn_s_barrier()
; template <class Epi, class Sched, bool ALIGN_EPI = false, bool SP2 = false>
; __device__ __forceinline__ void gemm_phase(PG8_LAS unsigned char* lds, const Gemm g, const Sched& S, const Epi& E, const int tid_in) {
;     ...
;         for (int t = 0; t < nt; t += 2) {
;             const bool last = (t == nt - 2);
;             const char* a1 = cA + (size_t)(t + 1) * kstep;
;             const char* a2 = last ? nA : cA + (size_t)(t + 2) * kstep; const char* b2 = last ? nB : cB + (size_t)(t + 2) * kstep;
;             const char* a3 = a2 + kstep; const char* b3 = b2 + kstep;
;             if (last && has_next) S.a_ready(nxt);
;             if constexpr (SP2) {
;             PG8_LDB(B0, 0, 0); PG8_LDB(B1, 0, 1); PG8_SCHED; PG8_LDA(At, 0, 0); PG8_STAGE(PG8_SA(1, 1), a1 + hstepA, voffA);
;             PG8_WAIT_V(8); PG8_WAIT_L(0); PG8_BAR; PG8_MMA(0, 0, At, B0); PG8_MMA(0, 1, At, B1); PG8_BAR; PG8_SCHED;
;             PG8_LDA(At, 0, 1); PG8_STAGE(PG8_SB(0, 0), b2, voffB); PG8_STAGE(PG8_SB(0, 1), b2 + hstepB, voffB); PG8_STAGE(PG8_SA(0, 0), a2, voffA);
.LBB0_815:
	s_add_u32 s12, s52, 0xfff80080
	s_addc_u32 s13, s53, -1
	s_add_i32 s79, 0, 0x10000
	s_cmp_eq_u32 s78, 28
	s_cselect_b32 s57, s23, s13
	s_cselect_b32 s56, s31, s12
	s_cselect_b32 s55, s45, s77
	s_cselect_b32 s54, s47, s76
	s_add_i32 s80, 0, 0x14000
	v_add_u32_e32 v140, s79, v174
	v_add_u32_e32 v161, s80, v174
	ds_read_b128 v[128:131], v140
	ds_read_b128 v[132:135], v140 offset:1024
	ds_read_b128 v[136:139], v140 offset:2048
	ds_read_b128 v[140:143], v140 offset:3072
	ds_read_b128 v[162:165], v161
	ds_read_b128 v[166:169], v161 offset:1024
	ds_read_b128 v[178:181], v161 offset:2048
	ds_read_b128 v[182:185], v161 offset:3072
	v_lshl_add_u64 v[170:171], s[52:53], 0, v[156:157]
	s_add_i32 m0, s65, 0xc000
	ds_read_b128 v[186:189], v176
	ds_read_b128 v[198:201], v176 offset:1024
	ds_read_b128 v[202:205], v176 offset:2048
	ds_read_b128 v[206:209], v176 offset:3072
	ds_read_b128 v[210:213], v176 offset:4096
	ds_read_b128 v[214:217], v176 offset:5120
	ds_read_b128 v[218:221], v176 offset:6144
	ds_read_b128 v[222:225], v176 offset:7168
	global_load_lds_dwordx4 v[170:171], off
	v_lshl_add_u64 v[170:171], s[52:53], 0, v[158:159]
	s_add_i32 m0, s65, 0xe000
	s_nop 0
	global_load_lds_dwordx4 v[170:171], off
	s_waitcnt vmcnt(8)
	s_waitcnt lgkmcnt(0)
	s_barrier
	s_setprio 1
	s_waitcnt lgkmcnt(0)
	v_mfma_f32_16x16x32_bf16 v[124:127], v[128:131], v[186:189], v[124:127]
	v_mfma_f32_16x16x32_bf16 v[120:123], v[136:139], v[186:189], v[120:123]
	v_mfma_f32_16x16x32_bf16 v[116:119], v[128:131], v[202:205], v[116:119]
	v_mfma_f32_16x16x32_bf16 v[112:115], v[136:139], v[202:205], v[112:115]
	v_mfma_f32_16x16x32_bf16 v[108:111], v[128:131], v[210:213], v[108:111]
	v_mfma_f32_16x16x32_bf16 v[100:103], v[136:139], v[210:213], v[100:103]
	v_mfma_f32_16x16x32_bf16 v[92:95], v[128:131], v[218:221], v[92:95]
	v_mfma_f32_16x16x32_bf16 v[80:83], v[136:139], v[218:221], v[80:83]
	v_mfma_f32_16x16x32_bf16 v[124:127], v[132:135], v[198:201], v[124:127]
	v_mfma_f32_16x16x32_bf16 v[120:123], v[140:143], v[198:201], v[120:123]
	v_mfma_f32_16x16x32_bf16 v[116:119], v[132:135], v[206:209], v[116:119]
	v_mfma_f32_16x16x32_bf16 v[112:115], v[140:143], v[206:209], v[112:115]
	v_mfma_f32_16x16x32_bf16 v[108:111], v[132:135], v[214:217], v[108:111]
	v_mfma_f32_16x16x32_bf16 v[100:103], v[140:143], v[214:217], v[100:103]
	v_mfma_f32_16x16x32_bf16 v[92:95], v[132:135], v[222:225], v[92:95]
	v_mfma_f32_16x16x32_bf16 v[80:83], v[140:143], v[222:225], v[80:83]
	v_mfma_f32_16x16x32_bf16 v[104:107], v[162:165], v[186:189], v[104:107]
	v_mfma_f32_16x16x32_bf16 v[96:99], v[178:181], v[186:189], v[96:99]
	v_mfma_f32_16x16x32_bf16 v[88:91], v[162:165], v[202:205], v[88:91]
	v_mfma_f32_16x16x32_bf16 v[84:87], v[178:181], v[202:205], v[84:87]
	v_mfma_f32_16x16x32_bf16 v[76:79], v[162:165], v[210:213], v[76:79]
	v_mfma_f32_16x16x32_bf16 v[72:75], v[178:181], v[210:213], v[72:75]
	v_mfma_f32_16x16x32_bf16 v[68:71], v[162:165], v[218:221], v[68:71]
	v_mfma_f32_16x16x32_bf16 v[64:67], v[178:181], v[218:221], v[64:67]
	v_mfma_f32_16x16x32_bf16 v[104:107], v[166:169], v[198:201], v[104:107]
	v_mfma_f32_16x16x32_bf16 v[96:99], v[182:185], v[198:201], v[96:99]
	v_mfma_f32_16x16x32_bf16 v[88:91], v[166:169], v[206:209], v[88:91]
	v_mfma_f32_16x16x32_bf16 v[84:87], v[182:185], v[206:209], v[84:87]
	v_mfma_f32_16x16x32_bf16 v[76:79], v[166:169], v[214:217], v[76:79]
	v_mfma_f32_16x16x32_bf16 v[72:75], v[182:185], v[214:217], v[72:75]
	v_mfma_f32_16x16x32_bf16 v[68:71], v[166:169], v[222:225], v[68:71]
	v_mfma_f32_16x16x32_bf16 v[64:67], v[182:185], v[222:225], v[64:67]
	s_setprio 0
	s_barrier
	s_add_i32 s12, s79, s64
	v_lshl_add_u64 v[170:171], s[54:55], 0, v[146:147]
	s_mov_b32 m0, s12
	ds_read_b128 v[186:189], v176 offset:16384
	ds_read_b128 v[198:201], v176 offset:17408
	ds_read_b128 v[202:205], v176 offset:18432
	ds_read_b128 v[206:209], v176 offset:19456
	ds_read_b128 v[210:213], v176 offset:20480
	ds_read_b128 v[214:217], v176 offset:21504
	ds_read_b128 v[218:221], v176 offset:22528
	ds_read_b128 v[222:225], v176 offset:23552
	global_load_lds_dwordx4 v[170:171], off
	s_add_i32 m0, s12, 0x2000
	s_add_u32 s12, s54, 0x80000
	v_lshl_add_u64 v[190:191], s[54:55], 0, v[150:151]
	s_addc_u32 s13, s55, 0
	s_add_i32 s79, s80, s64
	global_load_lds_dwordx4 v[190:191], off
	v_lshl_add_u64 v[194:195], s[12:13], 0, v[146:147]
	s_mov_b32 m0, s79
	v_lshl_add_u64 v[196:197], s[56:57], 0, v[148:149]
	global_load_lds_dwordx4 v[194:195], off
	v_lshl_add_u64 v[194:195], s[12:13], 0, v[150:151]
	s_add_i32 m0, s79, 0x2000
	s_nop 0
	global_load_lds_dwordx4 v[194:195], off
	v_lshl_add_u64 v[194:195], s[56:57], 0, v[144:145]
	s_mov_b32 m0, s65
	s_nop 0
	global_load_lds_dwordx4 v[194:195], off
	s_mov_b32 m0, s66
	s_nop 0
	global_load_lds_dwordx4 v[196:197], off
	s_waitcnt vmcnt(8)
	s_waitcnt lgkmcnt(0)
	s_barrier
; #define PG8_STAGE(bufoff, gbase, voff) do { _Pragma("unroll") for (int _i = 0; _i < 2; ++_i) \
;         __builtin_amdgcn_global_load_lds((const unsigned*)((const char*)(gbase) + (voff)[_i]), (PG8_LAS unsigned*)(lds + (bufoff) + ldsw + _i * 8192), 16, 0, 0); } while (0)
; #define PG8_LDA(dst, b, h) do { _Pragma("unroll") for (int m = 0; m < 4; ++m) _Pragma("unroll") for (int k = 0; k < 2; ++k) dst[m][k] = *(const PG8_LAS bf16x8*)(lds + PG8_SA(b, h) + aoff + m * 2048 + k * 1024); } while (0)
; #define PG8_LDB(dst, b, h) do { _Pragma("unroll") for (int n = 0; n < 2; ++n) _Pragma("unroll") for (int k = 0; k < 2; ++k) dst[n][k] = *(const PG8_LAS bf16x8*)(lds + PG8_SB(b, h) + boff + n * 2048 + k * 1024); } while (0)
; #define PG8_MMA(ai, bj, At, Bt) do { __builtin_amdgcn_s_setprio(1); _Pragma("unroll") for (int m = 0; m < 4; ++m) _Pragma("unroll") for (int n = 0; n < 2; ++n) _Pragma("unroll") for (int k = 0; k < 2; ++k) \
;         acc[ai][bj][m][n] = __builtin_amdgcn_mfma_f32_16x16x32_bf16(Bt[n][k], At[m][k], acc[ai][bj][m][n], 0, 0, 0); __builtin_amdgcn_s_setprio(0); } while (0)
; #define PG8_WAIT_V(n) asm volatile("s_waitcnt vmcnt(" #n ")" ::: "memory")
; #define PG8_WAIT_L(n) asm volatile("s_waitcnt lgkmcnt(" #n ")" ::: "memory")
; #define PG8_BAR __builtin_amdgcn_s_barrier()
; #define PG8_SCHED __builtin_amdgcn_sched_barrier(0)
; template <class Epi, class Sched, bool ALIGN_EPI = false, bool SP2 = false>
; __device__ __forceinline__ void gemm_phase(PG8_LAS unsigned char* lds, const Gemm g, const Sched& S, const Epi& E, const int tid_in) {
;     ...
;             PG8_WAIT_V(8); PG8_WAIT_L(0); PG8_BAR; PG8_MMA(1, 0, At, B0); PG8_MMA(1, 1, At, B1); PG8_BAR; PG8_SCHED;
;             PG8_LDB(B0, 1, 0); PG8_LDB(B1, 1, 1); PG8_SCHED; PG8_LDA(At, 1, 0); PG8_STAGE(PG8_SA(0, 1), a2 + hstepA, voffA);
;             PG8_WAIT_V(8); PG8_WAIT_L(0); PG8_BAR; PG8_MMA(0, 0, At, B0); PG8_MMA(0, 1, At, B1); PG8_BAR; PG8_SCHED;
	s_setprio 1
	s_waitcnt lgkmcnt(0)
	v_mfma_f32_16x16x32_bf16 v[60:63], v[128:131], v[186:189], v[60:63]
	v_mfma_f32_16x16x32_bf16 v[56:59], v[136:139], v[186:189], v[56:59]
	v_mfma_f32_16x16x32_bf16 v[48:51], v[128:131], v[202:205], v[48:51]
	v_mfma_f32_16x16x32_bf16 v[40:43], v[136:139], v[202:205], v[40:43]
	v_mfma_f32_16x16x32_bf16 v[32:35], v[128:131], v[210:213], v[32:35]
	v_mfma_f32_16x16x32_bf16 v[24:27], v[136:139], v[210:213], v[24:27]
	v_mfma_f32_16x16x32_bf16 v[16:19], v[128:131], v[218:221], v[16:19]
	v_mfma_f32_16x16x32_bf16 v[8:11], v[136:139], v[218:221], v[8:11]
	v_mfma_f32_16x16x32_bf16 v[60:63], v[132:135], v[198:201], v[60:63]
	v_mfma_f32_16x16x32_bf16 v[56:59], v[140:143], v[198:201], v[56:59]
	v_mfma_f32_16x16x32_bf16 v[48:51], v[132:135], v[206:209], v[48:51]
	v_mfma_f32_16x16x32_bf16 v[40:43], v[140:143], v[206:209], v[40:43]
	v_mfma_f32_16x16x32_bf16 v[32:35], v[132:135], v[214:217], v[32:35]
	v_mfma_f32_16x16x32_bf16 v[24:27], v[140:143], v[214:217], v[24:27]
	v_mfma_f32_16x16x32_bf16 v[16:19], v[132:135], v[222:225], v[16:19]
	v_mfma_f32_16x16x32_bf16 v[8:11], v[140:143], v[222:225], v[8:11]
	v_mfma_f32_16x16x32_bf16 v[52:55], v[162:165], v[186:189], v[52:55]
	v_mfma_f32_16x16x32_bf16 v[44:47], v[178:181], v[186:189], v[44:47]
	v_mfma_f32_16x16x32_bf16 v[36:39], v[162:165], v[202:205], v[36:39]
	v_mfma_f32_16x16x32_bf16 v[28:31], v[178:181], v[202:205], v[28:31]
	v_mfma_f32_16x16x32_bf16 v[20:23], v[162:165], v[210:213], v[20:23]
	v_mfma_f32_16x16x32_bf16 v[12:15], v[178:181], v[210:213], v[12:15]
	v_mfma_f32_16x16x32_bf16 v[4:7], v[162:165], v[218:221], v[4:7]
	v_mfma_f32_16x16x32_bf16 v[0:3], v[178:181], v[218:221], v[0:3]
	v_mfma_f32_16x16x32_bf16 v[52:55], v[166:169], v[198:201], v[52:55]
	v_mfma_f32_16x16x32_bf16 v[44:47], v[182:185], v[198:201], v[44:47]
	v_mfma_f32_16x16x32_bf16 v[36:39], v[166:169], v[206:209], v[36:39]
	v_mfma_f32_16x16x32_bf16 v[28:31], v[182:185], v[206:209], v[28:31]
	v_mfma_f32_16x16x32_bf16 v[20:23], v[166:169], v[214:217], v[20:23]
	v_mfma_f32_16x16x32_bf16 v[12:15], v[182:185], v[214:217], v[12:15]
	v_mfma_f32_16x16x32_bf16 v[4:7], v[166:169], v[222:225], v[4:7]
	v_mfma_f32_16x16x32_bf16 v[0:3], v[182:185], v[222:225], v[0:3]
	s_setprio 0
	s_barrier
	s_add_i32 s79, 0, 0x18000
	s_add_i32 s80, 0, 0x1c000
	v_add_u32_e32 v140, s79, v174
	v_add_u32_e32 v161, s80, v174
	ds_read_b128 v[128:131], v140
	ds_read_b128 v[132:135], v140 offset:1024
	ds_read_b128 v[136:139], v140 offset:2048
	ds_read_b128 v[140:143], v140 offset:3072
	ds_read_b128 v[162:165], v161
	ds_read_b128 v[166:169], v161 offset:1024
	ds_read_b128 v[178:181], v161 offset:2048
	ds_read_b128 v[182:185], v161 offset:3072
	s_add_u32 s12, s56, 0x80000
	s_addc_u32 s13, s57, 0
	s_mov_b32 m0, s67
	v_lshl_add_u64 v[226:227], s[12:13], 0, v[144:145]
	ds_read_b128 v[186:189], v176 offset:32768
	ds_read_b128 v[198:201], v176 offset:33792
	ds_read_b128 v[202:205], v176 offset:34816
	ds_read_b128 v[206:209], v176 offset:35840
	ds_read_b128 v[210:213], v176 offset:36864
	ds_read_b128 v[214:217], v176 offset:37888
	ds_read_b128 v[218:221], v176 offset:38912
	ds_read_b128 v[222:225], v176 offset:39936
	global_load_lds_dwordx4 v[226:227], off
	v_lshl_add_u64 v[226:227], s[12:13], 0, v[148:149]
	s_mov_b32 m0, s68
	s_nop 0
	global_load_lds_dwordx4 v[226:227], off
	s_waitcnt vmcnt(8)
	s_waitcnt lgkmcnt(0)
	s_barrier
	s_setprio 1
	s_waitcnt lgkmcnt(0)
	v_mfma_f32_16x16x32_bf16 v[124:127], v[128:131], v[186:189], v[124:127]
	v_mfma_f32_16x16x32_bf16 v[120:123], v[136:139], v[186:189], v[120:123]
	v_mfma_f32_16x16x32_bf16 v[116:119], v[128:131], v[202:205], v[116:119]
	v_mfma_f32_16x16x32_bf16 v[112:115], v[136:139], v[202:205], v[112:115]
	v_mfma_f32_16x16x32_bf16 v[108:111], v[128:131], v[210:213], v[108:111]
	v_mfma_f32_16x16x32_bf16 v[100:103], v[136:139], v[210:213], v[100:103]
	v_mfma_f32_16x16x32_bf16 v[92:95], v[128:131], v[218:221], v[92:95]
	v_mfma_f32_16x16x32_bf16 v[80:83], v[136:139], v[218:221], v[80:83]
	v_mfma_f32_16x16x32_bf16 v[124:127], v[132:135], v[198:201], v[124:127]
	v_mfma_f32_16x16x32_bf16 v[120:123], v[140:143], v[198:201], v[120:123]
	v_mfma_f32_16x16x32_bf16 v[116:119], v[132:135], v[206:209], v[116:119]
	v_mfma_f32_16x16x32_bf16 v[112:115], v[140:143], v[206:209], v[112:115]
	v_mfma_f32_16x16x32_bf16 v[108:111], v[132:135], v[214:217], v[108:111]
	v_mfma_f32_16x16x32_bf16 v[100:103], v[140:143], v[214:217], v[100:103]
	v_mfma_f32_16x16x32_bf16 v[92:95], v[132:135], v[222:225], v[92:95]
	v_mfma_f32_16x16x32_bf16 v[80:83], v[140:143], v[222:225], v[80:83]
	v_mfma_f32_16x16x32_bf16 v[104:107], v[162:165], v[186:189], v[104:107]
	v_mfma_f32_16x16x32_bf16 v[96:99], v[178:181], v[186:189], v[96:99]
	v_mfma_f32_16x16x32_bf16 v[88:91], v[162:165], v[202:205], v[88:91]
	v_mfma_f32_16x16x32_bf16 v[84:87], v[178:181], v[202:205], v[84:87]
	v_mfma_f32_16x16x32_bf16 v[76:79], v[162:165], v[210:213], v[76:79]
	v_mfma_f32_16x16x32_bf16 v[72:75], v[178:181], v[210:213], v[72:75]
	v_mfma_f32_16x16x32_bf16 v[68:71], v[162:165], v[218:221], v[68:71]
	v_mfma_f32_16x16x32_bf16 v[64:67], v[178:181], v[218:221], v[64:67]
	v_mfma_f32_16x16x32_bf16 v[104:107], v[166:169], v[198:201], v[104:107]
	v_mfma_f32_16x16x32_bf16 v[96:99], v[182:185], v[198:201], v[96:99]
	v_mfma_f32_16x16x32_bf16 v[88:91], v[166:169], v[206:209], v[88:91]
	v_mfma_f32_16x16x32_bf16 v[84:87], v[182:185], v[206:209], v[84:87]
	v_mfma_f32_16x16x32_bf16 v[76:79], v[166:169], v[214:217], v[76:79]
	v_mfma_f32_16x16x32_bf16 v[72:75], v[182:185], v[214:217], v[72:75]
	v_mfma_f32_16x16x32_bf16 v[68:71], v[166:169], v[222:225], v[68:71]
	v_mfma_f32_16x16x32_bf16 v[64:67], v[182:185], v[222:225], v[64:67]
	s_setprio 0
	s_barrier
; #define PG8_STAGE(bufoff, gbase, voff) do { _Pragma("unroll") for (int _i = 0; _i < 2; ++_i) \
;         __builtin_amdgcn_global_load_lds((const unsigned*)((const char*)(gbase) + (voff)[_i]), (PG8_LAS unsigned*)(lds + (bufoff) + ldsw + _i * 8192), 16, 0, 0); } while (0)
; #define PG8_LDA(dst, b, h) do { _Pragma("unroll") for (int m = 0; m < 4; ++m) _Pragma("unroll") for (int k = 0; k < 2; ++k) dst[m][k] = *(const PG8_LAS bf16x8*)(lds + PG8_SA(b, h) + aoff + m * 2048 + k * 1024); } while (0)
; #define PG8_BAR __builtin_amdgcn_s_barrier()
; template <class Epi, class Sched, bool ALIGN_EPI = false, bool SP2 = false>
; __device__ __forceinline__ void gemm_phase(PG8_LAS unsigned char* lds, const Gemm g, const Sched& S, const Epi& E, const int tid_in) {
;     ...
;             PG8_LDA(At, 1, 1); PG8_STAGE(PG8_SB(1, 0), b3, voffB); PG8_STAGE(PG8_SB(1, 1), b3 + hstepB, voffB); PG8_STAGE(PG8_SA(1, 0), a3, voffA);
;             PG8_WAIT_V(8); PG8_WAIT_L(0); PG8_BAR; PG8_MMA(1, 0, At, B0); PG8_MMA(1, 1, At, B1); PG8_BAR; PG8_SCHED;
;             } else {
;             PG8_LDB(B0, 0, 0); PG8_SCHED; PG8_LDA(At, 0, 0); PG8_STAGE(PG8_SA(1, 1), a1 + hstepA, voffA);
;             PG8_WAIT_L(8); PG8_BAR; PG8_WAIT_L(0); PG8_MMA(0, 0, At, B0); PG8_BAR; PG8_SCHED;
;             PG8_LDB(B1, 0, 1); PG8_STAGE(PG8_SB(0, 0), b2, voffB);
;             PG8_BAR; PG8_WAIT_L(0); PG8_MMA(0, 1, At, B1); PG8_BAR;
;             PG8_LDA(At, 0, 1); PG8_STAGE(PG8_SA(0, 0), a2, voffA);
;             PG8_BAR; PG8_WAIT_L(0); PG8_MMA(1, 0, At, B0); PG8_BAR; PG8_SCHED;
;             PG8_STAGE(PG8_SB(0, 1), b2 + hstepB, voffB);
;             PG8_WAIT_V(6); PG8_BAR; PG8_MMA(1, 1, At, B1); PG8_BAR;
;             PG8_LDB(B0, 1, 0); PG8_SCHED; PG8_LDA(At, 1, 0); PG8_STAGE(PG8_SA(0, 1), a2 + hstepA, voffA);
;             PG8_WAIT_L(8); PG8_BAR; PG8_WAIT_L(0); PG8_MMA(0, 0, At, B0); PG8_BAR; PG8_SCHED;
;             PG8_LDB(B1, 1, 1); PG8_STAGE(PG8_SB(1, 0), b3, voffB);
;             PG8_BAR; PG8_WAIT_L(0); PG8_MMA(0, 1, At, B1); PG8_BAR;
;             PG8_LDA(At, 1, 1); PG8_STAGE(PG8_SA(1, 0), a3, voffA);
;             PG8_BAR; PG8_WAIT_L(0); PG8_MMA(1, 0, At, B0); PG8_BAR; PG8_SCHED;
;             PG8_STAGE(PG8_SB(1, 1), b3 + hstepB, voffB);
;             PG8_WAIT_V(6); PG8_BAR; PG8_MMA(1, 1, At, B1); PG8_BAR;
;             }
;         }
;         if constexpr (ALIGN_EPI) { if (wr == 0) PG8_BAR; }
	s_add_i32 s12, s79, s64
	v_lshl_add_u64 v[170:171], v[170:171], 0, s[26:27]
	s_mov_b32 m0, s12
	ds_read_b128 v[186:189], v176 offset:49152
	ds_read_b128 v[198:201], v176 offset:50176
	ds_read_b128 v[202:205], v176 offset:51200
	ds_read_b128 v[206:209], v176 offset:52224
	ds_read_b128 v[210:213], v176 offset:53248
	ds_read_b128 v[214:217], v176 offset:54272
	ds_read_b128 v[218:221], v176 offset:55296
	ds_read_b128 v[222:225], v176 offset:56320
	global_load_lds_dwordx4 v[170:171], off
	s_add_i32 m0, s12, 0x2000
	s_add_u32 s12, s54, 0x80080
	v_lshl_add_u64 v[170:171], v[190:191], 0, s[26:27]
	s_addc_u32 s13, s55, 0
	s_add_i32 s54, s80, s64
	global_load_lds_dwordx4 v[170:171], off
	v_lshl_add_u64 v[170:171], s[12:13], 0, v[146:147]
	s_mov_b32 m0, s54
	s_nop 0
	global_load_lds_dwordx4 v[170:171], off
	v_lshl_add_u64 v[170:171], s[12:13], 0, v[150:151]
	s_add_i32 m0, s54, 0x2000
	s_nop 0
	global_load_lds_dwordx4 v[170:171], off
	v_lshl_add_u64 v[170:171], v[194:195], 0, s[26:27]
	s_mov_b32 m0, s73
	s_nop 0
	global_load_lds_dwordx4 v[170:171], off
	v_lshl_add_u64 v[170:171], v[196:197], 0, s[26:27]
	s_mov_b32 m0, s74
	s_nop 0
	global_load_lds_dwordx4 v[170:171], off
	s_waitcnt vmcnt(8)
	s_waitcnt lgkmcnt(0)
	s_barrier
	s_setprio 1
	s_waitcnt lgkmcnt(0)
	v_mfma_f32_16x16x32_bf16 v[60:63], v[128:131], v[186:189], v[60:63]
	v_mfma_f32_16x16x32_bf16 v[56:59], v[136:139], v[186:189], v[56:59]
	v_mfma_f32_16x16x32_bf16 v[48:51], v[128:131], v[202:205], v[48:51]
	v_mfma_f32_16x16x32_bf16 v[40:43], v[136:139], v[202:205], v[40:43]
	v_mfma_f32_16x16x32_bf16 v[32:35], v[128:131], v[210:213], v[32:35]
	v_mfma_f32_16x16x32_bf16 v[24:27], v[136:139], v[210:213], v[24:27]
	v_mfma_f32_16x16x32_bf16 v[16:19], v[128:131], v[218:221], v[16:19]
	v_mfma_f32_16x16x32_bf16 v[8:11], v[136:139], v[218:221], v[8:11]
	v_mfma_f32_16x16x32_bf16 v[60:63], v[132:135], v[198:201], v[60:63]
	v_mfma_f32_16x16x32_bf16 v[56:59], v[140:143], v[198:201], v[56:59]
	v_mfma_f32_16x16x32_bf16 v[48:51], v[132:135], v[206:209], v[48:51]
	v_mfma_f32_16x16x32_bf16 v[40:43], v[140:143], v[206:209], v[40:43]
	v_mfma_f32_16x16x32_bf16 v[32:35], v[132:135], v[214:217], v[32:35]
	v_mfma_f32_16x16x32_bf16 v[24:27], v[140:143], v[214:217], v[24:27]
	v_mfma_f32_16x16x32_bf16 v[16:19], v[132:135], v[222:225], v[16:19]
	v_mfma_f32_16x16x32_bf16 v[8:11], v[140:143], v[222:225], v[8:11]
	v_mfma_f32_16x16x32_bf16 v[52:55], v[162:165], v[186:189], v[52:55]
	v_mfma_f32_16x16x32_bf16 v[44:47], v[178:181], v[186:189], v[44:47]
	v_mfma_f32_16x16x32_bf16 v[36:39], v[162:165], v[202:205], v[36:39]
	v_mfma_f32_16x16x32_bf16 v[28:31], v[178:181], v[202:205], v[28:31]
	v_mfma_f32_16x16x32_bf16 v[20:23], v[162:165], v[210:213], v[20:23]
	v_mfma_f32_16x16x32_bf16 v[12:15], v[178:181], v[210:213], v[12:15]
	v_mfma_f32_16x16x32_bf16 v[4:7], v[162:165], v[218:221], v[4:7]
	v_mfma_f32_16x16x32_bf16 v[0:3], v[178:181], v[218:221], v[0:3]
	v_mfma_f32_16x16x32_bf16 v[52:55], v[166:169], v[198:201], v[52:55]
	v_mfma_f32_16x16x32_bf16 v[44:47], v[182:185], v[198:201], v[44:47]
	v_mfma_f32_16x16x32_bf16 v[36:39], v[166:169], v[206:209], v[36:39]
	v_mfma_f32_16x16x32_bf16 v[28:31], v[182:185], v[206:209], v[28:31]
	v_mfma_f32_16x16x32_bf16 v[20:23], v[166:169], v[214:217], v[20:23]
	v_mfma_f32_16x16x32_bf16 v[12:15], v[182:185], v[214:217], v[12:15]
	v_mfma_f32_16x16x32_bf16 v[4:7], v[166:169], v[222:225], v[4:7]
	v_mfma_f32_16x16x32_bf16 v[0:3], v[182:185], v[222:225], v[0:3]
	s_setprio 0
	s_barrier
	s_add_i32 s78, s78, 2
	s_add_u32 s52, s52, 0x100
	s_addc_u32 s53, s53, 0
	s_add_u32 s76, s76, 0x100
	s_addc_u32 s77, s77, 0
	s_cmp_gt_u32 s78, 29
	s_cbranch_scc0 .LBB0_815
	s_andn2_b64 vcc, s[42:43], s[34:35]
	s_cbranch_vccz .LBB0_818
	s_barrier

; #define PG8_BAR __builtin_amdgcn_s_barrier()
; template <class Epi, class Sched, bool ALIGN_EPI = false, bool SP2 = false>
; __device__ __forceinline__ void gemm_phase(PG8_LAS unsigned char* lds, const Gemm g, const Sched& S, const Epi& E, const int tid_in) {
;     ...
;         if (!has_next) break;
; #pragma unroll
;         for (int a = 0; a < 2; ++a)
; #pragma unroll
;             for (int b = 0; b < 2; ++b)
; #pragma unroll
;                 for (int m = 0; m < 4; ++m)
; #pragma unroll
;                     for (int n = 0; n < 2; ++n) acc[a][b][m][n] = (f32x4){0.f, 0.f, 0.f, 0.f};
;         cur = nxt; cA = nA; cB = nB; ++ui;
;         if constexpr (ALIGN_EPI) { if (wr == 1) PG8_BAR; }
.LBB0_855:
	s_andn2_b64 vcc, exec, s[36:37]
	s_cbranch_vccnz .LBB0_810
	s_branch .LBB0_810

; #define PG8_STAGE(bufoff, gbase, voff) do { _Pragma("unroll") for (int _i = 0; _i < 2; ++_i) \
;         __builtin_amdgcn_global_load_lds((const unsigned*)((const char*)(gbase) + (voff)[_i]), (PG8_LAS unsigned*)(lds + (bufoff) + ldsw + _i * 8192), 16, 0, 0); } while (0)
; #define PG8_LDA(dst, b, h) do { _Pragma("unroll") for (int m = 0; m < 4; ++m) _Pragma("unroll") for (int k = 0; k < 2; ++k) dst[m][k] = *(const PG8_LAS bf16x8*)(lds + PG8_SA(b, h) + aoff + m * 2048 + k * 1024); } while (0)
; #define PG8_LDB(dst, b, h) do { _Pragma("unroll") for (int n = 0; n < 2; ++n) _Pragma("unroll") for (int k = 0; k < 2; ++k) dst[n][k] = *(const PG8_LAS bf16x8*)(lds + PG8_SB(b, h) + boff + n * 2048 + k * 1024); } while (0)
; #define PG8_MMA(ai, bj, At, Bt) do { __builtin_amdgcn_s_setprio(1); _Pragma("unroll") for (int m = 0; m < 4; ++m) _Pragma("unroll") for (int n = 0; n < 2; ++n) _Pragma("unroll") for (int k = 0; k < 2; ++k) \
;         acc[ai][bj][m][n] = __builtin_amdgcn_mfma_f32_16x16x32_bf16(Bt[n][k], At[m][k], acc[ai][bj][m][n], 0, 0, 0); __builtin_amdgcn_s_setprio(0); } while (0)
; #define PG8_WAIT_V(n) asm volatile("s_waitcnt vmcnt(" #n ")" ::: "memory")
; #define PG8_WAIT_L(n) asm volatile("s_waitcnt lgkmcnt(" #n ")" ::: "memory")
; #define PG8_BAR __builtin_amdgcn_s_barrier()
; template <class Epi, class Sched, bool ALIGN_EPI = false, bool SP2 = false>
; __device__ __forceinline__ void gemm_phase(PG8_LAS unsigned char* lds, const Gemm g, const Sched& S, const Epi& E, const int tid_in) {
;     ...
;         for (int t = 0; t < nt; t += 2) {
;             const bool last = (t == nt - 2);
;             const char* a1 = cA + (size_t)(t + 1) * kstep;
;             const char* a2 = last ? nA : cA + (size_t)(t + 2) * kstep; const char* b2 = last ? nB : cB + (size_t)(t + 2) * kstep;
;             const char* a3 = a2 + kstep; const char* b3 = b2 + kstep;
;             if (last && has_next) S.a_ready(nxt);
;             if constexpr (SP2) {
;             PG8_LDB(B0, 0, 0); PG8_LDB(B1, 0, 1); PG8_SCHED; PG8_LDA(At, 0, 0); PG8_STAGE(PG8_SA(1, 1), a1 + hstepA, voffA);
;             PG8_WAIT_V(8); PG8_WAIT_L(0); PG8_BAR; PG8_MMA(0, 0, At, B0); PG8_MMA(0, 1, At, B1); PG8_BAR; PG8_SCHED;
;             PG8_LDA(At, 0, 1); PG8_STAGE(PG8_SB(0, 0), b2, voffB); PG8_STAGE(PG8_SB(0, 1), b2 + hstepB, voffB); PG8_STAGE(PG8_SA(0, 0), a2, voffA);
.LBB0_1060:
	s_add_u32 s12, s54, 0xfff80080
	s_addc_u32 s13, s55, -1
	s_add_i32 s76, 0, 0x10000
	s_cmp_eq_u32 s75, 28
	s_cselect_b32 s59, s37, s13
	s_cselect_b32 s58, s47, s12
	v_add_u32_e32 v138, s76, v141
	s_cselect_b32 s57, s45, s74
	s_cselect_b32 s56, s72, s73
	s_add_i32 s77, 0, 0x14000
	ds_read_b128 v[146:149], v138
	ds_read_b128 v[150:153], v138 offset:1024
	ds_read_b128 v[154:157], v138 offset:2048
	ds_read_b128 v[158:161], v138 offset:3072
	v_add_u32_e32 v138, s77, v141
	ds_read_b128 v[162:165], v138
	ds_read_b128 v[166:169], v138 offset:1024
	ds_read_b128 v[170:173], v138 offset:2048
	ds_read_b128 v[174:177], v138 offset:3072
	v_lshl_add_u64 v[190:191], s[54:55], 0, v[134:135]
	s_add_i32 m0, s53, 0xc000
	ds_read_b128 v[178:181], v145
	ds_read_b128 v[182:185], v145 offset:1024
	ds_read_b128 v[186:189], v145 offset:2048
	ds_read_b128 v[194:197], v145 offset:3072
	ds_read_b128 v[198:201], v145 offset:4096
	ds_read_b128 v[202:205], v145 offset:5120
	ds_read_b128 v[206:209], v145 offset:6144
	ds_read_b128 v[210:213], v145 offset:7168
	global_load_lds_dwordx4 v[190:191], off
	v_lshl_add_u64 v[190:191], s[54:55], 0, v[136:137]
	s_add_i32 m0, s53, 0xe000
	s_nop 0
	global_load_lds_dwordx4 v[190:191], off
	s_waitcnt vmcnt(8)
	s_waitcnt lgkmcnt(0)
	s_barrier
	s_setprio 1
	s_waitcnt lgkmcnt(0)
	v_mfma_f32_16x16x32_bf16 v[124:127], v[146:149], v[178:181], v[124:127]
	v_mfma_f32_16x16x32_bf16 v[120:123], v[154:157], v[178:181], v[120:123]
	v_mfma_f32_16x16x32_bf16 v[112:115], v[146:149], v[186:189], v[112:115]
	v_mfma_f32_16x16x32_bf16 v[104:107], v[154:157], v[186:189], v[104:107]
	v_mfma_f32_16x16x32_bf16 v[96:99], v[146:149], v[198:201], v[96:99]
	v_mfma_f32_16x16x32_bf16 v[88:91], v[154:157], v[198:201], v[88:91]
	v_mfma_f32_16x16x32_bf16 v[80:83], v[146:149], v[206:209], v[80:83]
	v_mfma_f32_16x16x32_bf16 v[72:75], v[154:157], v[206:209], v[72:75]
	v_mfma_f32_16x16x32_bf16 v[124:127], v[150:153], v[182:185], v[124:127]
	v_mfma_f32_16x16x32_bf16 v[120:123], v[158:161], v[182:185], v[120:123]
	v_mfma_f32_16x16x32_bf16 v[112:115], v[150:153], v[194:197], v[112:115]
	v_mfma_f32_16x16x32_bf16 v[104:107], v[158:161], v[194:197], v[104:107]
	v_mfma_f32_16x16x32_bf16 v[96:99], v[150:153], v[202:205], v[96:99]
	v_mfma_f32_16x16x32_bf16 v[88:91], v[158:161], v[202:205], v[88:91]
	v_mfma_f32_16x16x32_bf16 v[80:83], v[150:153], v[210:213], v[80:83]
	v_mfma_f32_16x16x32_bf16 v[72:75], v[158:161], v[210:213], v[72:75]
	v_mfma_f32_16x16x32_bf16 v[116:119], v[162:165], v[178:181], v[116:119]
	v_mfma_f32_16x16x32_bf16 v[108:111], v[170:173], v[178:181], v[108:111]
	v_mfma_f32_16x16x32_bf16 v[100:103], v[162:165], v[186:189], v[100:103]
	v_mfma_f32_16x16x32_bf16 v[92:95], v[170:173], v[186:189], v[92:95]
	v_mfma_f32_16x16x32_bf16 v[84:87], v[162:165], v[198:201], v[84:87]
	v_mfma_f32_16x16x32_bf16 v[76:79], v[170:173], v[198:201], v[76:79]
	v_mfma_f32_16x16x32_bf16 v[68:71], v[162:165], v[206:209], v[68:71]
	v_mfma_f32_16x16x32_bf16 v[64:67], v[170:173], v[206:209], v[64:67]
	v_mfma_f32_16x16x32_bf16 v[116:119], v[166:169], v[182:185], v[116:119]
	v_mfma_f32_16x16x32_bf16 v[108:111], v[174:177], v[182:185], v[108:111]
	v_mfma_f32_16x16x32_bf16 v[100:103], v[166:169], v[194:197], v[100:103]
	v_mfma_f32_16x16x32_bf16 v[92:95], v[174:177], v[194:197], v[92:95]
	v_mfma_f32_16x16x32_bf16 v[84:87], v[166:169], v[202:205], v[84:87]
	v_mfma_f32_16x16x32_bf16 v[76:79], v[174:177], v[202:205], v[76:79]
	v_mfma_f32_16x16x32_bf16 v[68:71], v[166:169], v[210:213], v[68:71]
	v_mfma_f32_16x16x32_bf16 v[64:67], v[174:177], v[210:213], v[64:67]
	s_setprio 0
	s_barrier
	s_add_i32 s12, s76, s66
	v_lshl_add_u64 v[190:191], s[56:57], 0, v[192:193]
	s_mov_b32 m0, s12
	ds_read_b128 v[178:181], v145 offset:16384
	ds_read_b128 v[182:185], v145 offset:17408
	ds_read_b128 v[186:189], v145 offset:18432
	ds_read_b128 v[194:197], v145 offset:19456
	ds_read_b128 v[198:201], v145 offset:20480
	ds_read_b128 v[202:205], v145 offset:21504
	ds_read_b128 v[206:209], v145 offset:22528
	ds_read_b128 v[210:213], v145 offset:23552
	global_load_lds_dwordx4 v[190:191], off
	s_add_i32 m0, s12, 0x2000
	s_add_u32 s12, s56, 0x80000
	v_lshl_add_u64 v[214:215], s[56:57], 0, v[132:133]
	s_addc_u32 s13, s57, 0
	s_add_i32 s76, s77, s66
	global_load_lds_dwordx4 v[214:215], off
	v_lshl_add_u64 v[216:217], s[12:13], 0, v[192:193]
	s_mov_b32 m0, s76
	v_lshl_add_u64 v[218:219], s[58:59], 0, v[130:131]
	global_load_lds_dwordx4 v[216:217], off
	v_lshl_add_u64 v[216:217], s[12:13], 0, v[132:133]
	s_add_i32 m0, s76, 0x2000
	s_nop 0
	global_load_lds_dwordx4 v[216:217], off
	v_lshl_add_u64 v[216:217], s[58:59], 0, v[128:129]
	s_mov_b32 m0, s53
	s_nop 0
	global_load_lds_dwordx4 v[216:217], off
	s_mov_b32 m0, s67
	s_nop 0
	global_load_lds_dwordx4 v[218:219], off
	s_waitcnt vmcnt(8)
	s_waitcnt lgkmcnt(0)
	s_barrier
; #define PG8_STAGE(bufoff, gbase, voff) do { _Pragma("unroll") for (int _i = 0; _i < 2; ++_i) \
;         __builtin_amdgcn_global_load_lds((const unsigned*)((const char*)(gbase) + (voff)[_i]), (PG8_LAS unsigned*)(lds + (bufoff) + ldsw + _i * 8192), 16, 0, 0); } while (0)
; #define PG8_LDA(dst, b, h) do { _Pragma("unroll") for (int m = 0; m < 4; ++m) _Pragma("unroll") for (int k = 0; k < 2; ++k) dst[m][k] = *(const PG8_LAS bf16x8*)(lds + PG8_SA(b, h) + aoff + m * 2048 + k * 1024); } while (0)
; #define PG8_LDB(dst, b, h) do { _Pragma("unroll") for (int n = 0; n < 2; ++n) _Pragma("unroll") for (int k = 0; k < 2; ++k) dst[n][k] = *(const PG8_LAS bf16x8*)(lds + PG8_SB(b, h) + boff + n * 2048 + k * 1024); } while (0)
; #define PG8_MMA(ai, bj, At, Bt) do { __builtin_amdgcn_s_setprio(1); _Pragma("unroll") for (int m = 0; m < 4; ++m) _Pragma("unroll") for (int n = 0; n < 2; ++n) _Pragma("unroll") for (int k = 0; k < 2; ++k) \
;         acc[ai][bj][m][n] = __builtin_amdgcn_mfma_f32_16x16x32_bf16(Bt[n][k], At[m][k], acc[ai][bj][m][n], 0, 0, 0); __builtin_amdgcn_s_setprio(0); } while (0)
; #define PG8_WAIT_V(n) asm volatile("s_waitcnt vmcnt(" #n ")" ::: "memory")
; #define PG8_WAIT_L(n) asm volatile("s_waitcnt lgkmcnt(" #n ")" ::: "memory")
; #define PG8_BAR __builtin_amdgcn_s_barrier()
; #define PG8_SCHED __builtin_amdgcn_sched_barrier(0)
; template <class Epi, class Sched, bool ALIGN_EPI = false, bool SP2 = false>
; __device__ __forceinline__ void gemm_phase(PG8_LAS unsigned char* lds, const Gemm g, const Sched& S, const Epi& E, const int tid_in) {
;     ...
;             PG8_WAIT_V(8); PG8_WAIT_L(0); PG8_BAR; PG8_MMA(1, 0, At, B0); PG8_MMA(1, 1, At, B1); PG8_BAR; PG8_SCHED;
;             PG8_LDB(B0, 1, 0); PG8_LDB(B1, 1, 1); PG8_SCHED; PG8_LDA(At, 1, 0); PG8_STAGE(PG8_SA(0, 1), a2 + hstepA, voffA);
;             PG8_WAIT_V(8); PG8_WAIT_L(0); PG8_BAR; PG8_MMA(0, 0, At, B0); PG8_MMA(0, 1, At, B1); PG8_BAR; PG8_SCHED;
	s_setprio 1
	s_waitcnt lgkmcnt(0)
	v_mfma_f32_16x16x32_bf16 v[60:63], v[146:149], v[178:181], v[60:63]
	v_mfma_f32_16x16x32_bf16 v[56:59], v[154:157], v[178:181], v[56:59]
	v_mfma_f32_16x16x32_bf16 v[48:51], v[146:149], v[186:189], v[48:51]
	v_mfma_f32_16x16x32_bf16 v[40:43], v[154:157], v[186:189], v[40:43]
	v_mfma_f32_16x16x32_bf16 v[32:35], v[146:149], v[198:201], v[32:35]
	v_mfma_f32_16x16x32_bf16 v[24:27], v[154:157], v[198:201], v[24:27]
	v_mfma_f32_16x16x32_bf16 v[16:19], v[146:149], v[206:209], v[16:19]
	v_mfma_f32_16x16x32_bf16 v[8:11], v[154:157], v[206:209], v[8:11]
	v_mfma_f32_16x16x32_bf16 v[60:63], v[150:153], v[182:185], v[60:63]
	v_mfma_f32_16x16x32_bf16 v[56:59], v[158:161], v[182:185], v[56:59]
	v_mfma_f32_16x16x32_bf16 v[48:51], v[150:153], v[194:197], v[48:51]
	v_mfma_f32_16x16x32_bf16 v[40:43], v[158:161], v[194:197], v[40:43]
	v_mfma_f32_16x16x32_bf16 v[32:35], v[150:153], v[202:205], v[32:35]
	v_mfma_f32_16x16x32_bf16 v[24:27], v[158:161], v[202:205], v[24:27]
	v_mfma_f32_16x16x32_bf16 v[16:19], v[150:153], v[210:213], v[16:19]
	v_mfma_f32_16x16x32_bf16 v[8:11], v[158:161], v[210:213], v[8:11]
	v_mfma_f32_16x16x32_bf16 v[52:55], v[162:165], v[178:181], v[52:55]
	v_mfma_f32_16x16x32_bf16 v[44:47], v[170:173], v[178:181], v[44:47]
	v_mfma_f32_16x16x32_bf16 v[36:39], v[162:165], v[186:189], v[36:39]
	v_mfma_f32_16x16x32_bf16 v[28:31], v[170:173], v[186:189], v[28:31]
	v_mfma_f32_16x16x32_bf16 v[20:23], v[162:165], v[198:201], v[20:23]
	v_mfma_f32_16x16x32_bf16 v[12:15], v[170:173], v[198:201], v[12:15]
	v_mfma_f32_16x16x32_bf16 v[4:7], v[162:165], v[206:209], v[4:7]
	v_mfma_f32_16x16x32_bf16 v[0:3], v[170:173], v[206:209], v[0:3]
	v_mfma_f32_16x16x32_bf16 v[52:55], v[166:169], v[182:185], v[52:55]
	v_mfma_f32_16x16x32_bf16 v[44:47], v[174:177], v[182:185], v[44:47]
	v_mfma_f32_16x16x32_bf16 v[36:39], v[166:169], v[194:197], v[36:39]
	v_mfma_f32_16x16x32_bf16 v[28:31], v[174:177], v[194:197], v[28:31]
	v_mfma_f32_16x16x32_bf16 v[20:23], v[166:169], v[202:205], v[20:23]
	v_mfma_f32_16x16x32_bf16 v[12:15], v[174:177], v[202:205], v[12:15]
	v_mfma_f32_16x16x32_bf16 v[4:7], v[166:169], v[210:213], v[4:7]
	v_mfma_f32_16x16x32_bf16 v[0:3], v[174:177], v[210:213], v[0:3]
	s_setprio 0
	s_barrier
	s_add_i32 s76, 0, 0x18000
	v_add_u32_e32 v138, s76, v141
	s_add_i32 s77, 0, 0x1c000
	ds_read_b128 v[146:149], v138
	ds_read_b128 v[150:153], v138 offset:1024
	ds_read_b128 v[154:157], v138 offset:2048
	ds_read_b128 v[158:161], v138 offset:3072
	v_add_u32_e32 v138, s77, v141
	ds_read_b128 v[162:165], v138
	ds_read_b128 v[166:169], v138 offset:1024
	ds_read_b128 v[170:173], v138 offset:2048
	ds_read_b128 v[174:177], v138 offset:3072
	s_add_u32 s12, s58, 0x80000
	s_addc_u32 s13, s59, 0
	s_mov_b32 m0, s68
	v_lshl_add_u64 v[220:221], s[12:13], 0, v[128:129]
	ds_read_b128 v[178:181], v145 offset:32768
	ds_read_b128 v[182:185], v145 offset:33792
	ds_read_b128 v[186:189], v145 offset:34816
	ds_read_b128 v[194:197], v145 offset:35840
	ds_read_b128 v[198:201], v145 offset:36864
	ds_read_b128 v[202:205], v145 offset:37888
	ds_read_b128 v[206:209], v145 offset:38912
	ds_read_b128 v[210:213], v145 offset:39936
	global_load_lds_dwordx4 v[220:221], off
	v_lshl_add_u64 v[220:221], s[12:13], 0, v[130:131]
	s_mov_b32 m0, s69
	s_nop 0
	global_load_lds_dwordx4 v[220:221], off
	s_waitcnt vmcnt(8)
	s_waitcnt lgkmcnt(0)
	s_barrier
	s_setprio 1
	s_waitcnt lgkmcnt(0)
	v_mfma_f32_16x16x32_bf16 v[124:127], v[146:149], v[178:181], v[124:127]
	v_mfma_f32_16x16x32_bf16 v[120:123], v[154:157], v[178:181], v[120:123]
	v_mfma_f32_16x16x32_bf16 v[112:115], v[146:149], v[186:189], v[112:115]
	v_mfma_f32_16x16x32_bf16 v[104:107], v[154:157], v[186:189], v[104:107]
	v_mfma_f32_16x16x32_bf16 v[96:99], v[146:149], v[198:201], v[96:99]
	v_mfma_f32_16x16x32_bf16 v[88:91], v[154:157], v[198:201], v[88:91]
	v_mfma_f32_16x16x32_bf16 v[80:83], v[146:149], v[206:209], v[80:83]
	v_mfma_f32_16x16x32_bf16 v[72:75], v[154:157], v[206:209], v[72:75]
	v_mfma_f32_16x16x32_bf16 v[124:127], v[150:153], v[182:185], v[124:127]
	v_mfma_f32_16x16x32_bf16 v[120:123], v[158:161], v[182:185], v[120:123]
	v_mfma_f32_16x16x32_bf16 v[112:115], v[150:153], v[194:197], v[112:115]
	v_mfma_f32_16x16x32_bf16 v[104:107], v[158:161], v[194:197], v[104:107]
	v_mfma_f32_16x16x32_bf16 v[96:99], v[150:153], v[202:205], v[96:99]
	v_mfma_f32_16x16x32_bf16 v[88:91], v[158:161], v[202:205], v[88:91]
	v_mfma_f32_16x16x32_bf16 v[80:83], v[150:153], v[210:213], v[80:83]
	v_mfma_f32_16x16x32_bf16 v[72:75], v[158:161], v[210:213], v[72:75]
	v_mfma_f32_16x16x32_bf16 v[116:119], v[162:165], v[178:181], v[116:119]
	v_mfma_f32_16x16x32_bf16 v[108:111], v[170:173], v[178:181], v[108:111]
	v_mfma_f32_16x16x32_bf16 v[100:103], v[162:165], v[186:189], v[100:103]
	v_mfma_f32_16x16x32_bf16 v[92:95], v[170:173], v[186:189], v[92:95]
	v_mfma_f32_16x16x32_bf16 v[84:87], v[162:165], v[198:201], v[84:87]
	v_mfma_f32_16x16x32_bf16 v[76:79], v[170:173], v[198:201], v[76:79]
	v_mfma_f32_16x16x32_bf16 v[68:71], v[162:165], v[206:209], v[68:71]
	v_mfma_f32_16x16x32_bf16 v[64:67], v[170:173], v[206:209], v[64:67]
	v_mfma_f32_16x16x32_bf16 v[116:119], v[166:169], v[182:185], v[116:119]
	v_mfma_f32_16x16x32_bf16 v[108:111], v[174:177], v[182:185], v[108:111]
	v_mfma_f32_16x16x32_bf16 v[100:103], v[166:169], v[194:197], v[100:103]
	v_mfma_f32_16x16x32_bf16 v[92:95], v[174:177], v[194:197], v[92:95]
	v_mfma_f32_16x16x32_bf16 v[84:87], v[166:169], v[202:205], v[84:87]
	v_mfma_f32_16x16x32_bf16 v[76:79], v[174:177], v[202:205], v[76:79]
	v_mfma_f32_16x16x32_bf16 v[68:71], v[166:169], v[210:213], v[68:71]
	v_mfma_f32_16x16x32_bf16 v[64:67], v[174:177], v[210:213], v[64:67]
	s_setprio 0
	s_barrier
; #define PG8_STAGE(bufoff, gbase, voff) do { _Pragma("unroll") for (int _i = 0; _i < 2; ++_i) \
;         __builtin_amdgcn_global_load_lds((const unsigned*)((const char*)(gbase) + (voff)[_i]), (PG8_LAS unsigned*)(lds + (bufoff) + ldsw + _i * 8192), 16, 0, 0); } while (0)
; #define PG8_LDA(dst, b, h) do { _Pragma("unroll") for (int m = 0; m < 4; ++m) _Pragma("unroll") for (int k = 0; k < 2; ++k) dst[m][k] = *(const PG8_LAS bf16x8*)(lds + PG8_SA(b, h) + aoff + m * 2048 + k * 1024); } while (0)
; #define PG8_BAR __builtin_amdgcn_s_barrier()
; template <class Epi, class Sched, bool ALIGN_EPI = false, bool SP2 = false>
; __device__ __forceinline__ void gemm_phase(PG8_LAS unsigned char* lds, const Gemm g, const Sched& S, const Epi& E, const int tid_in) {
;     ...
;             PG8_LDA(At, 1, 1); PG8_STAGE(PG8_SB(1, 0), b3, voffB); PG8_STAGE(PG8_SB(1, 1), b3 + hstepB, voffB); PG8_STAGE(PG8_SA(1, 0), a3, voffA);
;             PG8_WAIT_V(8); PG8_WAIT_L(0); PG8_BAR; PG8_MMA(1, 0, At, B0); PG8_MMA(1, 1, At, B1); PG8_BAR; PG8_SCHED;
;             } else {
;             PG8_LDB(B0, 0, 0); PG8_SCHED; PG8_LDA(At, 0, 0); PG8_STAGE(PG8_SA(1, 1), a1 + hstepA, voffA);
;             PG8_WAIT_L(8); PG8_BAR; PG8_WAIT_L(0); PG8_MMA(0, 0, At, B0); PG8_BAR; PG8_SCHED;
;             PG8_LDB(B1, 0, 1); PG8_STAGE(PG8_SB(0, 0), b2, voffB);
;             PG8_BAR; PG8_WAIT_L(0); PG8_MMA(0, 1, At, B1); PG8_BAR;
;             PG8_LDA(At, 0, 1); PG8_STAGE(PG8_SA(0, 0), a2, voffA);
;             PG8_BAR; PG8_WAIT_L(0); PG8_MMA(1, 0, At, B0); PG8_BAR; PG8_SCHED;
;             PG8_STAGE(PG8_SB(0, 1), b2 + hstepB, voffB);
;             PG8_WAIT_V(6); PG8_BAR; PG8_MMA(1, 1, At, B1); PG8_BAR;
;             PG8_LDB(B0, 1, 0); PG8_SCHED; PG8_LDA(At, 1, 0); PG8_STAGE(PG8_SA(0, 1), a2 + hstepA, voffA);
;             PG8_WAIT_L(8); PG8_BAR; PG8_WAIT_L(0); PG8_MMA(0, 0, At, B0); PG8_BAR; PG8_SCHED;
;             PG8_LDB(B1, 1, 1); PG8_STAGE(PG8_SB(1, 0), b3, voffB);
;             PG8_BAR; PG8_WAIT_L(0); PG8_MMA(0, 1, At, B1); PG8_BAR;
;             PG8_LDA(At, 1, 1); PG8_STAGE(PG8_SA(1, 0), a3, voffA);
;             PG8_BAR; PG8_WAIT_L(0); PG8_MMA(1, 0, At, B0); PG8_BAR; PG8_SCHED;
;             PG8_STAGE(PG8_SB(1, 1), b3 + hstepB, voffB);
;             PG8_WAIT_V(6); PG8_BAR; PG8_MMA(1, 1, At, B1); PG8_BAR;
;             }
;         }
;         if constexpr (ALIGN_EPI) { if (wr == 0) PG8_BAR; }
	s_add_i32 s12, s76, s66
	v_lshl_add_u64 v[190:191], v[190:191], 0, s[26:27]
	s_mov_b32 m0, s12
	ds_read_b128 v[178:181], v145 offset:49152
	ds_read_b128 v[182:185], v145 offset:50176
	ds_read_b128 v[186:189], v145 offset:51200
	ds_read_b128 v[194:197], v145 offset:52224
	ds_read_b128 v[198:201], v145 offset:53248
	ds_read_b128 v[202:205], v145 offset:54272
	ds_read_b128 v[206:209], v145 offset:55296
	ds_read_b128 v[210:213], v145 offset:56320
	global_load_lds_dwordx4 v[190:191], off
	s_add_i32 m0, s12, 0x2000
	s_add_u32 s12, s56, 0x80080
	v_lshl_add_u64 v[190:191], v[214:215], 0, s[26:27]
	s_addc_u32 s13, s57, 0
	s_add_i32 s56, s77, s66
	global_load_lds_dwordx4 v[190:191], off
	v_lshl_add_u64 v[190:191], s[12:13], 0, v[192:193]
	s_mov_b32 m0, s56
	s_nop 0
	global_load_lds_dwordx4 v[190:191], off
	v_lshl_add_u64 v[190:191], s[12:13], 0, v[132:133]
	s_add_i32 m0, s56, 0x2000
	s_nop 0
	global_load_lds_dwordx4 v[190:191], off
	v_lshl_add_u64 v[190:191], v[216:217], 0, s[26:27]
	s_mov_b32 m0, s11
	s_nop 0
	global_load_lds_dwordx4 v[190:191], off
	v_lshl_add_u64 v[190:191], v[218:219], 0, s[26:27]
	s_mov_b32 m0, s70
	s_nop 0
	global_load_lds_dwordx4 v[190:191], off
	s_waitcnt vmcnt(8)
	s_waitcnt lgkmcnt(0)
	s_barrier
	s_setprio 1
	s_waitcnt lgkmcnt(0)
	v_mfma_f32_16x16x32_bf16 v[60:63], v[146:149], v[178:181], v[60:63]
	v_mfma_f32_16x16x32_bf16 v[56:59], v[154:157], v[178:181], v[56:59]
	v_mfma_f32_16x16x32_bf16 v[48:51], v[146:149], v[186:189], v[48:51]
	v_mfma_f32_16x16x32_bf16 v[40:43], v[154:157], v[186:189], v[40:43]
	v_mfma_f32_16x16x32_bf16 v[32:35], v[146:149], v[198:201], v[32:35]
	v_mfma_f32_16x16x32_bf16 v[24:27], v[154:157], v[198:201], v[24:27]
	v_mfma_f32_16x16x32_bf16 v[16:19], v[146:149], v[206:209], v[16:19]
	v_mfma_f32_16x16x32_bf16 v[8:11], v[154:157], v[206:209], v[8:11]
	v_mfma_f32_16x16x32_bf16 v[60:63], v[150:153], v[182:185], v[60:63]
	v_mfma_f32_16x16x32_bf16 v[56:59], v[158:161], v[182:185], v[56:59]
	v_mfma_f32_16x16x32_bf16 v[48:51], v[150:153], v[194:197], v[48:51]
	v_mfma_f32_16x16x32_bf16 v[40:43], v[158:161], v[194:197], v[40:43]
	v_mfma_f32_16x16x32_bf16 v[32:35], v[150:153], v[202:205], v[32:35]
	v_mfma_f32_16x16x32_bf16 v[24:27], v[158:161], v[202:205], v[24:27]
	v_mfma_f32_16x16x32_bf16 v[16:19], v[150:153], v[210:213], v[16:19]
	v_mfma_f32_16x16x32_bf16 v[8:11], v[158:161], v[210:213], v[8:11]
	v_mfma_f32_16x16x32_bf16 v[52:55], v[162:165], v[178:181], v[52:55]
	v_mfma_f32_16x16x32_bf16 v[44:47], v[170:173], v[178:181], v[44:47]
	v_mfma_f32_16x16x32_bf16 v[36:39], v[162:165], v[186:189], v[36:39]
	v_mfma_f32_16x16x32_bf16 v[28:31], v[170:173], v[186:189], v[28:31]
	v_mfma_f32_16x16x32_bf16 v[20:23], v[162:165], v[198:201], v[20:23]
	v_mfma_f32_16x16x32_bf16 v[12:15], v[170:173], v[198:201], v[12:15]
	v_mfma_f32_16x16x32_bf16 v[4:7], v[162:165], v[206:209], v[4:7]
	v_mfma_f32_16x16x32_bf16 v[0:3], v[170:173], v[206:209], v[0:3]
	v_mfma_f32_16x16x32_bf16 v[52:55], v[166:169], v[182:185], v[52:55]
	v_mfma_f32_16x16x32_bf16 v[44:47], v[174:177], v[182:185], v[44:47]
	v_mfma_f32_16x16x32_bf16 v[36:39], v[166:169], v[194:197], v[36:39]
	v_mfma_f32_16x16x32_bf16 v[28:31], v[174:177], v[194:197], v[28:31]
	v_mfma_f32_16x16x32_bf16 v[20:23], v[166:169], v[202:205], v[20:23]
	v_mfma_f32_16x16x32_bf16 v[12:15], v[174:177], v[202:205], v[12:15]
	v_mfma_f32_16x16x32_bf16 v[4:7], v[166:169], v[210:213], v[4:7]
	v_mfma_f32_16x16x32_bf16 v[0:3], v[174:177], v[210:213], v[0:3]
	s_setprio 0
	s_barrier
	s_add_i32 s75, s75, 2
	s_add_u32 s54, s54, 0x100
	s_addc_u32 s55, s55, 0
	s_add_u32 s73, s73, 0x100
	s_addc_u32 s74, s74, 0
	s_cmp_gt_u32 s75, 29
	s_cbranch_scc0 .LBB0_1060
	s_andn2_b64 vcc, s[42:43], s[34:35]
	s_cbranch_vccz .LBB0_1063
	s_barrier

; __device__ __forceinline__ unsigned cvt_pk_bf16(float lo, float hi) { unsigned r; asm volatile("v_cvt_pk_bf16_f32 %0, %1, %2" : "=v"(r) : "v"(lo), "v"(hi)); return r; }
;     __device__ __forceinline__ void operator()(const f32x4 (&acc)[2][2][4][2], const Unit& u, int wr, int wc, int fr, int fq) const {
;         const int row0 = u.pm * BM + wr * 64 + fr; int colt = u.pn * BM; bf16_t* base = O;
;         if (split_cols && colt >= split_cols) { base = O2; colt -= split_cols; }
;         const int col0 = colt + wc * 32 + 8 * fq;
;         float rsv[2][4];
; #pragma unroll
;         for (int ai = 0; ai < 2; ++ai)
; #pragma unroll
;             for (int m = 0; m < 4; ++m) rsv[ai][m] = rs ? rs[row0 + ai * HALF + m * 16] : 1.f;
; #pragma unroll
;         for (int ai = 0; ai < 2; ++ai)
; #pragma unroll
;             for (int m = 0; m < 4; ++m) { bf16_t* rowp = base + (size_t)(row0 + ai * HALF + m * 16) * ldc + col0;
;                 const float rsc = rsv[ai][m];
; #pragma unroll
;                 for (int bj = 0; bj < 2; ++bj) { f32x4 v0 = acc[ai][bj][m][0] * rsc, v1 = acc[ai][bj][m][1] * rsc;
;                     if (ACT == 1) {
; #pragma unroll
;                         for (int e = 0; e < 4; ++e) { const float a = fmaxf(v0[e], 0.f), b = fmaxf(v1[e], 0.f); v0[e] = a * a; v1[e] = b * b; } }
;                     u32x4 w; w.x = cvt_pk_bf16(v0[0], v0[1]); w.y = cvt_pk_bf16(v0[2], v0[3]); w.z = cvt_pk_bf16(v1[0], v1[1]); w.w = cvt_pk_bf16(v1[2], v1[3]);
;                     *(u32x4*)(rowp + bj * HALF) = w; } }
.LBB0_1073:
	v_lshl_or_b32 v158, s52, 8, v143
	v_ashrrev_i32_e32 v159, 31, v158
	v_lshl_add_u64 v[158:159], v[158:159], 1, s[30:31]
	v_lshlrev_b64 v[160:161], 13, v[148:149]
	v_lshl_add_u64 v[160:161], v[158:159], 0, v[160:161]
	s_waitcnt vmcnt(0)
	v_pk_mul_f32 v[126:127], v[126:127], v[154:155] op_sel_hi:[1,0]
	v_pk_mul_f32 v[124:125], v[124:125], v[154:155] op_sel_hi:[1,0]
	v_pk_mul_f32 v[162:163], v[122:123], v[154:155] op_sel_hi:[1,0]
	v_pk_mul_f32 v[122:123], v[120:121], v[154:155] op_sel_hi:[1,0]
	v_cvt_pk_bf16_f32 v120, v124, v125
	v_cvt_pk_bf16_f32 v121, v126, v127
	v_pk_mul_f32 v[116:117], v[116:117], v[154:155] op_sel_hi:[1,0]
	v_cvt_pk_bf16_f32 v122, v122, v123
	v_cvt_pk_bf16_f32 v123, v162, v163
	global_store_dwordx4 v[160:161], v[120:123], off
	v_pk_mul_f32 v[118:119], v[118:119], v[154:155] op_sel_hi:[1,0]
	v_pk_mul_f32 v[112:113], v[112:113], v[152:153] op_sel_hi:[1,0]
	v_pk_mul_f32 v[120:121], v[110:111], v[154:155] op_sel_hi:[1,0]
	v_pk_mul_f32 v[110:111], v[108:109], v[154:155] op_sel_hi:[1,0]
	v_cvt_pk_bf16_f32 v108, v116, v117
	v_cvt_pk_bf16_f32 v109, v118, v119
	v_pk_mul_f32 v[100:101], v[100:101], v[152:153] op_sel_hi:[1,0]
	v_cvt_pk_bf16_f32 v110, v110, v111
	v_cvt_pk_bf16_f32 v111, v120, v121
	global_store_dwordx4 v[160:161], v[108:111], off offset:256
	v_pk_mul_f32 v[102:103], v[102:103], v[152:153] op_sel_hi:[1,0]
	v_pk_mul_f32 v[96:97], v[96:97], v[150:151] op_sel_hi:[1,0]
	v_or_b32_e32 v108, 16, v148
	v_ashrrev_i32_e32 v109, 31, v108
	v_lshlrev_b64 v[108:109], 13, v[108:109]
	v_lshl_add_u64 v[108:109], v[158:159], 0, v[108:109]
	v_pk_mul_f32 v[110:111], v[114:115], v[152:153] op_sel_hi:[1,0]
	v_pk_mul_f32 v[114:115], v[106:107], v[152:153] op_sel_hi:[1,0]
	v_pk_mul_f32 v[106:107], v[104:105], v[152:153] op_sel_hi:[1,0]
	v_cvt_pk_bf16_f32 v104, v112, v113
	v_cvt_pk_bf16_f32 v105, v110, v111
	v_pk_mul_f32 v[84:85], v[84:85], v[150:151] op_sel_hi:[1,0]
	v_cvt_pk_bf16_f32 v106, v106, v107
	v_cvt_pk_bf16_f32 v107, v114, v115
	global_store_dwordx4 v[108:109], v[104:107], off
	v_pk_mul_f32 v[86:87], v[86:87], v[150:151] op_sel_hi:[1,0]
	v_pk_mul_f32 v[80:81], v[80:81], v[146:147] op_sel_hi:[1,0]
	v_pk_mul_f32 v[104:105], v[94:95], v[152:153] op_sel_hi:[1,0]
	v_pk_mul_f32 v[94:95], v[92:93], v[152:153] op_sel_hi:[1,0]
	v_cvt_pk_bf16_f32 v92, v100, v101
	v_cvt_pk_bf16_f32 v93, v102, v103
	v_lshlrev_b64 v[156:157], 13, v[148:149]
	v_cvt_pk_bf16_f32 v94, v94, v95
	v_cvt_pk_bf16_f32 v95, v104, v105
	global_store_dwordx4 v[108:109], v[92:95], off offset:256
	v_pk_mul_f32 v[70:71], v[70:71], v[146:147] op_sel_hi:[1,0]
	v_pk_mul_f32 v[68:69], v[68:69], v[146:147] op_sel_hi:[1,0]
	v_or_b32_e32 v92, 32, v148
	v_ashrrev_i32_e32 v93, 31, v92
	v_lshlrev_b64 v[92:93], 13, v[92:93]
	v_lshl_add_u64 v[92:93], v[158:159], 0, v[92:93]
	v_pk_mul_f32 v[94:95], v[98:99], v[150:151] op_sel_hi:[1,0]
	v_pk_mul_f32 v[98:99], v[90:91], v[150:151] op_sel_hi:[1,0]
	v_pk_mul_f32 v[90:91], v[88:89], v[150:151] op_sel_hi:[1,0]
	v_cvt_pk_bf16_f32 v88, v96, v97
	v_cvt_pk_bf16_f32 v89, v94, v95
	v_pk_mul_f32 v[60:61], v[60:61], v[144:145] op_sel_hi:[1,0]
	v_cvt_pk_bf16_f32 v90, v90, v91
	v_cvt_pk_bf16_f32 v91, v98, v99
	global_store_dwordx4 v[92:93], v[88:91], off
	v_pk_mul_f32 v[62:63], v[62:63], v[144:145] op_sel_hi:[1,0]
	s_mov_b64 s[12:13], 0x100000
	v_pk_mul_f32 v[88:89], v[78:79], v[150:151] op_sel_hi:[1,0]
	v_pk_mul_f32 v[78:79], v[76:77], v[150:151] op_sel_hi:[1,0]
	v_cvt_pk_bf16_f32 v76, v84, v85
	v_cvt_pk_bf16_f32 v77, v86, v87
	v_pk_mul_f32 v[54:55], v[54:55], v[144:145] op_sel_hi:[1,0]
	v_cvt_pk_bf16_f32 v78, v78, v79
	v_cvt_pk_bf16_f32 v79, v88, v89
	global_store_dwordx4 v[92:93], v[76:79], off offset:256
	v_pk_mul_f32 v[52:53], v[52:53], v[144:145] op_sel_hi:[1,0]
	v_pk_mul_f32 v[48:49], v[48:49], v[142:143] op_sel_hi:[1,0]
	v_or_b32_e32 v76, 48, v148
	v_ashrrev_i32_e32 v77, 31, v76
	v_lshlrev_b64 v[76:77], 13, v[76:77]
	v_lshl_add_u64 v[76:77], v[158:159], 0, v[76:77]
	v_pk_mul_f32 v[78:79], v[82:83], v[146:147] op_sel_hi:[1,0]
	v_pk_mul_f32 v[82:83], v[74:75], v[146:147] op_sel_hi:[1,0]
	v_pk_mul_f32 v[74:75], v[72:73], v[146:147] op_sel_hi:[1,0]
	v_cvt_pk_bf16_f32 v72, v80, v81
	v_cvt_pk_bf16_f32 v73, v78, v79
	v_pk_mul_f32 v[38:39], v[38:39], v[142:143] op_sel_hi:[1,0]
	v_cvt_pk_bf16_f32 v74, v74, v75
; __device__ __forceinline__ unsigned cvt_pk_bf16(float lo, float hi) { unsigned r; asm volatile("v_cvt_pk_bf16_f32 %0, %1, %2" : "=v"(r) : "v"(lo), "v"(hi)); return r; }
; #define PG8_BAR __builtin_amdgcn_s_barrier()
;     __device__ __forceinline__ void operator()(const f32x4 (&acc)[2][2][4][2], const Unit& u, int wr, int wc, int fr, int fq) const {
;         const int row0 = u.pm * BM + wr * 64 + fr; int colt = u.pn * BM; bf16_t* base = O;
;         if (split_cols && colt >= split_cols) { base = O2; colt -= split_cols; }
;         const int col0 = colt + wc * 32 + 8 * fq;
;         float rsv[2][4];
; #pragma unroll
;         for (int ai = 0; ai < 2; ++ai)
; #pragma unroll
;             for (int m = 0; m < 4; ++m) rsv[ai][m] = rs ? rs[row0 + ai * HALF + m * 16] : 1.f;
; #pragma unroll
;         for (int ai = 0; ai < 2; ++ai)
; #pragma unroll
;             for (int m = 0; m < 4; ++m) { bf16_t* rowp = base + (size_t)(row0 + ai * HALF + m * 16) * ldc + col0;
;                 const float rsc = rsv[ai][m];
; #pragma unroll
;                 for (int bj = 0; bj < 2; ++bj) { f32x4 v0 = acc[ai][bj][m][0] * rsc, v1 = acc[ai][bj][m][1] * rsc;
;                     if (ACT == 1) {
; #pragma unroll
;                         for (int e = 0; e < 4; ++e) { const float a = fmaxf(v0[e], 0.f), b = fmaxf(v1[e], 0.f); v0[e] = a * a; v1[e] = b * b; } }
;                     u32x4 w; w.x = cvt_pk_bf16(v0[0], v0[1]); w.y = cvt_pk_bf16(v0[2], v0[3]); w.z = cvt_pk_bf16(v1[0], v1[1]); w.w = cvt_pk_bf16(v1[2], v1[3]);
;                     *(u32x4*)(rowp + bj * HALF) = w; } }
; template <class Epi, class Sched, bool ALIGN_EPI = false, bool SP2 = false>
; __device__ __forceinline__ void gemm_phase(PG8_LAS unsigned char* lds, const Gemm g, const Sched& S, const Epi& E, const int tid_in) {
;     ...
;         if (!has_next) break;
; #pragma unroll
;         for (int a = 0; a < 2; ++a)
; #pragma unroll
;             for (int b = 0; b < 2; ++b)
; #pragma unroll
;                 for (int m = 0; m < 4; ++m)
; #pragma unroll
;                     for (int n = 0; n < 2; ++n) acc[a][b][m][n] = (f32x4){0.f, 0.f, 0.f, 0.f};
;         cur = nxt; cA = nA; cB = nB; ++ui;
;         if constexpr (ALIGN_EPI) { if (wr == 1) PG8_BAR; }
	v_cvt_pk_bf16_f32 v75, v82, v83
	global_store_dwordx4 v[76:77], v[72:75], off
	v_pk_mul_f32 v[36:37], v[36:37], v[142:143] op_sel_hi:[1,0]
	v_pk_mul_f32 v[32:33], v[32:33], v[140:141] op_sel_hi:[1,0]
	v_pk_mul_f32 v[72:73], v[66:67], v[146:147] op_sel_hi:[1,0]
	v_pk_mul_f32 v[66:67], v[64:65], v[146:147] op_sel_hi:[1,0]
	v_cvt_pk_bf16_f32 v64, v68, v69
	v_cvt_pk_bf16_f32 v65, v70, v71
	v_pk_mul_f32 v[68:69], v[58:59], v[144:145] op_sel_hi:[1,0]
	v_cvt_pk_bf16_f32 v66, v66, v67
	v_cvt_pk_bf16_f32 v67, v72, v73
	global_store_dwordx4 v[76:77], v[64:67], off offset:256
	v_pk_mul_f32 v[58:59], v[56:57], v[144:145] op_sel_hi:[1,0]
	v_cvt_pk_bf16_f32 v56, v60, v61
	v_cvt_pk_bf16_f32 v57, v62, v63
	v_pk_mul_f32 v[22:23], v[22:23], v[140:141] op_sel_hi:[1,0]
	v_lshl_add_u64 v[64:65], v[158:159], 0, v[156:157]
	v_add_co_u32_e32 v60, vcc, s6, v64
	v_cvt_pk_bf16_f32 v58, v58, v59
	v_cvt_pk_bf16_f32 v59, v68, v69
	v_lshl_add_u64 v[66:67], v[64:65], 0, s[12:13]
	s_nop 0
	v_addc_co_u32_e32 v61, vcc, 0, v65, vcc
	global_store_dwordx4 v[60:61], v[56:59], off
	s_mov_b64 s[12:13], 0x120000
	v_pk_mul_f32 v[20:21], v[20:21], v[140:141] op_sel_hi:[1,0]
	v_pk_mul_f32 v[56:57], v[46:47], v[144:145] op_sel_hi:[1,0]
	v_pk_mul_f32 v[46:47], v[44:45], v[144:145] op_sel_hi:[1,0]
	v_cvt_pk_bf16_f32 v44, v52, v53
	v_cvt_pk_bf16_f32 v45, v54, v55
	v_pk_mul_f32 v[16:17], v[16:17], v[138:139] op_sel_hi:[1,0]
	v_cvt_pk_bf16_f32 v46, v46, v47
	v_cvt_pk_bf16_f32 v47, v56, v57
	global_store_dwordx4 v[66:67], v[44:47], off offset:256
	v_pk_mul_f32 v[6:7], v[6:7], v[138:139] op_sel_hi:[1,0]
	v_pk_mul_f32 v[4:5], v[4:5], v[138:139] op_sel_hi:[1,0]
	v_pk_mul_f32 v[46:47], v[50:51], v[142:143] op_sel_hi:[1,0]
	v_pk_mul_f32 v[50:51], v[42:43], v[142:143] op_sel_hi:[1,0]
	v_pk_mul_f32 v[42:43], v[40:41], v[142:143] op_sel_hi:[1,0]
	v_cvt_pk_bf16_f32 v40, v48, v49
	v_cvt_pk_bf16_f32 v41, v46, v47
	v_add_co_u32_e32 v46, vcc, s7, v64
	v_cvt_pk_bf16_f32 v42, v42, v43
	v_cvt_pk_bf16_f32 v43, v50, v51
	v_lshl_add_u64 v[44:45], v[64:65], 0, s[12:13]
	s_nop 0
	v_addc_co_u32_e32 v47, vcc, 0, v65, vcc
	global_store_dwordx4 v[46:47], v[40:43], off
	s_mov_b64 s[12:13], 0x140000
	s_nop 0
	v_pk_mul_f32 v[40:41], v[30:31], v[142:143] op_sel_hi:[1,0]
	v_pk_mul_f32 v[30:31], v[28:29], v[142:143] op_sel_hi:[1,0]
	v_cvt_pk_bf16_f32 v28, v36, v37
	v_cvt_pk_bf16_f32 v29, v38, v39
	s_nop 0
	v_cvt_pk_bf16_f32 v30, v30, v31
	v_cvt_pk_bf16_f32 v31, v40, v41
	global_store_dwordx4 v[44:45], v[28:31], off offset:256
	s_nop 1
	v_pk_mul_f32 v[30:31], v[34:35], v[140:141] op_sel_hi:[1,0]
	v_pk_mul_f32 v[34:35], v[26:27], v[140:141] op_sel_hi:[1,0]
	v_pk_mul_f32 v[26:27], v[24:25], v[140:141] op_sel_hi:[1,0]
	v_cvt_pk_bf16_f32 v24, v32, v33
	v_cvt_pk_bf16_f32 v25, v30, v31
	v_add_co_u32_e32 v30, vcc, s4, v64
	v_cvt_pk_bf16_f32 v26, v26, v27
	v_cvt_pk_bf16_f32 v27, v34, v35
	v_lshl_add_u64 v[28:29], v[64:65], 0, s[12:13]
	s_nop 0
	v_addc_co_u32_e32 v31, vcc, 0, v65, vcc
	global_store_dwordx4 v[30:31], v[24:27], off
	s_mov_b64 s[12:13], 0x160000
	s_nop 0
	v_pk_mul_f32 v[24:25], v[14:15], v[140:141] op_sel_hi:[1,0]
	v_pk_mul_f32 v[14:15], v[12:13], v[140:141] op_sel_hi:[1,0]
	v_cvt_pk_bf16_f32 v12, v20, v21
	v_cvt_pk_bf16_f32 v13, v22, v23
	s_nop 0
	v_cvt_pk_bf16_f32 v14, v14, v15
	v_cvt_pk_bf16_f32 v15, v24, v25
	global_store_dwordx4 v[28:29], v[12:15], off offset:256
	s_nop 1
	v_pk_mul_f32 v[14:15], v[18:19], v[138:139] op_sel_hi:[1,0]
	v_pk_mul_f32 v[18:19], v[10:11], v[138:139] op_sel_hi:[1,0]
	v_pk_mul_f32 v[10:11], v[8:9], v[138:139] op_sel_hi:[1,0]
	v_cvt_pk_bf16_f32 v8, v16, v17
	v_cvt_pk_bf16_f32 v9, v14, v15
	v_add_co_u32_e32 v14, vcc, s5, v64
	v_lshl_add_u64 v[12:13], v[64:65], 0, s[12:13]
	s_nop 0
	v_addc_co_u32_e32 v15, vcc, 0, v65, vcc
	v_cvt_pk_bf16_f32 v10, v10, v11
	v_cvt_pk_bf16_f32 v11, v18, v19
	global_store_dwordx4 v[14:15], v[8:11], off
	s_andn2_b64 vcc, exec, s[34:35]
	s_mov_b64 s[34:35], -1
	v_pk_mul_f32 v[8:9], v[2:3], v[138:139] op_sel_hi:[1,0]
	v_pk_mul_f32 v[2:3], v[0:1], v[138:139] op_sel_hi:[1,0]
	v_cvt_pk_bf16_f32 v0, v4, v5
	v_cvt_pk_bf16_f32 v1, v6, v7
	s_nop 0
	v_cvt_pk_bf16_f32 v2, v2, v3
	v_cvt_pk_bf16_f32 v3, v8, v9
	global_store_dwordx4 v[12:13], v[0:3], off offset:256
	s_cbranch_vccnz .LBB0_1056
	s_andn2_b64 vcc, exec, s[22:23]
	s_cbranch_vccnz .LBB0_1055
	s_branch .LBB0_1055

; #define PG8_STAGE(bufoff, gbase, voff) do { _Pragma("unroll") for (int _i = 0; _i < 2; ++_i) \
;         __builtin_amdgcn_global_load_lds((const unsigned*)((const char*)(gbase) + (voff)[_i]), (PG8_LAS unsigned*)(lds + (bufoff) + ldsw + _i * 8192), 16, 0, 0); } while (0)
; #define PG8_LDA(dst, b, h) do { _Pragma("unroll") for (int m = 0; m < 4; ++m) _Pragma("unroll") for (int k = 0; k < 2; ++k) dst[m][k] = *(const PG8_LAS bf16x8*)(lds + PG8_SA(b, h) + aoff + m * 2048 + k * 1024); } while (0)
; #define PG8_LDB(dst, b, h) do { _Pragma("unroll") for (int n = 0; n < 2; ++n) _Pragma("unroll") for (int k = 0; k < 2; ++k) dst[n][k] = *(const PG8_LAS bf16x8*)(lds + PG8_SB(b, h) + boff + n * 2048 + k * 1024); } while (0)
; #define PG8_MMA(ai, bj, At, Bt) do { __builtin_amdgcn_s_setprio(1); _Pragma("unroll") for (int m = 0; m < 4; ++m) _Pragma("unroll") for (int n = 0; n < 2; ++n) _Pragma("unroll") for (int k = 0; k < 2; ++k) \
;         acc[ai][bj][m][n] = __builtin_amdgcn_mfma_f32_16x16x32_bf16(Bt[n][k], At[m][k], acc[ai][bj][m][n], 0, 0, 0); __builtin_amdgcn_s_setprio(0); } while (0)
; #define PG8_WAIT_V(n) asm volatile("s_waitcnt vmcnt(" #n ")" ::: "memory")
; #define PG8_WAIT_L(n) asm volatile("s_waitcnt lgkmcnt(" #n ")" ::: "memory")
; #define PG8_BAR __builtin_amdgcn_s_barrier()
; template <class Epi, class Sched, bool ALIGN_EPI = false, bool SP2 = false>
; __device__ __forceinline__ void gemm_phase(PG8_LAS unsigned char* lds, const Gemm g, const Sched& S, const Epi& E, const int tid_in) {
;     ...
;         for (int t = 0; t < nt; t += 2) {
;             const bool last = (t == nt - 2);
;             const char* a1 = cA + (size_t)(t + 1) * kstep;
;             const char* a2 = last ? nA : cA + (size_t)(t + 2) * kstep; const char* b2 = last ? nB : cB + (size_t)(t + 2) * kstep;
;             const char* a3 = a2 + kstep; const char* b3 = b2 + kstep;
;             if (last && has_next) S.a_ready(nxt);
;             if constexpr (SP2) {
;             PG8_LDB(B0, 0, 0); PG8_LDB(B1, 0, 1); PG8_SCHED; PG8_LDA(At, 0, 0); PG8_STAGE(PG8_SA(1, 1), a1 + hstepA, voffA);
;             PG8_WAIT_V(8); PG8_WAIT_L(0); PG8_BAR; PG8_MMA(0, 0, At, B0); PG8_MMA(0, 1, At, B1); PG8_BAR; PG8_SCHED;
;             PG8_LDA(At, 0, 1); PG8_STAGE(PG8_SB(0, 0), b2, voffB); PG8_STAGE(PG8_SB(0, 1), b2 + hstepB, voffB); PG8_STAGE(PG8_SA(0, 0), a2, voffA);
.LBB0_1221:
	s_add_u32 s12, s48, 0xfff00080
	s_addc_u32 s13, s49, -1
	s_add_i32 s71, 0, 0x10000
	s_cmp_eq_u32 s70, 60
	s_cselect_b32 s53, s41, s13
	s_cselect_b32 s52, s66, s12
	s_cselect_b32 s51, s39, s69
	s_cselect_b32 s50, s67, s68
	s_add_i32 s72, 0, 0x14000
	v_add_u32_e32 v140, s71, v224
	v_add_u32_e32 v156, s72, v224
	ds_read_b128 v[128:131], v140
	ds_read_b128 v[132:135], v140 offset:1024
	ds_read_b128 v[136:139], v140 offset:2048
	ds_read_b128 v[140:143], v140 offset:3072
	ds_read_b128 v[144:147], v156
	ds_read_b128 v[148:151], v156 offset:1024
	ds_read_b128 v[152:155], v156 offset:2048
	ds_read_b128 v[156:159], v156 offset:3072
	v_lshl_add_u64 v[204:205], s[48:49], 0, v[190:191]
	s_add_i32 m0, s59, 0xc000
	ds_read_b128 v[160:163], v226
	ds_read_b128 v[164:167], v226 offset:1024
	ds_read_b128 v[168:171], v226 offset:2048
	ds_read_b128 v[172:175], v226 offset:3072
	ds_read_b128 v[176:179], v226 offset:4096
	ds_read_b128 v[180:183], v226 offset:5120
	ds_read_b128 v[194:197], v226 offset:6144
	ds_read_b128 v[200:203], v226 offset:7168
	global_load_lds_dwordx4 v[204:205], off
	v_lshl_add_u64 v[204:205], s[48:49], 0, v[198:199]
	s_add_i32 m0, s59, 0xe000
	s_nop 0
	global_load_lds_dwordx4 v[204:205], off
	s_waitcnt vmcnt(8)
	s_waitcnt lgkmcnt(0)
	s_barrier
	s_setprio 1
	s_waitcnt lgkmcnt(0)
	v_mfma_f32_16x16x32_bf16 v[124:127], v[128:131], v[160:163], v[124:127]
	v_mfma_f32_16x16x32_bf16 v[120:123], v[136:139], v[160:163], v[120:123]
	v_mfma_f32_16x16x32_bf16 v[108:111], v[128:131], v[168:171], v[108:111]
	v_mfma_f32_16x16x32_bf16 v[104:107], v[136:139], v[168:171], v[104:107]
	v_mfma_f32_16x16x32_bf16 v[96:99], v[128:131], v[176:179], v[96:99]
	v_mfma_f32_16x16x32_bf16 v[88:91], v[136:139], v[176:179], v[88:91]
	v_mfma_f32_16x16x32_bf16 v[80:83], v[128:131], v[194:197], v[80:83]
	v_mfma_f32_16x16x32_bf16 v[72:75], v[136:139], v[194:197], v[72:75]
	v_mfma_f32_16x16x32_bf16 v[124:127], v[132:135], v[164:167], v[124:127]
	v_mfma_f32_16x16x32_bf16 v[120:123], v[140:143], v[164:167], v[120:123]
	v_mfma_f32_16x16x32_bf16 v[108:111], v[132:135], v[172:175], v[108:111]
	v_mfma_f32_16x16x32_bf16 v[104:107], v[140:143], v[172:175], v[104:107]
	v_mfma_f32_16x16x32_bf16 v[96:99], v[132:135], v[180:183], v[96:99]
	v_mfma_f32_16x16x32_bf16 v[88:91], v[140:143], v[180:183], v[88:91]
	v_mfma_f32_16x16x32_bf16 v[80:83], v[132:135], v[200:203], v[80:83]
	v_mfma_f32_16x16x32_bf16 v[72:75], v[140:143], v[200:203], v[72:75]
	v_mfma_f32_16x16x32_bf16 v[116:119], v[144:147], v[160:163], v[116:119]
	v_mfma_f32_16x16x32_bf16 v[112:115], v[152:155], v[160:163], v[112:115]
	v_mfma_f32_16x16x32_bf16 v[100:103], v[144:147], v[168:171], v[100:103]
	v_mfma_f32_16x16x32_bf16 v[92:95], v[152:155], v[168:171], v[92:95]
	v_mfma_f32_16x16x32_bf16 v[84:87], v[144:147], v[176:179], v[84:87]
	v_mfma_f32_16x16x32_bf16 v[76:79], v[152:155], v[176:179], v[76:79]
	v_mfma_f32_16x16x32_bf16 v[68:71], v[144:147], v[194:197], v[68:71]
	v_mfma_f32_16x16x32_bf16 v[64:67], v[152:155], v[194:197], v[64:67]
	v_mfma_f32_16x16x32_bf16 v[116:119], v[148:151], v[164:167], v[116:119]
	v_mfma_f32_16x16x32_bf16 v[112:115], v[156:159], v[164:167], v[112:115]
	v_mfma_f32_16x16x32_bf16 v[100:103], v[148:151], v[172:175], v[100:103]
	v_mfma_f32_16x16x32_bf16 v[92:95], v[156:159], v[172:175], v[92:95]
	v_mfma_f32_16x16x32_bf16 v[84:87], v[148:151], v[180:183], v[84:87]
	v_mfma_f32_16x16x32_bf16 v[76:79], v[156:159], v[180:183], v[76:79]
	v_mfma_f32_16x16x32_bf16 v[68:71], v[148:151], v[200:203], v[68:71]
	v_mfma_f32_16x16x32_bf16 v[64:67], v[156:159], v[200:203], v[64:67]
	s_setprio 0
	s_barrier
	s_add_i32 s12, s71, s58
	v_lshl_add_u64 v[204:205], s[50:51], 0, v[192:193]
	s_mov_b32 m0, s12
	ds_read_b128 v[160:163], v226 offset:16384
	ds_read_b128 v[164:167], v226 offset:17408
	ds_read_b128 v[168:171], v226 offset:18432
	ds_read_b128 v[172:175], v226 offset:19456
	ds_read_b128 v[176:179], v226 offset:20480
	ds_read_b128 v[180:183], v226 offset:21504
	ds_read_b128 v[194:197], v226 offset:22528
	ds_read_b128 v[200:203], v226 offset:23552
	global_load_lds_dwordx4 v[204:205], off
	s_add_i32 m0, s12, 0x2000
	s_add_u32 s12, s50, 0x100000
	v_lshl_add_u64 v[206:207], s[50:51], 0, v[188:189]
	s_addc_u32 s13, s51, 0
	s_add_i32 s71, s72, s58
	global_load_lds_dwordx4 v[206:207], off
	v_lshl_add_u64 v[208:209], s[12:13], 0, v[192:193]
	s_mov_b32 m0, s71
	v_lshl_add_u64 v[210:211], s[52:53], 0, v[186:187]
	global_load_lds_dwordx4 v[208:209], off
	v_lshl_add_u64 v[208:209], s[12:13], 0, v[188:189]
	s_add_i32 m0, s71, 0x2000
	s_nop 0
	global_load_lds_dwordx4 v[208:209], off
	v_lshl_add_u64 v[208:209], s[52:53], 0, v[184:185]
	s_mov_b32 m0, s59
	s_nop 0
	global_load_lds_dwordx4 v[208:209], off
	s_mov_b32 m0, s60
	s_nop 0
	global_load_lds_dwordx4 v[210:211], off
	s_waitcnt vmcnt(8)
	s_waitcnt lgkmcnt(0)
	s_barrier
; #define PG8_STAGE(bufoff, gbase, voff) do { _Pragma("unroll") for (int _i = 0; _i < 2; ++_i) \
;         __builtin_amdgcn_global_load_lds((const unsigned*)((const char*)(gbase) + (voff)[_i]), (PG8_LAS unsigned*)(lds + (bufoff) + ldsw + _i * 8192), 16, 0, 0); } while (0)
; #define PG8_LDA(dst, b, h) do { _Pragma("unroll") for (int m = 0; m < 4; ++m) _Pragma("unroll") for (int k = 0; k < 2; ++k) dst[m][k] = *(const PG8_LAS bf16x8*)(lds + PG8_SA(b, h) + aoff + m * 2048 + k * 1024); } while (0)
; #define PG8_LDB(dst, b, h) do { _Pragma("unroll") for (int n = 0; n < 2; ++n) _Pragma("unroll") for (int k = 0; k < 2; ++k) dst[n][k] = *(const PG8_LAS bf16x8*)(lds + PG8_SB(b, h) + boff + n * 2048 + k * 1024); } while (0)
; #define PG8_MMA(ai, bj, At, Bt) do { __builtin_amdgcn_s_setprio(1); _Pragma("unroll") for (int m = 0; m < 4; ++m) _Pragma("unroll") for (int n = 0; n < 2; ++n) _Pragma("unroll") for (int k = 0; k < 2; ++k) \
;         acc[ai][bj][m][n] = __builtin_amdgcn_mfma_f32_16x16x32_bf16(Bt[n][k], At[m][k], acc[ai][bj][m][n], 0, 0, 0); __builtin_amdgcn_s_setprio(0); } while (0)
; #define PG8_WAIT_V(n) asm volatile("s_waitcnt vmcnt(" #n ")" ::: "memory")
; #define PG8_WAIT_L(n) asm volatile("s_waitcnt lgkmcnt(" #n ")" ::: "memory")
; #define PG8_BAR __builtin_amdgcn_s_barrier()
; #define PG8_SCHED __builtin_amdgcn_sched_barrier(0)
; template <class Epi, class Sched, bool ALIGN_EPI = false, bool SP2 = false>
; __device__ __forceinline__ void gemm_phase(PG8_LAS unsigned char* lds, const Gemm g, const Sched& S, const Epi& E, const int tid_in) {
;     ...
;             PG8_WAIT_V(8); PG8_WAIT_L(0); PG8_BAR; PG8_MMA(1, 0, At, B0); PG8_MMA(1, 1, At, B1); PG8_BAR; PG8_SCHED;
;             PG8_LDB(B0, 1, 0); PG8_LDB(B1, 1, 1); PG8_SCHED; PG8_LDA(At, 1, 0); PG8_STAGE(PG8_SA(0, 1), a2 + hstepA, voffA);
;             PG8_WAIT_V(8); PG8_WAIT_L(0); PG8_BAR; PG8_MMA(0, 0, At, B0); PG8_MMA(0, 1, At, B1); PG8_BAR; PG8_SCHED;
	s_setprio 1
	s_waitcnt lgkmcnt(0)
	v_mfma_f32_16x16x32_bf16 v[60:63], v[128:131], v[160:163], v[60:63]
	v_mfma_f32_16x16x32_bf16 v[56:59], v[136:139], v[160:163], v[56:59]
	v_mfma_f32_16x16x32_bf16 v[48:51], v[128:131], v[168:171], v[48:51]
	v_mfma_f32_16x16x32_bf16 v[40:43], v[136:139], v[168:171], v[40:43]
	v_mfma_f32_16x16x32_bf16 v[32:35], v[128:131], v[176:179], v[32:35]
	v_mfma_f32_16x16x32_bf16 v[24:27], v[136:139], v[176:179], v[24:27]
	v_mfma_f32_16x16x32_bf16 v[16:19], v[128:131], v[194:197], v[16:19]
	v_mfma_f32_16x16x32_bf16 v[8:11], v[136:139], v[194:197], v[8:11]
	v_mfma_f32_16x16x32_bf16 v[60:63], v[132:135], v[164:167], v[60:63]
	v_mfma_f32_16x16x32_bf16 v[56:59], v[140:143], v[164:167], v[56:59]
	v_mfma_f32_16x16x32_bf16 v[48:51], v[132:135], v[172:175], v[48:51]
	v_mfma_f32_16x16x32_bf16 v[40:43], v[140:143], v[172:175], v[40:43]
	v_mfma_f32_16x16x32_bf16 v[32:35], v[132:135], v[180:183], v[32:35]
	v_mfma_f32_16x16x32_bf16 v[24:27], v[140:143], v[180:183], v[24:27]
	v_mfma_f32_16x16x32_bf16 v[16:19], v[132:135], v[200:203], v[16:19]
	v_mfma_f32_16x16x32_bf16 v[8:11], v[140:143], v[200:203], v[8:11]
	v_mfma_f32_16x16x32_bf16 v[52:55], v[144:147], v[160:163], v[52:55]
	v_mfma_f32_16x16x32_bf16 v[44:47], v[152:155], v[160:163], v[44:47]
	v_mfma_f32_16x16x32_bf16 v[36:39], v[144:147], v[168:171], v[36:39]
	v_mfma_f32_16x16x32_bf16 v[28:31], v[152:155], v[168:171], v[28:31]
	v_mfma_f32_16x16x32_bf16 v[20:23], v[144:147], v[176:179], v[20:23]
	v_mfma_f32_16x16x32_bf16 v[12:15], v[152:155], v[176:179], v[12:15]
	v_mfma_f32_16x16x32_bf16 v[4:7], v[144:147], v[194:197], v[4:7]
	v_mfma_f32_16x16x32_bf16 v[0:3], v[152:155], v[194:197], v[0:3]
	v_mfma_f32_16x16x32_bf16 v[52:55], v[148:151], v[164:167], v[52:55]
	v_mfma_f32_16x16x32_bf16 v[44:47], v[156:159], v[164:167], v[44:47]
	v_mfma_f32_16x16x32_bf16 v[36:39], v[148:151], v[172:175], v[36:39]
	v_mfma_f32_16x16x32_bf16 v[28:31], v[156:159], v[172:175], v[28:31]
	v_mfma_f32_16x16x32_bf16 v[20:23], v[148:151], v[180:183], v[20:23]
	v_mfma_f32_16x16x32_bf16 v[12:15], v[156:159], v[180:183], v[12:15]
	v_mfma_f32_16x16x32_bf16 v[4:7], v[148:151], v[200:203], v[4:7]
	v_mfma_f32_16x16x32_bf16 v[0:3], v[156:159], v[200:203], v[0:3]
	s_setprio 0
	s_barrier
	s_add_i32 s71, 0, 0x18000
	s_add_i32 s72, 0, 0x1c000
	v_add_u32_e32 v140, s71, v224
	v_add_u32_e32 v156, s72, v224
	ds_read_b128 v[128:131], v140
	ds_read_b128 v[132:135], v140 offset:1024
	ds_read_b128 v[136:139], v140 offset:2048
	ds_read_b128 v[140:143], v140 offset:3072
	ds_read_b128 v[144:147], v156
	ds_read_b128 v[148:151], v156 offset:1024
	ds_read_b128 v[152:155], v156 offset:2048
	ds_read_b128 v[156:159], v156 offset:3072
	s_add_u32 s12, s52, 0x100000
	s_addc_u32 s13, s53, 0
	s_mov_b32 m0, s61
	v_lshl_add_u64 v[212:213], s[12:13], 0, v[184:185]
	ds_read_b128 v[160:163], v226 offset:32768
	ds_read_b128 v[164:167], v226 offset:33792
	ds_read_b128 v[168:171], v226 offset:34816
	ds_read_b128 v[172:175], v226 offset:35840
	ds_read_b128 v[176:179], v226 offset:36864
	ds_read_b128 v[180:183], v226 offset:37888
	ds_read_b128 v[194:197], v226 offset:38912
	ds_read_b128 v[200:203], v226 offset:39936
	global_load_lds_dwordx4 v[212:213], off
	v_lshl_add_u64 v[212:213], s[12:13], 0, v[186:187]
	s_mov_b32 m0, s62
	s_nop 0
	global_load_lds_dwordx4 v[212:213], off
	s_waitcnt vmcnt(8)
	s_waitcnt lgkmcnt(0)
	s_barrier
	s_setprio 1
	s_waitcnt lgkmcnt(0)
	v_mfma_f32_16x16x32_bf16 v[124:127], v[128:131], v[160:163], v[124:127]
	v_mfma_f32_16x16x32_bf16 v[120:123], v[136:139], v[160:163], v[120:123]
	v_mfma_f32_16x16x32_bf16 v[108:111], v[128:131], v[168:171], v[108:111]
	v_mfma_f32_16x16x32_bf16 v[104:107], v[136:139], v[168:171], v[104:107]
	v_mfma_f32_16x16x32_bf16 v[96:99], v[128:131], v[176:179], v[96:99]
	v_mfma_f32_16x16x32_bf16 v[88:91], v[136:139], v[176:179], v[88:91]
	v_mfma_f32_16x16x32_bf16 v[80:83], v[128:131], v[194:197], v[80:83]
	v_mfma_f32_16x16x32_bf16 v[72:75], v[136:139], v[194:197], v[72:75]
	v_mfma_f32_16x16x32_bf16 v[124:127], v[132:135], v[164:167], v[124:127]
	v_mfma_f32_16x16x32_bf16 v[120:123], v[140:143], v[164:167], v[120:123]
	v_mfma_f32_16x16x32_bf16 v[108:111], v[132:135], v[172:175], v[108:111]
	v_mfma_f32_16x16x32_bf16 v[104:107], v[140:143], v[172:175], v[104:107]
	v_mfma_f32_16x16x32_bf16 v[96:99], v[132:135], v[180:183], v[96:99]
	v_mfma_f32_16x16x32_bf16 v[88:91], v[140:143], v[180:183], v[88:91]
	v_mfma_f32_16x16x32_bf16 v[80:83], v[132:135], v[200:203], v[80:83]
	v_mfma_f32_16x16x32_bf16 v[72:75], v[140:143], v[200:203], v[72:75]
	v_mfma_f32_16x16x32_bf16 v[116:119], v[144:147], v[160:163], v[116:119]
	v_mfma_f32_16x16x32_bf16 v[112:115], v[152:155], v[160:163], v[112:115]
	v_mfma_f32_16x16x32_bf16 v[100:103], v[144:147], v[168:171], v[100:103]
	v_mfma_f32_16x16x32_bf16 v[92:95], v[152:155], v[168:171], v[92:95]
	v_mfma_f32_16x16x32_bf16 v[84:87], v[144:147], v[176:179], v[84:87]
	v_mfma_f32_16x16x32_bf16 v[76:79], v[152:155], v[176:179], v[76:79]
	v_mfma_f32_16x16x32_bf16 v[68:71], v[144:147], v[194:197], v[68:71]
	v_mfma_f32_16x16x32_bf16 v[64:67], v[152:155], v[194:197], v[64:67]
	v_mfma_f32_16x16x32_bf16 v[116:119], v[148:151], v[164:167], v[116:119]
	v_mfma_f32_16x16x32_bf16 v[112:115], v[156:159], v[164:167], v[112:115]
	v_mfma_f32_16x16x32_bf16 v[100:103], v[148:151], v[172:175], v[100:103]
	v_mfma_f32_16x16x32_bf16 v[92:95], v[156:159], v[172:175], v[92:95]
	v_mfma_f32_16x16x32_bf16 v[84:87], v[148:151], v[180:183], v[84:87]
	v_mfma_f32_16x16x32_bf16 v[76:79], v[156:159], v[180:183], v[76:79]
	v_mfma_f32_16x16x32_bf16 v[68:71], v[148:151], v[200:203], v[68:71]
	v_mfma_f32_16x16x32_bf16 v[64:67], v[156:159], v[200:203], v[64:67]
	s_setprio 0
	s_barrier
; #define PG8_WAIT_V(n) asm volatile("s_waitcnt vmcnt(" #n ")" ::: "memory")
;     __device__ __forceinline__ void operator()(const f32x4 (&acc)[2][2][4][2], const Unit& u, int wr, int wc, int fr, int fq) const {
;         const int row0 = u.pm * BM + wr * 64 + fr; const int col0 = u.pn * BM + wc * 32 + 8 * fq;
;         u32x4 ov[2][4][2];
; #pragma unroll
;         for (int ai = 0; ai < 2; ++ai)
; #pragma unroll
;             for (int m = 0; m < 4; ++m) { const bf16_t* rowp = H + (size_t)(row0 + ai * HALF + m * 16) * ldc + col0;
; #pragma unroll
; template <class Epi, class Sched, bool ALIGN_EPI = false, bool SP2 = false>
; __device__ __forceinline__ void gemm_phase(PG8_LAS unsigned char* lds, const Gemm g, const Sched& S, const Epi& E, const int tid_in) {
;     ...
;             PG8_LDA(At, 1, 1); PG8_STAGE(PG8_SB(1, 0), b3, voffB); PG8_STAGE(PG8_SB(1, 1), b3 + hstepB, voffB); PG8_STAGE(PG8_SA(1, 0), a3, voffA);
;             PG8_WAIT_V(8); PG8_WAIT_L(0); PG8_BAR; PG8_MMA(1, 0, At, B0); PG8_MMA(1, 1, At, B1); PG8_BAR; PG8_SCHED;
;             } else {
;             PG8_LDB(B0, 0, 0); PG8_SCHED; PG8_LDA(At, 0, 0); PG8_STAGE(PG8_SA(1, 1), a1 + hstepA, voffA);
;             PG8_WAIT_L(8); PG8_BAR; PG8_WAIT_L(0); PG8_MMA(0, 0, At, B0); PG8_BAR; PG8_SCHED;
;             PG8_LDB(B1, 0, 1); PG8_STAGE(PG8_SB(0, 0), b2, voffB);
;             PG8_BAR; PG8_WAIT_L(0); PG8_MMA(0, 1, At, B1); PG8_BAR;
;             PG8_LDA(At, 0, 1); PG8_STAGE(PG8_SA(0, 0), a2, voffA);
;             PG8_BAR; PG8_WAIT_L(0); PG8_MMA(1, 0, At, B0); PG8_BAR; PG8_SCHED;
;             PG8_STAGE(PG8_SB(0, 1), b2 + hstepB, voffB);
;             PG8_WAIT_V(6); PG8_BAR; PG8_MMA(1, 1, At, B1); PG8_BAR;
;             PG8_LDB(B0, 1, 0); PG8_SCHED; PG8_LDA(At, 1, 0); PG8_STAGE(PG8_SA(0, 1), a2 + hstepA, voffA);
;             PG8_WAIT_L(8); PG8_BAR; PG8_WAIT_L(0); PG8_MMA(0, 0, At, B0); PG8_BAR; PG8_SCHED;
;             PG8_LDB(B1, 1, 1); PG8_STAGE(PG8_SB(1, 0), b3, voffB);
;             PG8_BAR; PG8_WAIT_L(0); PG8_MMA(0, 1, At, B1); PG8_BAR;
;             PG8_LDA(At, 1, 1); PG8_STAGE(PG8_SA(1, 0), a3, voffA);
;             PG8_BAR; PG8_WAIT_L(0); PG8_MMA(1, 0, At, B0); PG8_BAR; PG8_SCHED;
;             PG8_STAGE(PG8_SB(1, 1), b3 + hstepB, voffB);
;             PG8_WAIT_V(6); PG8_BAR; PG8_MMA(1, 1, At, B1); PG8_BAR;
;             }
;         }
;         if constexpr (ALIGN_EPI) { if (wr == 0) PG8_BAR; }
	s_add_i32 s12, s71, s58
	v_lshl_add_u64 v[204:205], v[204:205], 0, s[26:27]
	s_mov_b32 m0, s12
	ds_read_b128 v[160:163], v226 offset:49152
	ds_read_b128 v[164:167], v226 offset:50176
	ds_read_b128 v[168:171], v226 offset:51200
	ds_read_b128 v[172:175], v226 offset:52224
	ds_read_b128 v[176:179], v226 offset:53248
	ds_read_b128 v[180:183], v226 offset:54272
	ds_read_b128 v[194:197], v226 offset:55296
	ds_read_b128 v[200:203], v226 offset:56320
	global_load_lds_dwordx4 v[204:205], off
	s_add_i32 m0, s12, 0x2000
	s_add_u32 s12, s50, 0x100080
	v_lshl_add_u64 v[204:205], v[206:207], 0, s[26:27]
	s_addc_u32 s13, s51, 0
	s_add_i32 s50, s72, s58
	global_load_lds_dwordx4 v[204:205], off
	v_lshl_add_u64 v[204:205], s[12:13], 0, v[192:193]
	s_mov_b32 m0, s50
	s_nop 0
	global_load_lds_dwordx4 v[204:205], off
	v_lshl_add_u64 v[204:205], s[12:13], 0, v[188:189]
	s_add_i32 m0, s50, 0x2000
	s_nop 0
	global_load_lds_dwordx4 v[204:205], off
	v_lshl_add_u64 v[204:205], v[208:209], 0, s[26:27]
	s_mov_b32 m0, s64
	s_nop 0
	global_load_lds_dwordx4 v[204:205], off
	v_lshl_add_u64 v[204:205], v[210:211], 0, s[26:27]
	s_mov_b32 m0, s65
	s_nop 0
	global_load_lds_dwordx4 v[204:205], off
	s_waitcnt vmcnt(8)
	s_waitcnt lgkmcnt(0)
	s_barrier
	s_setprio 1
	s_waitcnt lgkmcnt(0)
	v_mfma_f32_16x16x32_bf16 v[60:63], v[128:131], v[160:163], v[60:63]
	v_mfma_f32_16x16x32_bf16 v[56:59], v[136:139], v[160:163], v[56:59]
	v_mfma_f32_16x16x32_bf16 v[48:51], v[128:131], v[168:171], v[48:51]
	v_mfma_f32_16x16x32_bf16 v[40:43], v[136:139], v[168:171], v[40:43]
	v_mfma_f32_16x16x32_bf16 v[32:35], v[128:131], v[176:179], v[32:35]
	v_mfma_f32_16x16x32_bf16 v[24:27], v[136:139], v[176:179], v[24:27]
	v_mfma_f32_16x16x32_bf16 v[16:19], v[128:131], v[194:197], v[16:19]
	v_mfma_f32_16x16x32_bf16 v[8:11], v[136:139], v[194:197], v[8:11]
	v_mfma_f32_16x16x32_bf16 v[60:63], v[132:135], v[164:167], v[60:63]
	v_mfma_f32_16x16x32_bf16 v[56:59], v[140:143], v[164:167], v[56:59]
	v_mfma_f32_16x16x32_bf16 v[48:51], v[132:135], v[172:175], v[48:51]
	v_mfma_f32_16x16x32_bf16 v[40:43], v[140:143], v[172:175], v[40:43]
	v_mfma_f32_16x16x32_bf16 v[32:35], v[132:135], v[180:183], v[32:35]
	v_mfma_f32_16x16x32_bf16 v[24:27], v[140:143], v[180:183], v[24:27]
	v_mfma_f32_16x16x32_bf16 v[16:19], v[132:135], v[200:203], v[16:19]
	v_mfma_f32_16x16x32_bf16 v[8:11], v[140:143], v[200:203], v[8:11]
	v_mfma_f32_16x16x32_bf16 v[52:55], v[144:147], v[160:163], v[52:55]
	v_mfma_f32_16x16x32_bf16 v[44:47], v[152:155], v[160:163], v[44:47]
	v_mfma_f32_16x16x32_bf16 v[36:39], v[144:147], v[168:171], v[36:39]
	v_mfma_f32_16x16x32_bf16 v[28:31], v[152:155], v[168:171], v[28:31]
	v_mfma_f32_16x16x32_bf16 v[20:23], v[144:147], v[176:179], v[20:23]
	v_mfma_f32_16x16x32_bf16 v[12:15], v[152:155], v[176:179], v[12:15]
	v_mfma_f32_16x16x32_bf16 v[4:7], v[144:147], v[194:197], v[4:7]
	v_mfma_f32_16x16x32_bf16 v[0:3], v[152:155], v[194:197], v[0:3]
	v_mfma_f32_16x16x32_bf16 v[52:55], v[148:151], v[164:167], v[52:55]
	v_mfma_f32_16x16x32_bf16 v[44:47], v[156:159], v[164:167], v[44:47]
	v_mfma_f32_16x16x32_bf16 v[36:39], v[148:151], v[172:175], v[36:39]
	v_mfma_f32_16x16x32_bf16 v[28:31], v[156:159], v[172:175], v[28:31]
	v_mfma_f32_16x16x32_bf16 v[20:23], v[148:151], v[180:183], v[20:23]
	v_mfma_f32_16x16x32_bf16 v[12:15], v[156:159], v[180:183], v[12:15]
	v_mfma_f32_16x16x32_bf16 v[4:7], v[148:151], v[200:203], v[4:7]
	v_mfma_f32_16x16x32_bf16 v[0:3], v[156:159], v[200:203], v[0:3]
	s_setprio 0
	s_barrier
	s_add_i32 s70, s70, 2
	s_add_u32 s48, s48, 0x100
	s_addc_u32 s49, s49, 0
	s_add_u32 s68, s68, 0x100
	s_addc_u32 s69, s69, 0
	s_cmp_gt_u32 s70, 61
	s_cbranch_scc0 .LBB0_1221
	s_andn2_b64 vcc, s[36:37], s[34:35]
	s_cbranch_vccz .LBB0_1224
	s_barrier
.LBB0_1224:
	v_lshl_or_b32 v130, s47, 8, v225
	v_lshl_add_u32 v128, s46, 8, v223
	v_ashrrev_i32_e32 v131, 31, v130
	v_lshlrev_b64 v[200:201], 1, v[130:131]
	v_ashrrev_i32_e32 v129, 31, v128
	v_lshl_add_u64 v[130:131], s[30:31], 0, v[200:201]
	v_lshlrev_b64 v[232:233], 12, v[128:129]
	v_lshl_add_u64 v[132:133], v[130:131], 0, v[232:233]
	global_load_dwordx4 v[194:197], v[132:133], off
	global_load_dwordx4 v[228:231], v[132:133], off offset:256
	v_or_b32_e32 v132, 16, v128
	v_ashrrev_i32_e32 v133, 31, v132
	v_lshlrev_b64 v[214:215], 12, v[132:133]
	v_lshl_add_u64 v[132:133], v[130:131], 0, v[214:215]
	global_load_dwordx4 v[180:183], v[132:133], off
	global_load_dwordx4 v[176:179], v[132:133], off offset:256
	v_or_b32_e32 v132, 32, v128
	v_ashrrev_i32_e32 v133, 31, v132
	v_lshlrev_b64 v[212:213], 12, v[132:133]
	v_lshl_add_u64 v[132:133], v[130:131], 0, v[212:213]
	global_load_dwordx4 v[172:175], v[132:133], off
	global_load_dwordx4 v[164:167], v[132:133], off offset:256
	v_or_b32_e32 v128, 48, v128
	v_ashrrev_i32_e32 v129, 31, v128
	v_lshlrev_b64 v[210:211], 12, v[128:129]
	v_lshl_add_u64 v[128:129], v[130:131], 0, v[210:211]
	global_load_dwordx4 v[168:171], v[128:129], off
	global_load_dwordx4 v[160:163], v[128:129], off offset:256
	v_lshl_add_u64 v[208:209], v[232:233], 0, s[24:25]
	v_lshl_add_u64 v[128:129], v[130:131], 0, v[208:209]
	s_mov_b64 s[12:13], 0x90000
	global_load_dwordx4 v[156:159], v[128:129], off
	global_load_dwordx4 v[152:155], v[128:129], off offset:256
	v_lshl_add_u64 v[206:207], v[232:233], 0, s[12:13]
	s_mov_b64 s[12:13], 0xa0000
	v_lshl_add_u64 v[128:129], v[130:131], 0, v[206:207]
	v_lshl_add_u64 v[204:205], v[232:233], 0, s[12:13]
	s_mov_b64 s[12:13], 0xb0000
	global_load_dwordx4 v[148:151], v[128:129], off
	global_load_dwordx4 v[144:147], v[128:129], off offset:256
	v_lshl_add_u64 v[128:129], v[130:131], 0, v[204:205]
	v_lshl_add_u64 v[202:203], v[232:233], 0, s[12:13]
	global_load_dwordx4 v[140:143], v[128:129], off
	global_load_dwordx4 v[136:139], v[128:129], off offset:256
	v_lshl_add_u64 v[128:129], v[130:131], 0, v[202:203]
	global_load_dwordx4 v[132:135], v[128:129], off
	s_nop 0
	global_load_dwordx4 v[128:131], v[128:129], off offset:256
	v_lshl_add_u64 v[232:233], s[30:31], 0, v[232:233]
	v_lshl_add_u64 v[232:233], v[232:233], 0, v[200:201]
	s_mov_b64 s[46:47], -1
	s_andn2_b64 vcc, exec, s[34:35]
	s_waitcnt vmcnt(0)
; __device__ __forceinline__ unsigned cvt_pk_bf16(float lo, float hi) { unsigned r; asm volatile("v_cvt_pk_bf16_f32 %0, %1, %2" : "=v"(r) : "v"(lo), "v"(hi)); return r; }
; __device__ __forceinline__ float bf_lo(unsigned w) { return __uint_as_float(w << 16); }
; __device__ __forceinline__ float bf_hi(unsigned w) { return __uint_as_float(w & 0xffff0000u); }
;     __device__ __forceinline__ void operator()(const f32x4 (&acc)[2][2][4][2], const Unit& u, int wr, int wc, int fr, int fq) const {
;     ...
; #pragma unroll
;         for (int ai = 0; ai < 2; ++ai)
; #pragma unroll
;             for (int m = 0; m < 4; ++m) { bf16_t* rowp = H + (size_t)(row0 + ai * HALF + m * 16) * ldc + col0;
;                 float sq = 0.f;
; #pragma unroll
;                 for (int bj = 0; bj < 2; ++bj) { const f32x4 v0 = acc[ai][bj][m][0], v1 = acc[ai][bj][m][1];
;                     const u32x4 o = ov[ai][m][bj]; u32x4 w;
;                     w.x = cvt_pk_bf16(bf_lo(o.x) + v0[0], bf_hi(o.x) + v0[1]); w.y = cvt_pk_bf16(bf_lo(o.y) + v0[2], bf_hi(o.y) + v0[3]);
;                     w.z = cvt_pk_bf16(bf_lo(o.z) + v1[0], bf_hi(o.z) + v1[1]); w.w = cvt_pk_bf16(bf_lo(o.w) + v1[2], bf_hi(o.w) + v1[3]);
;                     if (part) {
; #pragma unroll
;                         for (int e = 0; e < 4; ++e) { const float x = bf_lo(w[e]), y = bf_hi(w[e]); sq += x * x + y * y; } }
;                     if (!dry) *(u32x4*)(rowp + bj * HALF) = w; }
	v_lshlrev_b32_e32 v227, 16, v194
	v_and_b32_e32 v194, 0xffff0000, v194
	v_add_f32_e32 v124, v124, v227
	v_add_f32_e32 v125, v125, v194
	v_cvt_pk_bf16_f32 v124, v124, v125
	v_lshlrev_b32_e32 v125, 16, v195
	v_add_f32_e32 v125, v126, v125
	v_and_b32_e32 v126, 0xffff0000, v195
	v_add_f32_e32 v126, v127, v126
	v_cvt_pk_bf16_f32 v125, v125, v126
	v_lshlrev_b32_e32 v126, 16, v196
	v_add_f32_e32 v120, v120, v126
	v_and_b32_e32 v126, 0xffff0000, v196
	v_add_f32_e32 v121, v121, v126
	v_cvt_pk_bf16_f32 v126, v120, v121
	v_lshlrev_b32_e32 v120, 16, v197
	v_add_f32_e32 v120, v122, v120
	v_and_b32_e32 v121, 0xffff0000, v197
	v_add_f32_e32 v121, v123, v121
	v_cvt_pk_bf16_f32 v127, v120, v121
	v_lshlrev_b32_e32 v120, 16, v228
	v_add_f32_e32 v116, v116, v120
	v_and_b32_e32 v120, 0xffff0000, v228
	v_add_f32_e32 v117, v117, v120
	global_store_dwordx4 v[232:233], v[124:127], off
	v_cvt_pk_bf16_f32 v116, v116, v117
	v_lshlrev_b32_e32 v117, 16, v229
	v_add_f32_e32 v117, v118, v117
	v_and_b32_e32 v118, 0xffff0000, v229
	v_add_f32_e32 v118, v119, v118
	v_cvt_pk_bf16_f32 v117, v117, v118
	v_lshlrev_b32_e32 v118, 16, v230
	v_add_f32_e32 v112, v112, v118
	v_and_b32_e32 v118, 0xffff0000, v230
	v_add_f32_e32 v113, v113, v118
	v_cvt_pk_bf16_f32 v118, v112, v113
	v_lshlrev_b32_e32 v112, 16, v231
	v_add_f32_e32 v112, v114, v112
	v_lshlrev_b32_e32 v114, 16, v180
	v_add_f32_e32 v108, v108, v114
	v_and_b32_e32 v114, 0xffff0000, v180
	v_and_b32_e32 v113, 0xffff0000, v231
	v_add_f32_e32 v109, v109, v114
	v_add_f32_e32 v113, v115, v113
	v_cvt_pk_bf16_f32 v119, v112, v113
	global_store_dwordx4 v[232:233], v[116:119], off offset:256
	v_cvt_pk_bf16_f32 v108, v108, v109
	v_lshlrev_b32_e32 v109, 16, v181
	v_add_f32_e32 v109, v110, v109
	v_and_b32_e32 v110, 0xffff0000, v181
	v_add_f32_e32 v110, v111, v110
	v_cvt_pk_bf16_f32 v109, v109, v110
	v_lshlrev_b32_e32 v110, 16, v182
	v_add_f32_e32 v104, v104, v110
	v_and_b32_e32 v110, 0xffff0000, v182
	v_add_f32_e32 v105, v105, v110
	v_cvt_pk_bf16_f32 v110, v104, v105
	v_lshlrev_b32_e32 v104, 16, v183
	v_add_f32_e32 v104, v106, v104
	v_and_b32_e32 v105, 0xffff0000, v183
	v_add_f32_e32 v105, v107, v105
	v_cvt_pk_bf16_f32 v111, v104, v105
	v_lshlrev_b32_e32 v104, 16, v176
	v_lshl_add_u64 v[112:113], s[30:31], 0, v[214:215]
	v_add_f32_e32 v100, v100, v104
	v_and_b32_e32 v104, 0xffff0000, v176
	v_lshl_add_u64 v[112:113], v[112:113], 0, v[200:201]
	v_add_f32_e32 v101, v101, v104
	global_store_dwordx4 v[112:113], v[108:111], off
	v_cvt_pk_bf16_f32 v100, v100, v101
	v_lshlrev_b32_e32 v101, 16, v177
	v_add_f32_e32 v101, v102, v101
	v_and_b32_e32 v102, 0xffff0000, v177
	v_add_f32_e32 v102, v103, v102
	v_cvt_pk_bf16_f32 v101, v101, v102
	v_lshlrev_b32_e32 v102, 16, v178
	v_add_f32_e32 v92, v92, v102
	v_and_b32_e32 v102, 0xffff0000, v178
	v_add_f32_e32 v93, v93, v102
	v_cvt_pk_bf16_f32 v102, v92, v93
	v_lshlrev_b32_e32 v92, 16, v179
	v_and_b32_e32 v93, 0xffff0000, v179
	v_add_f32_e32 v92, v94, v92
	v_add_f32_e32 v93, v95, v93
	v_cvt_pk_bf16_f32 v103, v92, v93
	v_lshl_add_u64 v[92:93], s[30:31], 0, v[212:213]
	global_store_dwordx4 v[112:113], v[100:103], off offset:256
	v_and_b32_e32 v94, 0xffff0000, v173
	v_add_f32_e32 v94, v99, v94
	v_lshl_add_u64 v[100:101], v[92:93], 0, v[200:201]
	v_lshlrev_b32_e32 v92, 16, v172
	v_and_b32_e32 v93, 0xffff0000, v172
	v_add_f32_e32 v92, v96, v92
	v_add_f32_e32 v93, v97, v93
	v_cvt_pk_bf16_f32 v92, v92, v93
	v_lshlrev_b32_e32 v93, 16, v173
	v_add_f32_e32 v93, v98, v93
	v_cvt_pk_bf16_f32 v93, v93, v94
	v_lshlrev_b32_e32 v94, 16, v174
	v_add_f32_e32 v88, v88, v94
	v_and_b32_e32 v94, 0xffff0000, v174
	v_add_f32_e32 v89, v89, v94
	v_cvt_pk_bf16_f32 v94, v88, v89
	v_lshlrev_b32_e32 v88, 16, v175
	v_add_f32_e32 v88, v90, v88
	v_and_b32_e32 v89, 0xffff0000, v175
	v_add_f32_e32 v89, v91, v89
	v_cvt_pk_bf16_f32 v95, v88, v89
	v_lshlrev_b32_e32 v88, 16, v164
	v_add_f32_e32 v84, v84, v88
	v_and_b32_e32 v88, 0xffff0000, v164
	v_add_f32_e32 v85, v85, v88
	global_store_dwordx4 v[100:101], v[92:95], off
	v_cvt_pk_bf16_f32 v84, v84, v85
	v_lshlrev_b32_e32 v85, 16, v165
	v_add_f32_e32 v85, v86, v85
	v_and_b32_e32 v86, 0xffff0000, v165
	v_add_f32_e32 v86, v87, v86
	v_cvt_pk_bf16_f32 v85, v85, v86
	v_lshlrev_b32_e32 v86, 16, v166
	v_add_f32_e32 v76, v76, v86
	v_and_b32_e32 v86, 0xffff0000, v166
	v_add_f32_e32 v77, v77, v86
	v_cvt_pk_bf16_f32 v86, v76, v77
	v_lshlrev_b32_e32 v76, 16, v167
	v_and_b32_e32 v77, 0xffff0000, v167
	v_add_f32_e32 v76, v78, v76
	v_add_f32_e32 v77, v79, v77
	v_cvt_pk_bf16_f32 v87, v76, v77
	v_lshl_add_u64 v[76:77], s[30:31], 0, v[210:211]
	global_store_dwordx4 v[100:101], v[84:87], off offset:256
	v_and_b32_e32 v78, 0xffff0000, v169
	v_add_f32_e32 v78, v83, v78
	v_lshl_add_u64 v[84:85], v[76:77], 0, v[200:201]
	v_lshlrev_b32_e32 v76, 16, v168
	v_and_b32_e32 v77, 0xffff0000, v168
	v_add_f32_e32 v76, v80, v76
	v_add_f32_e32 v77, v81, v77
	v_cvt_pk_bf16_f32 v76, v76, v77
	v_lshlrev_b32_e32 v77, 16, v169
	v_add_f32_e32 v77, v82, v77
	v_cvt_pk_bf16_f32 v77, v77, v78
	v_lshlrev_b32_e32 v78, 16, v170
	v_add_f32_e32 v72, v72, v78
	v_and_b32_e32 v78, 0xffff0000, v170
	v_add_f32_e32 v73, v73, v78
	v_cvt_pk_bf16_f32 v78, v72, v73
	v_lshlrev_b32_e32 v72, 16, v171
	v_add_f32_e32 v72, v74, v72
	v_and_b32_e32 v73, 0xffff0000, v171
	v_add_f32_e32 v73, v75, v73
	v_cvt_pk_bf16_f32 v79, v72, v73
	v_lshlrev_b32_e32 v72, 16, v160
	v_add_f32_e32 v68, v68, v72
	v_and_b32_e32 v72, 0xffff0000, v160
	v_add_f32_e32 v69, v69, v72
	global_store_dwordx4 v[84:85], v[76:79], off
	v_cvt_pk_bf16_f32 v68, v68, v69
	v_lshlrev_b32_e32 v69, 16, v161
	v_add_f32_e32 v69, v70, v69
	v_and_b32_e32 v70, 0xffff0000, v161
	v_add_f32_e32 v70, v71, v70
; __device__ __forceinline__ unsigned cvt_pk_bf16(float lo, float hi) { unsigned r; asm volatile("v_cvt_pk_bf16_f32 %0, %1, %2" : "=v"(r) : "v"(lo), "v"(hi)); return r; }
; __device__ __forceinline__ float bf_lo(unsigned w) { return __uint_as_float(w << 16); }
; __device__ __forceinline__ float bf_hi(unsigned w) { return __uint_as_float(w & 0xffff0000u); }
; #define PG8_BAR __builtin_amdgcn_s_barrier()
;     __device__ __forceinline__ void operator()(const f32x4 (&acc)[2][2][4][2], const Unit& u, int wr, int wc, int fr, int fq) const {
;     ...
; #pragma unroll
;         for (int ai = 0; ai < 2; ++ai)
; #pragma unroll
;             for (int m = 0; m < 4; ++m) { bf16_t* rowp = H + (size_t)(row0 + ai * HALF + m * 16) * ldc + col0;
;                 float sq = 0.f;
; #pragma unroll
;                 for (int bj = 0; bj < 2; ++bj) { const f32x4 v0 = acc[ai][bj][m][0], v1 = acc[ai][bj][m][1];
;                     const u32x4 o = ov[ai][m][bj]; u32x4 w;
;                     w.x = cvt_pk_bf16(bf_lo(o.x) + v0[0], bf_hi(o.x) + v0[1]); w.y = cvt_pk_bf16(bf_lo(o.y) + v0[2], bf_hi(o.y) + v0[3]);
;                     w.z = cvt_pk_bf16(bf_lo(o.z) + v1[0], bf_hi(o.z) + v1[1]); w.w = cvt_pk_bf16(bf_lo(o.w) + v1[2], bf_hi(o.w) + v1[3]);
;                     if (part) {
; #pragma unroll
;                         for (int e = 0; e < 4; ++e) { const float x = bf_lo(w[e]), y = bf_hi(w[e]); sq += x * x + y * y; } }
;                     if (!dry) *(u32x4*)(rowp + bj * HALF) = w; }
; template <class Epi, class Sched, bool ALIGN_EPI = false, bool SP2 = false>
; __device__ __forceinline__ void gemm_phase(PG8_LAS unsigned char* lds, const Gemm g, const Sched& S, const Epi& E, const int tid_in) {
;     ...
;         if (!has_next) break;
; #pragma unroll
;         for (int a = 0; a < 2; ++a)
; #pragma unroll
;             for (int b = 0; b < 2; ++b)
; #pragma unroll
;                 for (int m = 0; m < 4; ++m)
; #pragma unroll
;                     for (int n = 0; n < 2; ++n) acc[a][b][m][n] = (f32x4){0.f, 0.f, 0.f, 0.f};
;         cur = nxt; cA = nA; cB = nB; ++ui;
;         if constexpr (ALIGN_EPI) { if (wr == 1) PG8_BAR; }
	v_cvt_pk_bf16_f32 v69, v69, v70
	v_lshlrev_b32_e32 v70, 16, v162
	v_add_f32_e32 v64, v64, v70
	v_and_b32_e32 v70, 0xffff0000, v162
	v_add_f32_e32 v65, v65, v70
	v_cvt_pk_bf16_f32 v70, v64, v65
	v_lshlrev_b32_e32 v64, 16, v163
	v_add_f32_e32 v64, v66, v64
	v_lshlrev_b32_e32 v66, 16, v156
	v_add_f32_e32 v60, v60, v66
	v_and_b32_e32 v66, 0xffff0000, v156
	v_and_b32_e32 v65, 0xffff0000, v163
	v_add_f32_e32 v61, v61, v66
	v_add_f32_e32 v65, v67, v65
	v_cvt_pk_bf16_f32 v71, v64, v65
	global_store_dwordx4 v[84:85], v[68:71], off offset:256
	v_cvt_pk_bf16_f32 v60, v60, v61
	v_lshlrev_b32_e32 v61, 16, v157
	v_add_f32_e32 v61, v62, v61
	v_and_b32_e32 v62, 0xffff0000, v157
	v_add_f32_e32 v62, v63, v62
	v_cvt_pk_bf16_f32 v61, v61, v62
	v_lshlrev_b32_e32 v62, 16, v158
	v_add_f32_e32 v56, v56, v62
	v_and_b32_e32 v62, 0xffff0000, v158
	v_add_f32_e32 v57, v57, v62
	v_cvt_pk_bf16_f32 v62, v56, v57
	v_lshlrev_b32_e32 v56, 16, v159
	v_add_f32_e32 v56, v58, v56
	v_and_b32_e32 v57, 0xffff0000, v159
	v_add_f32_e32 v57, v59, v57
	v_cvt_pk_bf16_f32 v63, v56, v57
	v_lshlrev_b32_e32 v56, 16, v152
	v_lshl_add_u64 v[64:65], s[30:31], 0, v[208:209]
	v_add_f32_e32 v52, v52, v56
	v_and_b32_e32 v56, 0xffff0000, v152
	v_lshl_add_u64 v[64:65], v[64:65], 0, v[200:201]
	v_add_f32_e32 v53, v53, v56
	global_store_dwordx4 v[64:65], v[60:63], off
	v_cvt_pk_bf16_f32 v52, v52, v53
	v_lshlrev_b32_e32 v53, 16, v153
	v_add_f32_e32 v53, v54, v53
	v_and_b32_e32 v54, 0xffff0000, v153
	v_add_f32_e32 v54, v55, v54
	v_cvt_pk_bf16_f32 v53, v53, v54
	v_lshlrev_b32_e32 v54, 16, v154
	v_add_f32_e32 v44, v44, v54
	v_and_b32_e32 v54, 0xffff0000, v154
	v_add_f32_e32 v45, v45, v54
	v_cvt_pk_bf16_f32 v54, v44, v45
	v_lshlrev_b32_e32 v44, 16, v155
	v_and_b32_e32 v45, 0xffff0000, v155
	v_add_f32_e32 v44, v46, v44
	v_add_f32_e32 v45, v47, v45
	v_cvt_pk_bf16_f32 v55, v44, v45
	v_lshl_add_u64 v[44:45], s[30:31], 0, v[206:207]
	global_store_dwordx4 v[64:65], v[52:55], off offset:256
	v_and_b32_e32 v46, 0xffff0000, v149
	v_add_f32_e32 v46, v51, v46
	v_lshl_add_u64 v[52:53], v[44:45], 0, v[200:201]
	v_lshlrev_b32_e32 v44, 16, v148
	v_and_b32_e32 v45, 0xffff0000, v148
	v_add_f32_e32 v44, v48, v44
	v_add_f32_e32 v45, v49, v45
	v_cvt_pk_bf16_f32 v44, v44, v45
	v_lshlrev_b32_e32 v45, 16, v149
	v_add_f32_e32 v45, v50, v45
	v_cvt_pk_bf16_f32 v45, v45, v46
	v_lshlrev_b32_e32 v46, 16, v150
	v_add_f32_e32 v40, v40, v46
	v_and_b32_e32 v46, 0xffff0000, v150
	v_add_f32_e32 v41, v41, v46
	v_cvt_pk_bf16_f32 v46, v40, v41
	v_lshlrev_b32_e32 v40, 16, v151
	v_add_f32_e32 v40, v42, v40
	v_and_b32_e32 v41, 0xffff0000, v151
	v_add_f32_e32 v41, v43, v41
	v_cvt_pk_bf16_f32 v47, v40, v41
	v_lshlrev_b32_e32 v40, 16, v144
	v_add_f32_e32 v36, v36, v40
	v_and_b32_e32 v40, 0xffff0000, v144
	v_add_f32_e32 v37, v37, v40
	global_store_dwordx4 v[52:53], v[44:47], off
	v_cvt_pk_bf16_f32 v36, v36, v37
	v_lshlrev_b32_e32 v37, 16, v145
	v_add_f32_e32 v37, v38, v37
	v_and_b32_e32 v38, 0xffff0000, v145
	v_add_f32_e32 v38, v39, v38
	v_cvt_pk_bf16_f32 v37, v37, v38
	v_lshlrev_b32_e32 v38, 16, v146
	v_add_f32_e32 v28, v28, v38
	v_and_b32_e32 v38, 0xffff0000, v146
	v_add_f32_e32 v29, v29, v38
	v_cvt_pk_bf16_f32 v38, v28, v29
	v_lshlrev_b32_e32 v28, 16, v147
	v_and_b32_e32 v29, 0xffff0000, v147
	v_add_f32_e32 v28, v30, v28
	v_add_f32_e32 v29, v31, v29
	v_cvt_pk_bf16_f32 v39, v28, v29
	v_lshl_add_u64 v[28:29], s[30:31], 0, v[204:205]
	global_store_dwordx4 v[52:53], v[36:39], off offset:256
	v_and_b32_e32 v30, 0xffff0000, v141
	v_add_f32_e32 v30, v35, v30
	v_lshl_add_u64 v[36:37], v[28:29], 0, v[200:201]
	v_lshlrev_b32_e32 v28, 16, v140
	v_and_b32_e32 v29, 0xffff0000, v140
	v_add_f32_e32 v28, v32, v28
	v_add_f32_e32 v29, v33, v29
	v_cvt_pk_bf16_f32 v28, v28, v29
	v_lshlrev_b32_e32 v29, 16, v141
	v_add_f32_e32 v29, v34, v29
	v_cvt_pk_bf16_f32 v29, v29, v30
	v_lshlrev_b32_e32 v30, 16, v142
	v_add_f32_e32 v24, v24, v30
	v_and_b32_e32 v30, 0xffff0000, v142
	v_add_f32_e32 v25, v25, v30
	v_cvt_pk_bf16_f32 v30, v24, v25
	v_lshlrev_b32_e32 v24, 16, v143
	v_add_f32_e32 v24, v26, v24
	v_and_b32_e32 v25, 0xffff0000, v143
	v_add_f32_e32 v25, v27, v25
	v_cvt_pk_bf16_f32 v31, v24, v25
	v_lshlrev_b32_e32 v24, 16, v136
	v_add_f32_e32 v20, v20, v24
	v_and_b32_e32 v24, 0xffff0000, v136
	v_add_f32_e32 v21, v21, v24
	global_store_dwordx4 v[36:37], v[28:31], off
	v_cvt_pk_bf16_f32 v20, v20, v21
	v_lshlrev_b32_e32 v21, 16, v137
	v_add_f32_e32 v21, v22, v21
	v_and_b32_e32 v22, 0xffff0000, v137
	v_add_f32_e32 v22, v23, v22
	v_cvt_pk_bf16_f32 v21, v21, v22
	v_lshlrev_b32_e32 v22, 16, v138
	v_add_f32_e32 v12, v12, v22
	v_and_b32_e32 v22, 0xffff0000, v138
	v_add_f32_e32 v13, v13, v22
	v_cvt_pk_bf16_f32 v22, v12, v13
	v_lshlrev_b32_e32 v12, 16, v139
	v_and_b32_e32 v13, 0xffff0000, v139
	v_add_f32_e32 v12, v14, v12
	v_add_f32_e32 v13, v15, v13
	v_cvt_pk_bf16_f32 v23, v12, v13
	v_lshl_add_u64 v[12:13], s[30:31], 0, v[202:203]
	global_store_dwordx4 v[36:37], v[20:23], off offset:256
	v_and_b32_e32 v14, 0xffff0000, v133
	v_add_f32_e32 v14, v19, v14
	v_lshl_add_u64 v[20:21], v[12:13], 0, v[200:201]
	v_lshlrev_b32_e32 v12, 16, v132
	v_and_b32_e32 v13, 0xffff0000, v132
	v_add_f32_e32 v12, v16, v12
	v_add_f32_e32 v13, v17, v13
	v_cvt_pk_bf16_f32 v12, v12, v13
	v_lshlrev_b32_e32 v13, 16, v133
	v_add_f32_e32 v13, v18, v13
	v_cvt_pk_bf16_f32 v13, v13, v14
	v_lshlrev_b32_e32 v14, 16, v134
	v_add_f32_e32 v8, v8, v14
	v_and_b32_e32 v14, 0xffff0000, v134
	v_add_f32_e32 v9, v9, v14
	v_cvt_pk_bf16_f32 v14, v8, v9
	v_lshlrev_b32_e32 v8, 16, v135
	v_add_f32_e32 v8, v10, v8
	v_and_b32_e32 v9, 0xffff0000, v135
	v_add_f32_e32 v9, v11, v9
	v_cvt_pk_bf16_f32 v15, v8, v9
	v_lshlrev_b32_e32 v8, 16, v128
	v_add_f32_e32 v4, v4, v8
	v_and_b32_e32 v8, 0xffff0000, v128
	v_add_f32_e32 v5, v5, v8
	global_store_dwordx4 v[20:21], v[12:15], off
	v_cvt_pk_bf16_f32 v4, v4, v5
	v_lshlrev_b32_e32 v5, 16, v129
	v_add_f32_e32 v5, v6, v5
	v_and_b32_e32 v6, 0xffff0000, v129
	v_add_f32_e32 v6, v7, v6
	v_cvt_pk_bf16_f32 v5, v5, v6
	v_lshlrev_b32_e32 v6, 16, v130
	v_add_f32_e32 v0, v0, v6
	v_and_b32_e32 v6, 0xffff0000, v130
	v_add_f32_e32 v1, v1, v6
	v_cvt_pk_bf16_f32 v6, v0, v1
	v_lshlrev_b32_e32 v0, 16, v131
	v_and_b32_e32 v1, 0xffff0000, v131
	v_add_f32_e32 v0, v2, v0
	v_add_f32_e32 v1, v3, v1
	v_cvt_pk_bf16_f32 v7, v0, v1
	global_store_dwordx4 v[20:21], v[4:7], off offset:256
	s_cbranch_vccnz .LBB0_1217
	s_andn2_b64 vcc, exec, s[28:29]
	s_cbranch_vccnz .LBB0_1216
	s_branch .LBB0_1216

; #define PG8_STAGE(bufoff, gbase, voff) do { _Pragma("unroll") for (int _i = 0; _i < 2; ++_i) \
;         __builtin_amdgcn_global_load_lds((const unsigned*)((const char*)(gbase) + (voff)[_i]), (PG8_LAS unsigned*)(lds + (bufoff) + ldsw + _i * 8192), 16, 0, 0); } while (0)
; #define PG8_LDA(dst, b, h) do { _Pragma("unroll") for (int m = 0; m < 4; ++m) _Pragma("unroll") for (int k = 0; k < 2; ++k) dst[m][k] = *(const PG8_LAS bf16x8*)(lds + PG8_SA(b, h) + aoff + m * 2048 + k * 1024); } while (0)
; #define PG8_LDB(dst, b, h) do { _Pragma("unroll") for (int n = 0; n < 2; ++n) _Pragma("unroll") for (int k = 0; k < 2; ++k) dst[n][k] = *(const PG8_LAS bf16x8*)(lds + PG8_SB(b, h) + boff + n * 2048 + k * 1024); } while (0)
; #define PG8_MMA(ai, bj, At, Bt) do { __builtin_amdgcn_s_setprio(1); _Pragma("unroll") for (int m = 0; m < 4; ++m) _Pragma("unroll") for (int n = 0; n < 2; ++n) _Pragma("unroll") for (int k = 0; k < 2; ++k) \
;         acc[ai][bj][m][n] = __builtin_amdgcn_mfma_f32_16x16x32_bf16(Bt[n][k], At[m][k], acc[ai][bj][m][n], 0, 0, 0); __builtin_amdgcn_s_setprio(0); } while (0)
; #define PG8_WAIT_V(n) asm volatile("s_waitcnt vmcnt(" #n ")" ::: "memory")
; #define PG8_WAIT_L(n) asm volatile("s_waitcnt lgkmcnt(" #n ")" ::: "memory")
; #define PG8_BAR __builtin_amdgcn_s_barrier()
; template <class Epi, class Sched, bool ALIGN_EPI = false, bool SP2 = false>
; __device__ __forceinline__ void gemm_phase(PG8_LAS unsigned char* lds, const Gemm g, const Sched& S, const Epi& E, const int tid_in) {
;     ...
;         for (int t = 0; t < nt; t += 2) {
;             const bool last = (t == nt - 2);
;             const char* a1 = cA + (size_t)(t + 1) * kstep;
;             const char* a2 = last ? nA : cA + (size_t)(t + 2) * kstep; const char* b2 = last ? nB : cB + (size_t)(t + 2) * kstep;
;             const char* a3 = a2 + kstep; const char* b3 = b2 + kstep;
;             if (last && has_next) S.a_ready(nxt);
;             if constexpr (SP2) {
;             PG8_LDB(B0, 0, 0); PG8_LDB(B1, 0, 1); PG8_SCHED; PG8_LDA(At, 0, 0); PG8_STAGE(PG8_SA(1, 1), a1 + hstepA, voffA);
;             PG8_WAIT_V(8); PG8_WAIT_L(0); PG8_BAR; PG8_MMA(0, 0, At, B0); PG8_MMA(0, 1, At, B1); PG8_BAR; PG8_SCHED;
;             PG8_LDA(At, 0, 1); PG8_STAGE(PG8_SB(0, 0), b2, voffB); PG8_STAGE(PG8_SB(0, 1), b2 + hstepB, voffB); PG8_STAGE(PG8_SA(0, 0), a2, voffA);
.LBB0_1359:
	s_add_u32 s12, s44, 0xfff80080
	s_addc_u32 s13, s45, -1
	s_add_i32 s66, 0, 0x10000
	s_cmp_eq_u32 s65, 28
	s_cselect_b32 s49, s39, s13
	s_cselect_b32 s48, s61, s12
	v_add_u32_e32 v138, s66, v141
	s_cselect_b32 s47, s37, s64
	s_cselect_b32 s46, s62, s63
	s_add_i32 s67, 0, 0x14000
	ds_read_b128 v[144:147], v138
	ds_read_b128 v[148:151], v138 offset:1024
	ds_read_b128 v[152:155], v138 offset:2048
	ds_read_b128 v[156:159], v138 offset:3072
	v_add_u32_e32 v138, s67, v141
	ds_read_b128 v[160:163], v138
	ds_read_b128 v[164:167], v138 offset:1024
	ds_read_b128 v[168:171], v138 offset:2048
	ds_read_b128 v[172:175], v138 offset:3072
	v_lshl_add_u64 v[138:139], s[44:45], 0, v[134:135]
	s_add_i32 m0, s51, 0xc000
	ds_read_b128 v[176:179], v143
	ds_read_b128 v[180:183], v143 offset:1024
	ds_read_b128 v[184:187], v143 offset:2048
	ds_read_b128 v[188:191], v143 offset:3072
	ds_read_b128 v[194:197], v143 offset:4096
	ds_read_b128 v[198:201], v143 offset:5120
	ds_read_b128 v[202:205], v143 offset:6144
	ds_read_b128 v[206:209], v143 offset:7168
	global_load_lds_dwordx4 v[138:139], off
	v_lshl_add_u64 v[138:139], s[44:45], 0, v[136:137]
	s_add_i32 m0, s51, 0xe000
	s_nop 0
	global_load_lds_dwordx4 v[138:139], off
	s_waitcnt vmcnt(8)
	s_waitcnt lgkmcnt(0)
	s_barrier
	s_setprio 1
	s_waitcnt lgkmcnt(0)
	v_mfma_f32_16x16x32_bf16 v[124:127], v[144:147], v[176:179], v[124:127]
	v_mfma_f32_16x16x32_bf16 v[120:123], v[152:155], v[176:179], v[120:123]
	v_mfma_f32_16x16x32_bf16 v[108:111], v[144:147], v[184:187], v[108:111]
	v_mfma_f32_16x16x32_bf16 v[104:107], v[152:155], v[184:187], v[104:107]
	v_mfma_f32_16x16x32_bf16 v[92:95], v[144:147], v[194:197], v[92:95]
	v_mfma_f32_16x16x32_bf16 v[88:91], v[152:155], v[194:197], v[88:91]
	v_mfma_f32_16x16x32_bf16 v[76:79], v[144:147], v[202:205], v[76:79]
	v_mfma_f32_16x16x32_bf16 v[72:75], v[152:155], v[202:205], v[72:75]
	v_mfma_f32_16x16x32_bf16 v[124:127], v[148:151], v[180:183], v[124:127]
	v_mfma_f32_16x16x32_bf16 v[120:123], v[156:159], v[180:183], v[120:123]
	v_mfma_f32_16x16x32_bf16 v[108:111], v[148:151], v[188:191], v[108:111]
	v_mfma_f32_16x16x32_bf16 v[104:107], v[156:159], v[188:191], v[104:107]
	v_mfma_f32_16x16x32_bf16 v[92:95], v[148:151], v[198:201], v[92:95]
	v_mfma_f32_16x16x32_bf16 v[88:91], v[156:159], v[198:201], v[88:91]
	v_mfma_f32_16x16x32_bf16 v[76:79], v[148:151], v[206:209], v[76:79]
	v_mfma_f32_16x16x32_bf16 v[72:75], v[156:159], v[206:209], v[72:75]
	v_mfma_f32_16x16x32_bf16 v[116:119], v[160:163], v[176:179], v[116:119]
	v_mfma_f32_16x16x32_bf16 v[112:115], v[168:171], v[176:179], v[112:115]
	v_mfma_f32_16x16x32_bf16 v[100:103], v[160:163], v[184:187], v[100:103]
	v_mfma_f32_16x16x32_bf16 v[96:99], v[168:171], v[184:187], v[96:99]
	v_mfma_f32_16x16x32_bf16 v[84:87], v[160:163], v[194:197], v[84:87]
	v_mfma_f32_16x16x32_bf16 v[80:83], v[168:171], v[194:197], v[80:83]
	v_mfma_f32_16x16x32_bf16 v[68:71], v[160:163], v[202:205], v[68:71]
	v_mfma_f32_16x16x32_bf16 v[64:67], v[168:171], v[202:205], v[64:67]
	v_mfma_f32_16x16x32_bf16 v[116:119], v[164:167], v[180:183], v[116:119]
	v_mfma_f32_16x16x32_bf16 v[112:115], v[172:175], v[180:183], v[112:115]
	v_mfma_f32_16x16x32_bf16 v[100:103], v[164:167], v[188:191], v[100:103]
	v_mfma_f32_16x16x32_bf16 v[96:99], v[172:175], v[188:191], v[96:99]
	v_mfma_f32_16x16x32_bf16 v[84:87], v[164:167], v[198:201], v[84:87]
	v_mfma_f32_16x16x32_bf16 v[80:83], v[172:175], v[198:201], v[80:83]
	v_mfma_f32_16x16x32_bf16 v[68:71], v[164:167], v[206:209], v[68:71]
	v_mfma_f32_16x16x32_bf16 v[64:67], v[172:175], v[206:209], v[64:67]
	s_setprio 0
	s_barrier
	s_add_i32 s12, s66, s50
	v_lshl_add_u64 v[138:139], s[46:47], 0, v[192:193]
	s_mov_b32 m0, s12
	ds_read_b128 v[176:179], v143 offset:16384
	ds_read_b128 v[180:183], v143 offset:17408
	ds_read_b128 v[184:187], v143 offset:18432
	ds_read_b128 v[188:191], v143 offset:19456
	ds_read_b128 v[194:197], v143 offset:20480
	ds_read_b128 v[198:201], v143 offset:21504
	ds_read_b128 v[202:205], v143 offset:22528
	ds_read_b128 v[206:209], v143 offset:23552
	global_load_lds_dwordx4 v[138:139], off
	s_add_i32 m0, s12, 0x2000
	s_add_u32 s12, s46, 0x80000
	v_lshl_add_u64 v[210:211], s[46:47], 0, v[128:129]
	s_addc_u32 s13, s47, 0
	s_add_i32 s66, s67, s50
	global_load_lds_dwordx4 v[210:211], off
	v_lshl_add_u64 v[212:213], s[12:13], 0, v[192:193]
	s_mov_b32 m0, s66
	v_lshl_add_u64 v[214:215], s[48:49], 0, v[130:131]
	global_load_lds_dwordx4 v[212:213], off
	v_lshl_add_u64 v[212:213], s[12:13], 0, v[128:129]
	s_add_i32 m0, s66, 0x2000
	s_nop 0
	global_load_lds_dwordx4 v[212:213], off
	v_lshl_add_u64 v[212:213], s[48:49], 0, v[132:133]
	s_mov_b32 m0, s51
	s_nop 0
	global_load_lds_dwordx4 v[212:213], off
	s_mov_b32 m0, s52
	s_nop 0
	global_load_lds_dwordx4 v[214:215], off
	s_waitcnt vmcnt(8)
	s_waitcnt lgkmcnt(0)
	s_barrier
; #define PG8_STAGE(bufoff, gbase, voff) do { _Pragma("unroll") for (int _i = 0; _i < 2; ++_i) \
;         __builtin_amdgcn_global_load_lds((const unsigned*)((const char*)(gbase) + (voff)[_i]), (PG8_LAS unsigned*)(lds + (bufoff) + ldsw + _i * 8192), 16, 0, 0); } while (0)
; #define PG8_LDA(dst, b, h) do { _Pragma("unroll") for (int m = 0; m < 4; ++m) _Pragma("unroll") for (int k = 0; k < 2; ++k) dst[m][k] = *(const PG8_LAS bf16x8*)(lds + PG8_SA(b, h) + aoff + m * 2048 + k * 1024); } while (0)
; #define PG8_LDB(dst, b, h) do { _Pragma("unroll") for (int n = 0; n < 2; ++n) _Pragma("unroll") for (int k = 0; k < 2; ++k) dst[n][k] = *(const PG8_LAS bf16x8*)(lds + PG8_SB(b, h) + boff + n * 2048 + k * 1024); } while (0)
; #define PG8_MMA(ai, bj, At, Bt) do { __builtin_amdgcn_s_setprio(1); _Pragma("unroll") for (int m = 0; m < 4; ++m) _Pragma("unroll") for (int n = 0; n < 2; ++n) _Pragma("unroll") for (int k = 0; k < 2; ++k) \
;         acc[ai][bj][m][n] = __builtin_amdgcn_mfma_f32_16x16x32_bf16(Bt[n][k], At[m][k], acc[ai][bj][m][n], 0, 0, 0); __builtin_amdgcn_s_setprio(0); } while (0)
; #define PG8_WAIT_V(n) asm volatile("s_waitcnt vmcnt(" #n ")" ::: "memory")
; #define PG8_WAIT_L(n) asm volatile("s_waitcnt lgkmcnt(" #n ")" ::: "memory")
; #define PG8_BAR __builtin_amdgcn_s_barrier()
; #define PG8_SCHED __builtin_amdgcn_sched_barrier(0)
; template <class Epi, class Sched, bool ALIGN_EPI = false, bool SP2 = false>
; __device__ __forceinline__ void gemm_phase(PG8_LAS unsigned char* lds, const Gemm g, const Sched& S, const Epi& E, const int tid_in) {
;     ...
;             PG8_WAIT_V(8); PG8_WAIT_L(0); PG8_BAR; PG8_MMA(1, 0, At, B0); PG8_MMA(1, 1, At, B1); PG8_BAR; PG8_SCHED;
;             PG8_LDB(B0, 1, 0); PG8_LDB(B1, 1, 1); PG8_SCHED; PG8_LDA(At, 1, 0); PG8_STAGE(PG8_SA(0, 1), a2 + hstepA, voffA);
;             PG8_WAIT_V(8); PG8_WAIT_L(0); PG8_BAR; PG8_MMA(0, 0, At, B0); PG8_MMA(0, 1, At, B1); PG8_BAR; PG8_SCHED;
	s_setprio 1
	s_waitcnt lgkmcnt(0)
	v_mfma_f32_16x16x32_bf16 v[60:63], v[144:147], v[176:179], v[60:63]
	v_mfma_f32_16x16x32_bf16 v[56:59], v[152:155], v[176:179], v[56:59]
	v_mfma_f32_16x16x32_bf16 v[44:47], v[144:147], v[184:187], v[44:47]
	v_mfma_f32_16x16x32_bf16 v[40:43], v[152:155], v[184:187], v[40:43]
	v_mfma_f32_16x16x32_bf16 v[28:31], v[144:147], v[194:197], v[28:31]
	v_mfma_f32_16x16x32_bf16 v[24:27], v[152:155], v[194:197], v[24:27]
	v_mfma_f32_16x16x32_bf16 v[12:15], v[144:147], v[202:205], v[12:15]
	v_mfma_f32_16x16x32_bf16 v[8:11], v[152:155], v[202:205], v[8:11]
	v_mfma_f32_16x16x32_bf16 v[60:63], v[148:151], v[180:183], v[60:63]
	v_mfma_f32_16x16x32_bf16 v[56:59], v[156:159], v[180:183], v[56:59]
	v_mfma_f32_16x16x32_bf16 v[44:47], v[148:151], v[188:191], v[44:47]
	v_mfma_f32_16x16x32_bf16 v[40:43], v[156:159], v[188:191], v[40:43]
	v_mfma_f32_16x16x32_bf16 v[28:31], v[148:151], v[198:201], v[28:31]
	v_mfma_f32_16x16x32_bf16 v[24:27], v[156:159], v[198:201], v[24:27]
	v_mfma_f32_16x16x32_bf16 v[12:15], v[148:151], v[206:209], v[12:15]
	v_mfma_f32_16x16x32_bf16 v[8:11], v[156:159], v[206:209], v[8:11]
	v_mfma_f32_16x16x32_bf16 v[52:55], v[160:163], v[176:179], v[52:55]
	v_mfma_f32_16x16x32_bf16 v[48:51], v[168:171], v[176:179], v[48:51]
	v_mfma_f32_16x16x32_bf16 v[36:39], v[160:163], v[184:187], v[36:39]
	v_mfma_f32_16x16x32_bf16 v[32:35], v[168:171], v[184:187], v[32:35]
	v_mfma_f32_16x16x32_bf16 v[20:23], v[160:163], v[194:197], v[20:23]
	v_mfma_f32_16x16x32_bf16 v[16:19], v[168:171], v[194:197], v[16:19]
	v_mfma_f32_16x16x32_bf16 v[4:7], v[160:163], v[202:205], v[4:7]
	v_mfma_f32_16x16x32_bf16 v[0:3], v[168:171], v[202:205], v[0:3]
	v_mfma_f32_16x16x32_bf16 v[52:55], v[164:167], v[180:183], v[52:55]
	v_mfma_f32_16x16x32_bf16 v[48:51], v[172:175], v[180:183], v[48:51]
	v_mfma_f32_16x16x32_bf16 v[36:39], v[164:167], v[188:191], v[36:39]
	v_mfma_f32_16x16x32_bf16 v[32:35], v[172:175], v[188:191], v[32:35]
	v_mfma_f32_16x16x32_bf16 v[20:23], v[164:167], v[198:201], v[20:23]
	v_mfma_f32_16x16x32_bf16 v[16:19], v[172:175], v[198:201], v[16:19]
	v_mfma_f32_16x16x32_bf16 v[4:7], v[164:167], v[206:209], v[4:7]
	v_mfma_f32_16x16x32_bf16 v[0:3], v[172:175], v[206:209], v[0:3]
	s_setprio 0
	s_barrier
	s_add_i32 s66, 0, 0x18000
	s_add_i32 s67, 0, 0x1c000
	v_add_u32_e32 v156, s66, v141
	v_add_u32_e32 v172, s67, v141
	ds_read_b128 v[144:147], v156
	ds_read_b128 v[148:151], v156 offset:1024
	ds_read_b128 v[152:155], v156 offset:2048
	ds_read_b128 v[156:159], v156 offset:3072
	ds_read_b128 v[160:163], v172
	ds_read_b128 v[164:167], v172 offset:1024
	ds_read_b128 v[168:171], v172 offset:2048
	ds_read_b128 v[172:175], v172 offset:3072
	s_add_u32 s12, s48, 0x80000
	s_addc_u32 s13, s49, 0
	s_mov_b32 m0, s53
	v_lshl_add_u64 v[216:217], s[12:13], 0, v[132:133]
	ds_read_b128 v[176:179], v143 offset:32768
	ds_read_b128 v[180:183], v143 offset:33792
	ds_read_b128 v[184:187], v143 offset:34816
	ds_read_b128 v[188:191], v143 offset:35840
	ds_read_b128 v[194:197], v143 offset:36864
	ds_read_b128 v[198:201], v143 offset:37888
	ds_read_b128 v[202:205], v143 offset:38912
	ds_read_b128 v[206:209], v143 offset:39936
	global_load_lds_dwordx4 v[216:217], off
	v_lshl_add_u64 v[216:217], s[12:13], 0, v[130:131]
	s_mov_b32 m0, s54
	s_nop 0
	global_load_lds_dwordx4 v[216:217], off
	s_waitcnt vmcnt(8)
	s_waitcnt lgkmcnt(0)
	s_barrier
	s_setprio 1
	s_waitcnt lgkmcnt(0)
	v_mfma_f32_16x16x32_bf16 v[124:127], v[144:147], v[176:179], v[124:127]
	v_mfma_f32_16x16x32_bf16 v[120:123], v[152:155], v[176:179], v[120:123]
	v_mfma_f32_16x16x32_bf16 v[108:111], v[144:147], v[184:187], v[108:111]
	v_mfma_f32_16x16x32_bf16 v[104:107], v[152:155], v[184:187], v[104:107]
	v_mfma_f32_16x16x32_bf16 v[92:95], v[144:147], v[194:197], v[92:95]
	v_mfma_f32_16x16x32_bf16 v[88:91], v[152:155], v[194:197], v[88:91]
	v_mfma_f32_16x16x32_bf16 v[76:79], v[144:147], v[202:205], v[76:79]
	v_mfma_f32_16x16x32_bf16 v[72:75], v[152:155], v[202:205], v[72:75]
	v_mfma_f32_16x16x32_bf16 v[124:127], v[148:151], v[180:183], v[124:127]
	v_mfma_f32_16x16x32_bf16 v[120:123], v[156:159], v[180:183], v[120:123]
	v_mfma_f32_16x16x32_bf16 v[108:111], v[148:151], v[188:191], v[108:111]
	v_mfma_f32_16x16x32_bf16 v[104:107], v[156:159], v[188:191], v[104:107]
	v_mfma_f32_16x16x32_bf16 v[92:95], v[148:151], v[198:201], v[92:95]
	v_mfma_f32_16x16x32_bf16 v[88:91], v[156:159], v[198:201], v[88:91]
	v_mfma_f32_16x16x32_bf16 v[76:79], v[148:151], v[206:209], v[76:79]
	v_mfma_f32_16x16x32_bf16 v[72:75], v[156:159], v[206:209], v[72:75]
	v_mfma_f32_16x16x32_bf16 v[116:119], v[160:163], v[176:179], v[116:119]
	v_mfma_f32_16x16x32_bf16 v[112:115], v[168:171], v[176:179], v[112:115]
	v_mfma_f32_16x16x32_bf16 v[100:103], v[160:163], v[184:187], v[100:103]
	v_mfma_f32_16x16x32_bf16 v[96:99], v[168:171], v[184:187], v[96:99]
	v_mfma_f32_16x16x32_bf16 v[84:87], v[160:163], v[194:197], v[84:87]
	v_mfma_f32_16x16x32_bf16 v[80:83], v[168:171], v[194:197], v[80:83]
	v_mfma_f32_16x16x32_bf16 v[68:71], v[160:163], v[202:205], v[68:71]
	v_mfma_f32_16x16x32_bf16 v[64:67], v[168:171], v[202:205], v[64:67]
	v_mfma_f32_16x16x32_bf16 v[116:119], v[164:167], v[180:183], v[116:119]
	v_mfma_f32_16x16x32_bf16 v[112:115], v[172:175], v[180:183], v[112:115]
	v_mfma_f32_16x16x32_bf16 v[100:103], v[164:167], v[188:191], v[100:103]
	v_mfma_f32_16x16x32_bf16 v[96:99], v[172:175], v[188:191], v[96:99]
	v_mfma_f32_16x16x32_bf16 v[84:87], v[164:167], v[198:201], v[84:87]
	v_mfma_f32_16x16x32_bf16 v[80:83], v[172:175], v[198:201], v[80:83]
	v_mfma_f32_16x16x32_bf16 v[68:71], v[164:167], v[206:209], v[68:71]
	v_mfma_f32_16x16x32_bf16 v[64:67], v[172:175], v[206:209], v[64:67]
	s_setprio 0
	s_barrier
; #define PG8_BAR __builtin_amdgcn_s_barrier()
;     __device__ __forceinline__ void operator()(const f32x4 (&acc)[2][2][4][2], const Unit& u, int wr, int wc, int fr, int fq) const {
;     ...
;             for (int m = 0; m < 4; ++m) { bf16_t* rowp = base + (size_t)(row0 + ai * HALF + m * 16) * ldc + col0;
;                 const float rsc = rsv[ai][m];
; #pragma unroll
;                 for (int bj = 0; bj < 2; ++bj) { f32x4 v0 = acc[ai][bj][m][0] * rsc, v1 = acc[ai][bj][m][1] * rsc;
;                     if (ACT == 1) {
; #pragma unroll
; template <class Epi, class Sched, bool ALIGN_EPI = false, bool SP2 = false>
; __device__ __forceinline__ void gemm_phase(PG8_LAS unsigned char* lds, const Gemm g, const Sched& S, const Epi& E, const int tid_in) {
;     ...
;             PG8_LDA(At, 1, 1); PG8_STAGE(PG8_SB(1, 0), b3, voffB); PG8_STAGE(PG8_SB(1, 1), b3 + hstepB, voffB); PG8_STAGE(PG8_SA(1, 0), a3, voffA);
;             PG8_WAIT_V(8); PG8_WAIT_L(0); PG8_BAR; PG8_MMA(1, 0, At, B0); PG8_MMA(1, 1, At, B1); PG8_BAR; PG8_SCHED;
;             } else {
;             PG8_LDB(B0, 0, 0); PG8_SCHED; PG8_LDA(At, 0, 0); PG8_STAGE(PG8_SA(1, 1), a1 + hstepA, voffA);
;             PG8_WAIT_L(8); PG8_BAR; PG8_WAIT_L(0); PG8_MMA(0, 0, At, B0); PG8_BAR; PG8_SCHED;
;             PG8_LDB(B1, 0, 1); PG8_STAGE(PG8_SB(0, 0), b2, voffB);
;             PG8_BAR; PG8_WAIT_L(0); PG8_MMA(0, 1, At, B1); PG8_BAR;
;             PG8_LDA(At, 0, 1); PG8_STAGE(PG8_SA(0, 0), a2, voffA);
;             PG8_BAR; PG8_WAIT_L(0); PG8_MMA(1, 0, At, B0); PG8_BAR; PG8_SCHED;
;             PG8_STAGE(PG8_SB(0, 1), b2 + hstepB, voffB);
;             PG8_WAIT_V(6); PG8_BAR; PG8_MMA(1, 1, At, B1); PG8_BAR;
;             PG8_LDB(B0, 1, 0); PG8_SCHED; PG8_LDA(At, 1, 0); PG8_STAGE(PG8_SA(0, 1), a2 + hstepA, voffA);
;             PG8_WAIT_L(8); PG8_BAR; PG8_WAIT_L(0); PG8_MMA(0, 0, At, B0); PG8_BAR; PG8_SCHED;
;             PG8_LDB(B1, 1, 1); PG8_STAGE(PG8_SB(1, 0), b3, voffB);
;             PG8_BAR; PG8_WAIT_L(0); PG8_MMA(0, 1, At, B1); PG8_BAR;
;             PG8_LDA(At, 1, 1); PG8_STAGE(PG8_SA(1, 0), a3, voffA);
;             PG8_BAR; PG8_WAIT_L(0); PG8_MMA(1, 0, At, B0); PG8_BAR; PG8_SCHED;
;             PG8_STAGE(PG8_SB(1, 1), b3 + hstepB, voffB);
;             PG8_WAIT_V(6); PG8_BAR; PG8_MMA(1, 1, At, B1); PG8_BAR;
;             }
;         }
;         if constexpr (ALIGN_EPI) { if (wr == 0) PG8_BAR; }
	s_add_i32 s12, s66, s50
	v_lshl_add_u64 v[138:139], v[138:139], 0, s[26:27]
	s_mov_b32 m0, s12
	ds_read_b128 v[176:179], v143 offset:49152
	ds_read_b128 v[180:183], v143 offset:50176
	ds_read_b128 v[184:187], v143 offset:51200
	ds_read_b128 v[188:191], v143 offset:52224
	ds_read_b128 v[194:197], v143 offset:53248
	ds_read_b128 v[198:201], v143 offset:54272
	ds_read_b128 v[202:205], v143 offset:55296
	ds_read_b128 v[206:209], v143 offset:56320
	global_load_lds_dwordx4 v[138:139], off
	s_add_i32 m0, s12, 0x2000
	s_add_u32 s12, s46, 0x80080
	v_lshl_add_u64 v[138:139], v[210:211], 0, s[26:27]
	s_addc_u32 s13, s47, 0
	s_add_i32 s46, s67, s50
	global_load_lds_dwordx4 v[138:139], off
	v_lshl_add_u64 v[138:139], s[12:13], 0, v[192:193]
	s_mov_b32 m0, s46
	s_nop 0
	global_load_lds_dwordx4 v[138:139], off
	v_lshl_add_u64 v[138:139], s[12:13], 0, v[128:129]
	s_add_i32 m0, s46, 0x2000
	s_nop 0
	global_load_lds_dwordx4 v[138:139], off
	v_lshl_add_u64 v[138:139], v[212:213], 0, s[26:27]
	s_mov_b32 m0, s55
	s_nop 0
	global_load_lds_dwordx4 v[138:139], off
	v_lshl_add_u64 v[138:139], v[214:215], 0, s[26:27]
	s_mov_b32 m0, s56
	s_nop 0
	global_load_lds_dwordx4 v[138:139], off
	s_waitcnt vmcnt(8)
	s_waitcnt lgkmcnt(0)
	s_barrier
	s_setprio 1
	s_waitcnt lgkmcnt(0)
	v_mfma_f32_16x16x32_bf16 v[60:63], v[144:147], v[176:179], v[60:63]
	v_mfma_f32_16x16x32_bf16 v[56:59], v[152:155], v[176:179], v[56:59]
	v_mfma_f32_16x16x32_bf16 v[44:47], v[144:147], v[184:187], v[44:47]
	v_mfma_f32_16x16x32_bf16 v[40:43], v[152:155], v[184:187], v[40:43]
	v_mfma_f32_16x16x32_bf16 v[28:31], v[144:147], v[194:197], v[28:31]
	v_mfma_f32_16x16x32_bf16 v[24:27], v[152:155], v[194:197], v[24:27]
	v_mfma_f32_16x16x32_bf16 v[12:15], v[144:147], v[202:205], v[12:15]
	v_mfma_f32_16x16x32_bf16 v[8:11], v[152:155], v[202:205], v[8:11]
	v_mfma_f32_16x16x32_bf16 v[60:63], v[148:151], v[180:183], v[60:63]
	v_mfma_f32_16x16x32_bf16 v[56:59], v[156:159], v[180:183], v[56:59]
	v_mfma_f32_16x16x32_bf16 v[44:47], v[148:151], v[188:191], v[44:47]
	v_mfma_f32_16x16x32_bf16 v[40:43], v[156:159], v[188:191], v[40:43]
	v_mfma_f32_16x16x32_bf16 v[28:31], v[148:151], v[198:201], v[28:31]
	v_mfma_f32_16x16x32_bf16 v[24:27], v[156:159], v[198:201], v[24:27]
	v_mfma_f32_16x16x32_bf16 v[12:15], v[148:151], v[206:209], v[12:15]
	v_mfma_f32_16x16x32_bf16 v[8:11], v[156:159], v[206:209], v[8:11]
	v_mfma_f32_16x16x32_bf16 v[52:55], v[160:163], v[176:179], v[52:55]
	v_mfma_f32_16x16x32_bf16 v[48:51], v[168:171], v[176:179], v[48:51]
	v_mfma_f32_16x16x32_bf16 v[36:39], v[160:163], v[184:187], v[36:39]
	v_mfma_f32_16x16x32_bf16 v[32:35], v[168:171], v[184:187], v[32:35]
	v_mfma_f32_16x16x32_bf16 v[20:23], v[160:163], v[194:197], v[20:23]
	v_mfma_f32_16x16x32_bf16 v[16:19], v[168:171], v[194:197], v[16:19]
	v_mfma_f32_16x16x32_bf16 v[4:7], v[160:163], v[202:205], v[4:7]
	v_mfma_f32_16x16x32_bf16 v[0:3], v[168:171], v[202:205], v[0:3]
	v_mfma_f32_16x16x32_bf16 v[52:55], v[164:167], v[180:183], v[52:55]
	v_mfma_f32_16x16x32_bf16 v[48:51], v[172:175], v[180:183], v[48:51]
	v_mfma_f32_16x16x32_bf16 v[36:39], v[164:167], v[188:191], v[36:39]
	v_mfma_f32_16x16x32_bf16 v[32:35], v[172:175], v[188:191], v[32:35]
	v_mfma_f32_16x16x32_bf16 v[20:23], v[164:167], v[198:201], v[20:23]
	v_mfma_f32_16x16x32_bf16 v[16:19], v[172:175], v[198:201], v[16:19]
	v_mfma_f32_16x16x32_bf16 v[4:7], v[164:167], v[206:209], v[4:7]
	v_mfma_f32_16x16x32_bf16 v[0:3], v[172:175], v[206:209], v[0:3]
	s_setprio 0
	s_barrier
	s_add_i32 s65, s65, 2
	s_add_u32 s44, s44, 0x100
	s_addc_u32 s45, s45, 0
	s_add_u32 s63, s63, 0x100
	s_addc_u32 s64, s64, 0
	s_cmp_gt_u32 s65, 29
	s_cbranch_scc0 .LBB0_1359
	s_andn2_b64 vcc, s[30:31], s[34:35]
	s_cbranch_vccz .LBB0_1362
	s_barrier
.LBB0_1362:
	v_max_f32_e32 v120, v120, v120
	v_max_f32_e32 v120, 0, v120
	v_max_f32_e32 v121, v121, v121
	v_max_f32_e32 v122, v122, v122
	v_lshl_or_b32 v138, s58, 8, v142
	v_mul_f32_e32 v149, v120, v120
	v_max_f32_e32 v120, v125, v125
	v_max_f32_e32 v121, 0, v121
	v_max_f32_e32 v122, 0, v122
	v_ashrrev_i32_e32 v139, 31, v138
	v_max_f32_e32 v124, v124, v124
	v_max_f32_e32 v120, 0, v120
	v_mul_f32_e32 v125, v121, v121
	v_max_f32_e32 v121, v126, v126
	v_mul_f32_e32 v126, v122, v122
	v_max_f32_e32 v122, v127, v127
	v_max_f32_e32 v123, v123, v123
	v_lshl_add_u32 v146, s59, 8, v140
	v_lshl_add_u64 v[138:139], v[138:139], 1, s[28:29]
	v_max_f32_e32 v124, 0, v124
	v_mul_f32_e32 v120, v120, v120
	v_max_f32_e32 v121, 0, v121
	v_max_f32_e32 v122, 0, v122
	v_max_f32_e32 v123, 0, v123
	v_max_f32_e32 v112, v112, v112
	v_max_f32_e32 v113, v113, v113
	v_max_f32_e32 v114, v114, v114
	v_mad_i64_i32 v[144:145], s[12:13], v146, s73, v[138:139]
	v_mul_f32_e32 v124, v124, v124
	v_mul_f32_e32 v121, v121, v121
	v_mul_f32_e32 v122, v122, v122
	v_mul_f32_e32 v123, v123, v123
	v_cvt_pk_bf16_f32 v120, v124, v120
	v_max_f32_e32 v112, 0, v112
	v_max_f32_e32 v113, 0, v113
	v_max_f32_e32 v114, 0, v114
	v_cvt_pk_bf16_f32 v121, v121, v122
	v_cvt_pk_bf16_f32 v122, v149, v125
	v_cvt_pk_bf16_f32 v123, v126, v123
	global_store_dwordx4 v[144:145], v[120:123], off
	v_max_f32_e32 v116, v116, v116
	v_max_f32_e32 v115, v115, v115
	v_mul_f32_e32 v120, v112, v112
	v_max_f32_e32 v112, v117, v117
	v_mul_f32_e32 v117, v113, v113
	v_max_f32_e32 v113, v118, v118
	v_mul_f32_e32 v118, v114, v114
	v_max_f32_e32 v114, v119, v119
	v_max_f32_e32 v112, 0, v112
	v_max_f32_e32 v113, 0, v113
	v_max_f32_e32 v114, 0, v114
	v_max_f32_e32 v116, 0, v116
	v_mul_f32_e32 v112, v112, v112
	v_mul_f32_e32 v113, v113, v113
	v_max_f32_e32 v115, 0, v115
	v_mul_f32_e32 v114, v114, v114
	v_max_f32_e32 v104, v104, v104
	v_mul_f32_e32 v116, v116, v116
; __device__ __forceinline__ unsigned cvt_pk_bf16(float lo, float hi) { unsigned r; asm volatile("v_cvt_pk_bf16_f32 %0, %1, %2" : "=v"(r) : "v"(lo), "v"(hi)); return r; }
;     __device__ __forceinline__ void operator()(const f32x4 (&acc)[2][2][4][2], const Unit& u, int wr, int wc, int fr, int fq) const {
;     ...
;             for (int m = 0; m < 4; ++m) { bf16_t* rowp = base + (size_t)(row0 + ai * HALF + m * 16) * ldc + col0;
;                 const float rsc = rsv[ai][m];
; #pragma unroll
;                 for (int bj = 0; bj < 2; ++bj) { f32x4 v0 = acc[ai][bj][m][0] * rsc, v1 = acc[ai][bj][m][1] * rsc;
;                     if (ACT == 1) {
; #pragma unroll
;                         for (int e = 0; e < 4; ++e) { const float a = fmaxf(v0[e], 0.f), b = fmaxf(v1[e], 0.f); v0[e] = a * a; v1[e] = b * b; } }
;                     u32x4 w; w.x = cvt_pk_bf16(v0[0], v0[1]); w.y = cvt_pk_bf16(v0[2], v0[3]); w.z = cvt_pk_bf16(v1[0], v1[1]); w.w = cvt_pk_bf16(v1[2], v1[3]);
;                     *(u32x4*)(rowp + bj * HALF) = w; } }
	v_mul_f32_e32 v115, v115, v115
	v_cvt_pk_bf16_f32 v112, v116, v112
	v_cvt_pk_bf16_f32 v113, v113, v114
	v_cvt_pk_bf16_f32 v114, v120, v117
	v_max_f32_e32 v104, 0, v104
	v_max_f32_e32 v105, v105, v105
	v_max_f32_e32 v106, v106, v106
	v_cvt_pk_bf16_f32 v115, v118, v115
	global_store_dwordx4 v[144:145], v[112:115], off offset:256
	v_max_f32_e32 v105, 0, v105
	v_max_f32_e32 v106, 0, v106
	v_mul_f32_e32 v114, v104, v104
	v_max_f32_e32 v104, v109, v109
	v_max_f32_e32 v108, v108, v108
	v_max_f32_e32 v104, 0, v104
	v_mul_f32_e32 v109, v105, v105
	v_max_f32_e32 v105, v110, v110
	v_mul_f32_e32 v110, v106, v106
	v_max_f32_e32 v106, v111, v111
	v_max_f32_e32 v107, v107, v107
	v_or_b32_e32 v112, 16, v146
	v_max_f32_e32 v108, 0, v108
	v_mul_f32_e32 v104, v104, v104
	v_max_f32_e32 v105, 0, v105
	v_max_f32_e32 v106, 0, v106
	v_max_f32_e32 v107, 0, v107
	v_max_f32_e32 v96, v96, v96
	v_max_f32_e32 v97, v97, v97
	v_max_f32_e32 v98, v98, v98
	v_mad_i64_i32 v[112:113], s[12:13], v112, s73, v[138:139]
	v_mul_f32_e32 v108, v108, v108
	v_mul_f32_e32 v105, v105, v105
	v_mul_f32_e32 v106, v106, v106
	v_mul_f32_e32 v107, v107, v107
	v_cvt_pk_bf16_f32 v104, v108, v104
	v_max_f32_e32 v96, 0, v96
	v_max_f32_e32 v97, 0, v97
	v_max_f32_e32 v98, 0, v98
	v_cvt_pk_bf16_f32 v105, v105, v106
	v_cvt_pk_bf16_f32 v106, v114, v109
	v_cvt_pk_bf16_f32 v107, v110, v107
	global_store_dwordx4 v[112:113], v[104:107], off
	v_max_f32_e32 v100, v100, v100
	v_max_f32_e32 v99, v99, v99
	v_mul_f32_e32 v104, v96, v96
	v_max_f32_e32 v96, v101, v101
	v_mul_f32_e32 v101, v97, v97
	v_max_f32_e32 v97, v102, v102
	v_mul_f32_e32 v102, v98, v98
	v_max_f32_e32 v98, v103, v103
	v_max_f32_e32 v96, 0, v96
	v_max_f32_e32 v97, 0, v97
	v_max_f32_e32 v98, 0, v98
	v_max_f32_e32 v100, 0, v100
	v_mul_f32_e32 v96, v96, v96
	v_mul_f32_e32 v97, v97, v97
	v_max_f32_e32 v99, 0, v99
	v_mul_f32_e32 v98, v98, v98
	v_max_f32_e32 v88, v88, v88
	v_mul_f32_e32 v100, v100, v100
	v_mul_f32_e32 v99, v99, v99
	v_cvt_pk_bf16_f32 v96, v100, v96
	v_cvt_pk_bf16_f32 v97, v97, v98
	v_cvt_pk_bf16_f32 v98, v104, v101
	v_max_f32_e32 v88, 0, v88
	v_max_f32_e32 v89, v89, v89
	v_max_f32_e32 v90, v90, v90
	v_cvt_pk_bf16_f32 v99, v102, v99
	global_store_dwordx4 v[112:113], v[96:99], off offset:256
	v_max_f32_e32 v89, 0, v89
	v_max_f32_e32 v90, 0, v90
	v_mul_f32_e32 v98, v88, v88
	v_max_f32_e32 v88, v93, v93
	v_max_f32_e32 v92, v92, v92
	v_max_f32_e32 v88, 0, v88
	v_mul_f32_e32 v93, v89, v89
	v_max_f32_e32 v89, v94, v94
	v_mul_f32_e32 v94, v90, v90
	v_max_f32_e32 v90, v95, v95
	v_max_f32_e32 v91, v91, v91
	v_or_b32_e32 v96, 32, v146
	v_max_f32_e32 v92, 0, v92
	v_mul_f32_e32 v88, v88, v88
	v_max_f32_e32 v89, 0, v89
	v_max_f32_e32 v90, 0, v90
	v_max_f32_e32 v91, 0, v91
	v_max_f32_e32 v80, v80, v80
	v_max_f32_e32 v81, v81, v81
	v_max_f32_e32 v82, v82, v82
	v_mad_i64_i32 v[96:97], s[12:13], v96, s73, v[138:139]
	v_mul_f32_e32 v92, v92, v92
	v_mul_f32_e32 v89, v89, v89
	v_mul_f32_e32 v90, v90, v90
	v_mul_f32_e32 v91, v91, v91
	v_cvt_pk_bf16_f32 v88, v92, v88
	v_max_f32_e32 v80, 0, v80
	v_max_f32_e32 v81, 0, v81
	v_max_f32_e32 v82, 0, v82
	v_cvt_pk_bf16_f32 v89, v89, v90
	v_cvt_pk_bf16_f32 v90, v98, v93
	v_cvt_pk_bf16_f32 v91, v94, v91
	global_store_dwordx4 v[96:97], v[88:91], off
	v_max_f32_e32 v84, v84, v84
	v_max_f32_e32 v83, v83, v83
	v_mul_f32_e32 v88, v80, v80
	v_max_f32_e32 v80, v85, v85
	v_mul_f32_e32 v85, v81, v81
	v_max_f32_e32 v81, v86, v86
	v_mul_f32_e32 v86, v82, v82
	v_max_f32_e32 v82, v87, v87
	v_max_f32_e32 v80, 0, v80
	v_max_f32_e32 v81, 0, v81
	v_max_f32_e32 v82, 0, v82
	v_max_f32_e32 v84, 0, v84
	v_mul_f32_e32 v80, v80, v80
	v_mul_f32_e32 v81, v81, v81
	v_max_f32_e32 v83, 0, v83
	v_mul_f32_e32 v82, v82, v82
	v_max_f32_e32 v72, v72, v72
	v_mul_f32_e32 v84, v84, v84
	v_mul_f32_e32 v83, v83, v83
	v_cvt_pk_bf16_f32 v80, v84, v80
	v_cvt_pk_bf16_f32 v81, v81, v82
	v_cvt_pk_bf16_f32 v82, v88, v85
	v_max_f32_e32 v72, 0, v72
	v_max_f32_e32 v73, v73, v73
	v_max_f32_e32 v74, v74, v74
	v_cvt_pk_bf16_f32 v83, v86, v83
	global_store_dwordx4 v[96:97], v[80:83], off offset:256
	v_max_f32_e32 v73, 0, v73
	v_max_f32_e32 v74, 0, v74
	v_mul_f32_e32 v82, v72, v72
	v_max_f32_e32 v72, v77, v77
	v_max_f32_e32 v76, v76, v76
	v_max_f32_e32 v72, 0, v72
	v_mul_f32_e32 v77, v73, v73
	v_max_f32_e32 v73, v78, v78
	v_mul_f32_e32 v78, v74, v74
	v_max_f32_e32 v74, v79, v79
	v_max_f32_e32 v75, v75, v75
	v_or_b32_e32 v80, 48, v146
	v_max_f32_e32 v76, 0, v76
	v_mul_f32_e32 v72, v72, v72
	v_max_f32_e32 v73, 0, v73
	v_max_f32_e32 v74, 0, v74
	v_max_f32_e32 v75, 0, v75
	v_max_f32_e32 v64, v64, v64
	v_max_f32_e32 v65, v65, v65
	v_max_f32_e32 v66, v66, v66
	v_mad_i64_i32 v[80:81], s[12:13], v80, s73, v[138:139]
	v_mul_f32_e32 v76, v76, v76
	v_mul_f32_e32 v73, v73, v73
	v_mul_f32_e32 v74, v74, v74
	v_mul_f32_e32 v75, v75, v75
	v_cvt_pk_bf16_f32 v72, v76, v72
	v_max_f32_e32 v64, 0, v64
	v_max_f32_e32 v65, 0, v65
	v_max_f32_e32 v66, 0, v66
	v_cvt_pk_bf16_f32 v73, v73, v74
	v_cvt_pk_bf16_f32 v74, v82, v77
	v_cvt_pk_bf16_f32 v75, v78, v75
	global_store_dwordx4 v[80:81], v[72:75], off
	v_max_f32_e32 v68, v68, v68
	v_max_f32_e32 v67, v67, v67
	v_mul_f32_e32 v72, v64, v64
	v_max_f32_e32 v64, v69, v69
	v_mul_f32_e32 v69, v65, v65
	v_max_f32_e32 v65, v70, v70
	v_mul_f32_e32 v70, v66, v66
	v_max_f32_e32 v66, v71, v71
	v_max_f32_e32 v64, 0, v64
	v_max_f32_e32 v65, 0, v65
	v_max_f32_e32 v66, 0, v66
	v_max_f32_e32 v68, 0, v68
	v_mul_f32_e32 v64, v64, v64
	v_mul_f32_e32 v65, v65, v65
	v_max_f32_e32 v67, 0, v67
	v_mul_f32_e32 v66, v66, v66
	v_max_f32_e32 v56, v56, v56
	v_mul_f32_e32 v68, v68, v68
	v_mul_f32_e32 v67, v67, v67
	v_cvt_pk_bf16_f32 v64, v68, v64
	v_cvt_pk_bf16_f32 v65, v65, v66
; __device__ __forceinline__ unsigned cvt_pk_bf16(float lo, float hi) { unsigned r; asm volatile("v_cvt_pk_bf16_f32 %0, %1, %2" : "=v"(r) : "v"(lo), "v"(hi)); return r; }
;     __device__ __forceinline__ void operator()(const f32x4 (&acc)[2][2][4][2], const Unit& u, int wr, int wc, int fr, int fq) const {
;     ...
;             for (int m = 0; m < 4; ++m) { bf16_t* rowp = base + (size_t)(row0 + ai * HALF + m * 16) * ldc + col0;
;                 const float rsc = rsv[ai][m];
; #pragma unroll
;                 for (int bj = 0; bj < 2; ++bj) { f32x4 v0 = acc[ai][bj][m][0] * rsc, v1 = acc[ai][bj][m][1] * rsc;
;                     if (ACT == 1) {
; #pragma unroll
;                         for (int e = 0; e < 4; ++e) { const float a = fmaxf(v0[e], 0.f), b = fmaxf(v1[e], 0.f); v0[e] = a * a; v1[e] = b * b; } }
;                     u32x4 w; w.x = cvt_pk_bf16(v0[0], v0[1]); w.y = cvt_pk_bf16(v0[2], v0[3]); w.z = cvt_pk_bf16(v1[0], v1[1]); w.w = cvt_pk_bf16(v1[2], v1[3]);
;                     *(u32x4*)(rowp + bj * HALF) = w; } }
	v_cvt_pk_bf16_f32 v66, v72, v69
	v_max_f32_e32 v56, 0, v56
	v_max_f32_e32 v57, v57, v57
	v_max_f32_e32 v58, v58, v58
	v_cvt_pk_bf16_f32 v67, v70, v67
	global_store_dwordx4 v[80:81], v[64:67], off offset:256
	v_max_f32_e32 v57, 0, v57
	v_max_f32_e32 v58, 0, v58
	v_mul_f32_e32 v66, v56, v56
	v_max_f32_e32 v56, v61, v61
	v_max_f32_e32 v60, v60, v60
	v_max_f32_e32 v56, 0, v56
	v_mul_f32_e32 v61, v57, v57
	v_max_f32_e32 v57, v62, v62
	v_mul_f32_e32 v62, v58, v58
	v_max_f32_e32 v58, v63, v63
	v_max_f32_e32 v59, v59, v59
	v_add_u32_e32 v147, 0x80, v146
	v_max_f32_e32 v60, 0, v60
	v_mul_f32_e32 v56, v56, v56
	v_max_f32_e32 v57, 0, v57
	v_max_f32_e32 v58, 0, v58
	v_max_f32_e32 v59, 0, v59
	v_max_f32_e32 v48, v48, v48
	v_max_f32_e32 v49, v49, v49
	v_max_f32_e32 v50, v50, v50
	v_mad_i64_i32 v[64:65], s[12:13], v147, s73, v[138:139]
	v_mul_f32_e32 v60, v60, v60
	v_mul_f32_e32 v57, v57, v57
	v_mul_f32_e32 v58, v58, v58
	v_mul_f32_e32 v59, v59, v59
	v_cvt_pk_bf16_f32 v56, v60, v56
	v_max_f32_e32 v48, 0, v48
	v_max_f32_e32 v49, 0, v49
	v_max_f32_e32 v50, 0, v50
	v_cvt_pk_bf16_f32 v57, v57, v58
	v_cvt_pk_bf16_f32 v58, v66, v61
	v_cvt_pk_bf16_f32 v59, v62, v59
	global_store_dwordx4 v[64:65], v[56:59], off
	v_max_f32_e32 v52, v52, v52
	v_max_f32_e32 v51, v51, v51
	v_mul_f32_e32 v56, v48, v48
	v_max_f32_e32 v48, v53, v53
	v_mul_f32_e32 v53, v49, v49
	v_max_f32_e32 v49, v54, v54
	v_mul_f32_e32 v54, v50, v50
	v_max_f32_e32 v50, v55, v55
	v_max_f32_e32 v48, 0, v48
	v_max_f32_e32 v49, 0, v49
	v_max_f32_e32 v50, 0, v50
	v_max_f32_e32 v52, 0, v52
	v_mul_f32_e32 v48, v48, v48
	v_mul_f32_e32 v49, v49, v49
	v_max_f32_e32 v51, 0, v51
	v_mul_f32_e32 v50, v50, v50
	v_max_f32_e32 v40, v40, v40
	v_mul_f32_e32 v52, v52, v52
	v_mul_f32_e32 v51, v51, v51
	v_cvt_pk_bf16_f32 v48, v52, v48
	v_cvt_pk_bf16_f32 v49, v49, v50
	v_cvt_pk_bf16_f32 v50, v56, v53
	v_max_f32_e32 v40, 0, v40
	v_max_f32_e32 v41, v41, v41
	v_max_f32_e32 v42, v42, v42
	v_cvt_pk_bf16_f32 v51, v54, v51
	global_store_dwordx4 v[64:65], v[48:51], off offset:256
	v_max_f32_e32 v41, 0, v41
	v_max_f32_e32 v42, 0, v42
	v_mul_f32_e32 v50, v40, v40
	v_max_f32_e32 v40, v45, v45
	v_max_f32_e32 v44, v44, v44
	v_max_f32_e32 v40, 0, v40
	v_mul_f32_e32 v45, v41, v41
	v_max_f32_e32 v41, v46, v46
	v_mul_f32_e32 v46, v42, v42
	v_max_f32_e32 v42, v47, v47
	v_max_f32_e32 v43, v43, v43
	v_add_u32_e32 v48, 0x90, v146
	v_max_f32_e32 v44, 0, v44
	v_mul_f32_e32 v40, v40, v40
	v_max_f32_e32 v41, 0, v41
	v_max_f32_e32 v42, 0, v42
	v_max_f32_e32 v43, 0, v43
	v_max_f32_e32 v32, v32, v32
	v_max_f32_e32 v33, v33, v33
	v_max_f32_e32 v34, v34, v34
	v_mad_i64_i32 v[48:49], s[12:13], v48, s73, v[138:139]
	v_mul_f32_e32 v44, v44, v44
	v_mul_f32_e32 v41, v41, v41
	v_mul_f32_e32 v42, v42, v42
	v_mul_f32_e32 v43, v43, v43
	v_cvt_pk_bf16_f32 v40, v44, v40
	v_max_f32_e32 v32, 0, v32
	v_max_f32_e32 v33, 0, v33
	v_max_f32_e32 v34, 0, v34
	v_cvt_pk_bf16_f32 v41, v41, v42
	v_cvt_pk_bf16_f32 v42, v50, v45
	v_cvt_pk_bf16_f32 v43, v46, v43
	global_store_dwordx4 v[48:49], v[40:43], off
	v_max_f32_e32 v36, v36, v36
	v_max_f32_e32 v35, v35, v35
	v_mul_f32_e32 v40, v32, v32
	v_max_f32_e32 v32, v37, v37
	v_mul_f32_e32 v37, v33, v33
	v_max_f32_e32 v33, v38, v38
	v_mul_f32_e32 v38, v34, v34
	v_max_f32_e32 v34, v39, v39
	v_max_f32_e32 v32, 0, v32
	v_max_f32_e32 v33, 0, v33
	v_max_f32_e32 v34, 0, v34
	v_max_f32_e32 v36, 0, v36
	v_mul_f32_e32 v32, v32, v32
	v_mul_f32_e32 v33, v33, v33
	v_max_f32_e32 v35, 0, v35
	v_mul_f32_e32 v34, v34, v34
	v_max_f32_e32 v24, v24, v24
	v_mul_f32_e32 v36, v36, v36
	v_mul_f32_e32 v35, v35, v35
	v_cvt_pk_bf16_f32 v32, v36, v32
	v_cvt_pk_bf16_f32 v33, v33, v34
	v_cvt_pk_bf16_f32 v34, v40, v37
	v_max_f32_e32 v24, 0, v24
	v_max_f32_e32 v25, v25, v25
; __device__ __forceinline__ unsigned cvt_pk_bf16(float lo, float hi) { unsigned r; asm volatile("v_cvt_pk_bf16_f32 %0, %1, %2" : "=v"(r) : "v"(lo), "v"(hi)); return r; }
; #define PG8_BAR __builtin_amdgcn_s_barrier()
;     __device__ __forceinline__ void operator()(const f32x4 (&acc)[2][2][4][2], const Unit& u, int wr, int wc, int fr, int fq) const {
;     ...
;             for (int m = 0; m < 4; ++m) { bf16_t* rowp = base + (size_t)(row0 + ai * HALF + m * 16) * ldc + col0;
;                 const float rsc = rsv[ai][m];
; #pragma unroll
;                 for (int bj = 0; bj < 2; ++bj) { f32x4 v0 = acc[ai][bj][m][0] * rsc, v1 = acc[ai][bj][m][1] * rsc;
;                     if (ACT == 1) {
; #pragma unroll
;                         for (int e = 0; e < 4; ++e) { const float a = fmaxf(v0[e], 0.f), b = fmaxf(v1[e], 0.f); v0[e] = a * a; v1[e] = b * b; } }
;                     u32x4 w; w.x = cvt_pk_bf16(v0[0], v0[1]); w.y = cvt_pk_bf16(v0[2], v0[3]); w.z = cvt_pk_bf16(v1[0], v1[1]); w.w = cvt_pk_bf16(v1[2], v1[3]);
;                     *(u32x4*)(rowp + bj * HALF) = w; } }
; template <class Epi, class Sched, bool ALIGN_EPI = false, bool SP2 = false>
; __device__ __forceinline__ void gemm_phase(PG8_LAS unsigned char* lds, const Gemm g, const Sched& S, const Epi& E, const int tid_in) {
;     ...
;         if (!has_next) break;
; #pragma unroll
;         for (int a = 0; a < 2; ++a)
; #pragma unroll
;             for (int b = 0; b < 2; ++b)
; #pragma unroll
;                 for (int m = 0; m < 4; ++m)
; #pragma unroll
;                     for (int n = 0; n < 2; ++n) acc[a][b][m][n] = (f32x4){0.f, 0.f, 0.f, 0.f};
;         cur = nxt; cA = nA; cB = nB; ++ui;
;         if constexpr (ALIGN_EPI) { if (wr == 1) PG8_BAR; }
	v_max_f32_e32 v26, v26, v26
	v_cvt_pk_bf16_f32 v35, v38, v35
	global_store_dwordx4 v[48:49], v[32:35], off offset:256
	v_max_f32_e32 v25, 0, v25
	v_max_f32_e32 v26, 0, v26
	v_mul_f32_e32 v34, v24, v24
	v_max_f32_e32 v24, v29, v29
	v_max_f32_e32 v28, v28, v28
	v_max_f32_e32 v24, 0, v24
	v_mul_f32_e32 v29, v25, v25
	v_max_f32_e32 v25, v30, v30
	v_mul_f32_e32 v30, v26, v26
	v_max_f32_e32 v26, v31, v31
	v_max_f32_e32 v27, v27, v27
	v_add_u32_e32 v32, 0xa0, v146
	v_max_f32_e32 v28, 0, v28
	v_mul_f32_e32 v24, v24, v24
	v_max_f32_e32 v25, 0, v25
	v_max_f32_e32 v26, 0, v26
	v_max_f32_e32 v27, 0, v27
	v_max_f32_e32 v16, v16, v16
	v_max_f32_e32 v17, v17, v17
	v_max_f32_e32 v18, v18, v18
	v_mad_i64_i32 v[32:33], s[12:13], v32, s73, v[138:139]
	v_mul_f32_e32 v28, v28, v28
	v_mul_f32_e32 v25, v25, v25
	v_mul_f32_e32 v26, v26, v26
	v_mul_f32_e32 v27, v27, v27
	v_cvt_pk_bf16_f32 v24, v28, v24
	v_max_f32_e32 v16, 0, v16
	v_max_f32_e32 v17, 0, v17
	v_max_f32_e32 v18, 0, v18
	v_cvt_pk_bf16_f32 v25, v25, v26
	v_cvt_pk_bf16_f32 v26, v34, v29
	v_cvt_pk_bf16_f32 v27, v30, v27
	global_store_dwordx4 v[32:33], v[24:27], off
	v_max_f32_e32 v20, v20, v20
	v_max_f32_e32 v19, v19, v19
	v_mul_f32_e32 v24, v16, v16
	v_max_f32_e32 v16, v21, v21
	v_mul_f32_e32 v21, v17, v17
	v_max_f32_e32 v17, v22, v22
	v_mul_f32_e32 v22, v18, v18
	v_max_f32_e32 v18, v23, v23
	v_max_f32_e32 v16, 0, v16
	v_max_f32_e32 v17, 0, v17
	v_max_f32_e32 v18, 0, v18
	v_max_f32_e32 v20, 0, v20
	v_mul_f32_e32 v16, v16, v16
	v_mul_f32_e32 v17, v17, v17
	v_max_f32_e32 v19, 0, v19
	v_mul_f32_e32 v18, v18, v18
	v_max_f32_e32 v8, v8, v8
	v_mul_f32_e32 v20, v20, v20
	v_mul_f32_e32 v19, v19, v19
	v_cvt_pk_bf16_f32 v16, v20, v16
	v_cvt_pk_bf16_f32 v17, v17, v18
	v_cvt_pk_bf16_f32 v18, v24, v21
	v_max_f32_e32 v8, 0, v8
	v_max_f32_e32 v9, v9, v9
	v_max_f32_e32 v10, v10, v10
	v_cvt_pk_bf16_f32 v19, v22, v19
	global_store_dwordx4 v[32:33], v[16:19], off offset:256
	v_max_f32_e32 v9, 0, v9
	v_max_f32_e32 v10, 0, v10
	v_mul_f32_e32 v18, v8, v8
	v_max_f32_e32 v8, v13, v13
	v_max_f32_e32 v12, v12, v12
	v_max_f32_e32 v8, 0, v8
	v_mul_f32_e32 v13, v9, v9
	v_max_f32_e32 v9, v14, v14
	v_mul_f32_e32 v14, v10, v10
	v_max_f32_e32 v10, v15, v15
	v_max_f32_e32 v11, v11, v11
	v_add_u32_e32 v148, 0xb0, v146
	v_max_f32_e32 v12, 0, v12
	v_mul_f32_e32 v8, v8, v8
	v_max_f32_e32 v9, 0, v9
	v_max_f32_e32 v10, 0, v10
	v_max_f32_e32 v11, 0, v11
	v_max_f32_e32 v0, v0, v0
	v_max_f32_e32 v1, v1, v1
	v_max_f32_e32 v2, v2, v2
	v_mad_i64_i32 v[16:17], s[12:13], v148, s73, v[138:139]
	v_mul_f32_e32 v12, v12, v12
	v_mul_f32_e32 v9, v9, v9
	v_mul_f32_e32 v10, v10, v10
	v_mul_f32_e32 v11, v11, v11
	v_cvt_pk_bf16_f32 v8, v12, v8
	v_max_f32_e32 v0, 0, v0
	v_max_f32_e32 v1, 0, v1
	v_max_f32_e32 v2, 0, v2
	v_cvt_pk_bf16_f32 v9, v9, v10
	v_cvt_pk_bf16_f32 v10, v18, v13
	v_cvt_pk_bf16_f32 v11, v14, v11
	global_store_dwordx4 v[16:17], v[8:11], off
	v_max_f32_e32 v3, v3, v3
	v_max_f32_e32 v4, v4, v4
	v_mul_f32_e32 v8, v0, v0
	v_max_f32_e32 v0, v5, v5
	v_mul_f32_e32 v5, v1, v1
	v_max_f32_e32 v1, v6, v6
	v_mul_f32_e32 v6, v2, v2
	v_max_f32_e32 v2, v7, v7
	v_max_f32_e32 v0, 0, v0
	v_max_f32_e32 v1, 0, v1
	v_max_f32_e32 v2, 0, v2
	v_max_f32_e32 v3, 0, v3
	v_max_f32_e32 v4, 0, v4
	v_mul_f32_e32 v0, v0, v0
	v_mul_f32_e32 v1, v1, v1
	v_mul_f32_e32 v2, v2, v2
	v_mul_f32_e32 v3, v3, v3
	s_andn2_b64 vcc, exec, s[34:35]
	s_mov_b64 s[34:35], -1
	v_mul_f32_e32 v4, v4, v4
	v_cvt_pk_bf16_f32 v0, v4, v0
	v_cvt_pk_bf16_f32 v1, v1, v2
	v_cvt_pk_bf16_f32 v2, v8, v5
	v_cvt_pk_bf16_f32 v3, v6, v3
	global_store_dwordx4 v[16:17], v[0:3], off offset:256
	s_cbranch_vccnz .LBB0_1351
	s_andn2_b64 vcc, exec, s[22:23]
	s_cbranch_vccnz .LBB0_1350
	s_branch .LBB0_1350
